# E57: write-through tile stores (sc1) given the streaming hint as well (sc1 nt); on E41
# baseline (speedup 1.0000x reference)
.LBB0_220:
	v_lshl_add_u32 v148, s4, 8, v154
	s_lshl_b32 s4, s48, 8
	s_and_b32 s4, s4, 0x100
	s_cmp_eq_u32 s5, 1
	s_cselect_b64 vcc, -1, 0
	v_ashrrev_i32_e32 v149, 31, v148
	v_or_b32_e32 v161, s4, v156
	v_cndmask_b32_e32 v146, 1.0, v160, vcc
	v_lshlrev_b64 v[150:151], 9, v[148:149]
	v_cndmask_b32_e64 v146, v146, 1.0, s[84:85]
	s_cmp_lg_u64 s[78:79], 0
	v_or_b32_e32 v150, v150, v161
	s_cselect_b64 s[48:49], -1, 0
	s_cmp_eq_u64 s[78:79], 0
	v_lshl_add_u64 v[152:153], v[150:151], 1, s[76:77]
	v_lshl_add_u64 v[150:151], v[150:151], 2, s[78:79]
	v_pk_mul_f32 v[128:129], v[146:147], v[128:129] op_sel_hi:[0,1]
	v_pk_mul_f32 v[126:127], v[146:147], v[126:127] op_sel_hi:[0,1]
	v_pk_mul_f32 v[124:125], v[146:147], v[124:125] op_sel_hi:[0,1]
	v_pk_mul_f32 v[122:123], v[146:147], v[122:123] op_sel_hi:[0,1]
	v_cvt_pk_bf16_f32 v164, v126, v127
	v_cvt_pk_bf16_f32 v165, v128, v129
	v_cvt_pk_bf16_f32 v166, v122, v123
	v_cvt_pk_bf16_f32 v167, v124, v125
	global_store_dwordx4 v[152:153], v[164:167], off sc1 nt
	s_cbranch_scc1 .LBB0_222
	global_store_dwordx4 v[150:151], v[126:129], off nt
	global_store_dwordx4 v[150:151], v[122:125], off offset:16 nt
.LBB0_222:
	v_mov_b32_e32 v147, v146
	s_nop 0
	v_mov_b32_e32 v122, v146
	v_mov_b32_e32 v123, v146
	v_pk_mul_f32 v[118:119], v[146:147], v[118:119]
	v_pk_mul_f32 v[120:121], v[122:123], v[120:121]
	v_cvt_pk_bf16_f32 v124, v118, v119
	v_pk_mul_f32 v[116:117], v[122:123], v[116:117]
	v_pk_mul_f32 v[114:115], v[146:147], v[114:115]
	v_cvt_pk_bf16_f32 v125, v120, v121
	s_andn2_b64 vcc, exec, s[48:49]
	v_cvt_pk_bf16_f32 v126, v114, v115
	v_cvt_pk_bf16_f32 v127, v116, v117
	global_store_dwordx4 v[152:153], v[124:127], off offset:256 sc1 nt
	s_nop 1
	v_cndmask_b32_e64 v124, 0, 1, s[48:49]
	v_cmp_ne_u32_e64 s[4:5], 1, v124
	s_cbranch_vccnz .LBB0_224
	global_store_dwordx4 v[150:151], v[118:121], off offset:512 nt
	global_store_dwordx4 v[150:151], v[114:117], off offset:528 nt
.LBB0_224:
	s_nop 1
	v_or_b32_e32 v114, 16, v148
	v_ashrrev_i32_e32 v115, 31, v114
	v_lshlrev_b64 v[114:115], 9, v[114:115]
	v_or_b32_e32 v114, v114, v161
	v_lshl_add_u64 v[116:117], v[114:115], 1, s[76:77]
	v_lshl_add_u64 v[114:115], v[114:115], 2, s[78:79]
	v_pk_mul_f32 v[112:113], v[122:123], v[112:113]
	v_pk_mul_f32 v[110:111], v[146:147], v[110:111]
	v_pk_mul_f32 v[108:109], v[122:123], v[108:109]
	v_pk_mul_f32 v[106:107], v[146:147], v[106:107]
	s_and_b64 vcc, exec, s[4:5]
	v_cvt_pk_bf16_f32 v118, v110, v111
	v_cvt_pk_bf16_f32 v119, v112, v113
	v_cvt_pk_bf16_f32 v120, v106, v107
	v_cvt_pk_bf16_f32 v121, v108, v109
	global_store_dwordx4 v[116:117], v[118:121], off sc1 nt
	s_cbranch_vccnz .LBB0_226
	global_store_dwordx4 v[114:115], v[110:113], off nt
	global_store_dwordx4 v[114:115], v[106:109], off offset:16 nt
.LBB0_226:
	s_nop 1
	v_mov_b32_e32 v106, v146
	v_mov_b32_e32 v107, v146
	v_pk_mul_f32 v[104:105], v[106:107], v[104:105]
	v_pk_mul_f32 v[102:103], v[146:147], v[102:103]
	v_pk_mul_f32 v[100:101], v[106:107], v[100:101]
	v_pk_mul_f32 v[98:99], v[146:147], v[98:99]
	s_and_b64 vcc, exec, s[4:5]
	v_cvt_pk_bf16_f32 v108, v102, v103
	v_cvt_pk_bf16_f32 v109, v104, v105
	v_cvt_pk_bf16_f32 v110, v98, v99
	v_cvt_pk_bf16_f32 v111, v100, v101
	global_store_dwordx4 v[116:117], v[108:111], off offset:256 sc1 nt
	s_cbranch_vccnz .LBB0_228
	global_store_dwordx4 v[114:115], v[102:105], off offset:512 nt
	global_store_dwordx4 v[114:115], v[98:101], off offset:528 nt
.LBB0_228:
	s_nop 1
	v_or_b32_e32 v98, 32, v148
	v_ashrrev_i32_e32 v99, 31, v98
	v_lshlrev_b64 v[98:99], 9, v[98:99]
	v_or_b32_e32 v98, v98, v161
	v_lshl_add_u64 v[100:101], v[98:99], 1, s[76:77]
	v_lshl_add_u64 v[98:99], v[98:99], 2, s[78:79]
	v_pk_mul_f32 v[96:97], v[106:107], v[96:97]
	v_pk_mul_f32 v[94:95], v[146:147], v[94:95]
	v_pk_mul_f32 v[92:93], v[106:107], v[92:93]
	v_pk_mul_f32 v[90:91], v[146:147], v[90:91]
	s_and_b64 vcc, exec, s[4:5]
	v_cvt_pk_bf16_f32 v102, v94, v95
	v_cvt_pk_bf16_f32 v103, v96, v97
	v_cvt_pk_bf16_f32 v104, v90, v91
	v_cvt_pk_bf16_f32 v105, v92, v93
	global_store_dwordx4 v[100:101], v[102:105], off sc1 nt
	s_cbranch_vccnz .LBB0_230
	global_store_dwordx4 v[98:99], v[94:97], off nt
	global_store_dwordx4 v[98:99], v[90:93], off offset:16 nt
.LBB0_230:
	s_nop 1
	v_mov_b32_e32 v90, v146
	v_mov_b32_e32 v91, v146
	v_pk_mul_f32 v[88:89], v[90:91], v[88:89]
	v_pk_mul_f32 v[86:87], v[146:147], v[86:87]
	v_pk_mul_f32 v[84:85], v[90:91], v[84:85]
	v_pk_mul_f32 v[82:83], v[146:147], v[82:83]
	s_and_b64 vcc, exec, s[4:5]
	v_cvt_pk_bf16_f32 v92, v86, v87
	v_cvt_pk_bf16_f32 v93, v88, v89
	v_cvt_pk_bf16_f32 v94, v82, v83
	v_cvt_pk_bf16_f32 v95, v84, v85
	global_store_dwordx4 v[100:101], v[92:95], off offset:256 sc1 nt
	s_cbranch_vccnz .LBB0_232
	global_store_dwordx4 v[98:99], v[86:89], off offset:512 nt
	global_store_dwordx4 v[98:99], v[82:85], off offset:528 nt
.LBB0_232:
	s_nop 1
	v_or_b32_e32 v82, 48, v148
	v_ashrrev_i32_e32 v83, 31, v82
	v_lshlrev_b64 v[82:83], 9, v[82:83]
	v_or_b32_e32 v82, v82, v161
	v_lshl_add_u64 v[84:85], v[82:83], 1, s[76:77]
	v_lshl_add_u64 v[82:83], v[82:83], 2, s[78:79]
	v_pk_mul_f32 v[80:81], v[90:91], v[80:81]
	v_pk_mul_f32 v[78:79], v[146:147], v[78:79]
	v_pk_mul_f32 v[76:77], v[90:91], v[76:77]
	v_pk_mul_f32 v[74:75], v[146:147], v[74:75]
	s_and_b64 vcc, exec, s[4:5]
	v_cvt_pk_bf16_f32 v86, v78, v79
	v_cvt_pk_bf16_f32 v87, v80, v81
	v_cvt_pk_bf16_f32 v88, v74, v75
	v_cvt_pk_bf16_f32 v89, v76, v77
	global_store_dwordx4 v[84:85], v[86:89], off sc1 nt
	s_cbranch_vccnz .LBB0_234
	global_store_dwordx4 v[82:83], v[78:81], off nt
	global_store_dwordx4 v[82:83], v[74:77], off offset:16 nt
.LBB0_234:
	s_nop 1
	v_mov_b32_e32 v74, v146
	v_mov_b32_e32 v75, v146
	v_pk_mul_f32 v[72:73], v[74:75], v[72:73]
	v_pk_mul_f32 v[70:71], v[146:147], v[70:71]
	v_pk_mul_f32 v[68:69], v[74:75], v[68:69]
	v_pk_mul_f32 v[66:67], v[146:147], v[66:67]
	s_and_b64 vcc, exec, s[4:5]
	v_cvt_pk_bf16_f32 v76, v70, v71
	v_cvt_pk_bf16_f32 v77, v72, v73
	v_cvt_pk_bf16_f32 v78, v66, v67
	v_cvt_pk_bf16_f32 v79, v68, v69
	global_store_dwordx4 v[84:85], v[76:79], off offset:256 sc1 nt
	s_cbranch_vccnz .LBB0_236
	global_store_dwordx4 v[82:83], v[70:73], off offset:512 nt
	global_store_dwordx4 v[82:83], v[66:69], off offset:528 nt
.LBB0_236:
	s_nop 1
	v_lshlrev_b64 v[66:67], 9, v[148:149]
	v_or_b32_e32 v66, v66, v161
	s_mov_b64 s[48:49], 0x10000
	v_lshl_add_u64 v[66:67], v[66:67], 0, s[48:49]
	v_lshl_add_u64 v[68:69], v[66:67], 1, s[76:77]
	v_lshl_add_u64 v[66:67], v[66:67], 2, s[78:79]
	v_pk_mul_f32 v[64:65], v[74:75], v[64:65]
	v_pk_mul_f32 v[62:63], v[146:147], v[62:63]
	v_pk_mul_f32 v[60:61], v[74:75], v[60:61]
	v_pk_mul_f32 v[58:59], v[146:147], v[58:59]
	s_and_b64 vcc, exec, s[4:5]
	v_cvt_pk_bf16_f32 v70, v62, v63
	v_cvt_pk_bf16_f32 v71, v64, v65
	v_cvt_pk_bf16_f32 v72, v58, v59
	v_cvt_pk_bf16_f32 v73, v60, v61
	global_store_dwordx4 v[68:69], v[70:73], off sc1 nt
	s_cbranch_vccnz .LBB0_238
	global_store_dwordx4 v[66:67], v[62:65], off nt
	global_store_dwordx4 v[66:67], v[58:61], off offset:16 nt
.LBB0_238:
	s_nop 1
	v_mov_b32_e32 v58, v146
	v_mov_b32_e32 v59, v146
	v_pk_mul_f32 v[56:57], v[58:59], v[56:57]
	v_pk_mul_f32 v[54:55], v[146:147], v[54:55]
	v_pk_mul_f32 v[52:53], v[58:59], v[52:53]
	v_pk_mul_f32 v[50:51], v[146:147], v[50:51]
	s_and_b64 vcc, exec, s[4:5]
	v_cvt_pk_bf16_f32 v60, v54, v55
	v_cvt_pk_bf16_f32 v61, v56, v57
	v_cvt_pk_bf16_f32 v62, v50, v51
	v_cvt_pk_bf16_f32 v63, v52, v53
	global_store_dwordx4 v[68:69], v[60:63], off offset:256 sc1 nt
	s_cbranch_vccnz .LBB0_240
	global_store_dwordx4 v[66:67], v[54:57], off offset:512 nt
	global_store_dwordx4 v[66:67], v[50:53], off offset:528 nt
.LBB0_240:
	s_nop 1
	v_lshlrev_b64 v[50:51], 9, v[148:149]
	v_or_b32_e32 v50, v50, v161
	s_mov_b64 s[48:49], 0x12000
	v_lshl_add_u64 v[50:51], v[50:51], 0, s[48:49]
	v_lshl_add_u64 v[52:53], v[50:51], 1, s[76:77]
	v_lshl_add_u64 v[50:51], v[50:51], 2, s[78:79]
	v_pk_mul_f32 v[48:49], v[58:59], v[48:49]
	v_pk_mul_f32 v[46:47], v[146:147], v[46:47]
	v_pk_mul_f32 v[44:45], v[58:59], v[44:45]
	v_pk_mul_f32 v[42:43], v[146:147], v[42:43]
	s_and_b64 vcc, exec, s[4:5]
	v_cvt_pk_bf16_f32 v54, v46, v47
	v_cvt_pk_bf16_f32 v55, v48, v49
	v_cvt_pk_bf16_f32 v56, v42, v43
	v_cvt_pk_bf16_f32 v57, v44, v45
	global_store_dwordx4 v[52:53], v[54:57], off sc1 nt
	s_cbranch_vccnz .LBB0_242
	global_store_dwordx4 v[50:51], v[46:49], off nt
	global_store_dwordx4 v[50:51], v[42:45], off offset:16 nt
.LBB0_242:
	s_nop 1
	v_mov_b32_e32 v42, v146
	v_mov_b32_e32 v43, v146
	v_pk_mul_f32 v[40:41], v[42:43], v[40:41]
	v_pk_mul_f32 v[38:39], v[146:147], v[38:39]
	v_pk_mul_f32 v[36:37], v[42:43], v[36:37]
	v_pk_mul_f32 v[34:35], v[146:147], v[34:35]
	s_and_b64 vcc, exec, s[4:5]
	v_cvt_pk_bf16_f32 v44, v38, v39
	v_cvt_pk_bf16_f32 v45, v40, v41
	v_cvt_pk_bf16_f32 v46, v34, v35
	v_cvt_pk_bf16_f32 v47, v36, v37
	global_store_dwordx4 v[52:53], v[44:47], off offset:256 sc1 nt
	s_cbranch_vccnz .LBB0_244
	global_store_dwordx4 v[50:51], v[38:41], off offset:512 nt
	global_store_dwordx4 v[50:51], v[34:37], off offset:528 nt
.LBB0_244:
	s_nop 1
	v_lshlrev_b64 v[34:35], 9, v[148:149]
	v_or_b32_e32 v34, v34, v161
	s_mov_b64 s[48:49], 0x14000
	v_lshl_add_u64 v[34:35], v[34:35], 0, s[48:49]
	v_lshl_add_u64 v[36:37], v[34:35], 1, s[76:77]
	v_lshl_add_u64 v[34:35], v[34:35], 2, s[78:79]
	v_pk_mul_f32 v[32:33], v[42:43], v[32:33]
	v_pk_mul_f32 v[30:31], v[146:147], v[30:31]
	v_pk_mul_f32 v[28:29], v[42:43], v[28:29]
	v_pk_mul_f32 v[26:27], v[146:147], v[26:27]
	s_and_b64 vcc, exec, s[4:5]
	v_cvt_pk_bf16_f32 v38, v30, v31
	v_cvt_pk_bf16_f32 v39, v32, v33
	v_cvt_pk_bf16_f32 v40, v26, v27
	v_cvt_pk_bf16_f32 v41, v28, v29
	global_store_dwordx4 v[36:37], v[38:41], off sc1 nt
	s_cbranch_vccnz .LBB0_246
	global_store_dwordx4 v[34:35], v[30:33], off nt
	global_store_dwordx4 v[34:35], v[26:29], off offset:16 nt
.LBB0_246:
	s_nop 1
	v_mov_b32_e32 v26, v146
	v_mov_b32_e32 v27, v146
	v_pk_mul_f32 v[24:25], v[26:27], v[24:25]
	v_pk_mul_f32 v[22:23], v[146:147], v[22:23]
	v_pk_mul_f32 v[20:21], v[26:27], v[20:21]
	v_pk_mul_f32 v[18:19], v[146:147], v[18:19]
	s_and_b64 vcc, exec, s[4:5]
	v_cvt_pk_bf16_f32 v28, v22, v23
	v_cvt_pk_bf16_f32 v29, v24, v25
	v_cvt_pk_bf16_f32 v30, v18, v19
	v_cvt_pk_bf16_f32 v31, v20, v21
	global_store_dwordx4 v[36:37], v[28:31], off offset:256 sc1 nt
	s_cbranch_vccnz .LBB0_248
	global_store_dwordx4 v[34:35], v[22:25], off offset:512 nt
	global_store_dwordx4 v[34:35], v[18:21], off offset:528 nt
.LBB0_248:
	s_nop 1
	v_lshlrev_b64 v[18:19], 9, v[148:149]
	v_or_b32_e32 v18, v18, v161
	s_mov_b64 s[48:49], 0x16000
	v_lshl_add_u64 v[18:19], v[18:19], 0, s[48:49]
	v_lshl_add_u64 v[20:21], v[18:19], 1, s[76:77]
	v_lshl_add_u64 v[18:19], v[18:19], 2, s[78:79]
	v_pk_mul_f32 v[16:17], v[26:27], v[16:17]
	v_pk_mul_f32 v[14:15], v[146:147], v[14:15]
	v_pk_mul_f32 v[12:13], v[26:27], v[12:13]
	v_pk_mul_f32 v[10:11], v[146:147], v[10:11]
	s_and_b64 vcc, exec, s[4:5]
	v_cvt_pk_bf16_f32 v22, v14, v15
	v_cvt_pk_bf16_f32 v23, v16, v17
	v_cvt_pk_bf16_f32 v24, v10, v11
	v_cvt_pk_bf16_f32 v25, v12, v13
	global_store_dwordx4 v[20:21], v[22:25], off sc1 nt
	s_cbranch_vccnz .LBB0_250
	global_store_dwordx4 v[18:19], v[14:17], off nt
	global_store_dwordx4 v[18:19], v[10:13], off offset:16 nt
.LBB0_250:
	s_nop 1
	v_mov_b32_e32 v10, v146
	v_mov_b32_e32 v11, v146
	v_pk_mul_f32 v[8:9], v[10:11], v[8:9]
	v_pk_mul_f32 v[6:7], v[146:147], v[6:7]
	v_pk_mul_f32 v[4:5], v[10:11], v[4:5]
	v_pk_mul_f32 v[2:3], v[146:147], v[2:3]
	s_and_b64 vcc, exec, s[4:5]
	v_cvt_pk_bf16_f32 v10, v6, v7
	v_cvt_pk_bf16_f32 v11, v8, v9
	v_cvt_pk_bf16_f32 v12, v2, v3
	v_cvt_pk_bf16_f32 v13, v4, v5
	global_store_dwordx4 v[20:21], v[10:13], off offset:256 sc1 nt
	s_cbranch_vccnz .LBB0_252
	global_store_dwordx4 v[18:19], v[6:9], off offset:512 nt
	global_store_dwordx4 v[18:19], v[2:5], off offset:528 nt

.LBB0_713:
	s_or_b64 exec, exec, s[12:13]
	s_lshl_b32 s4, s33, 5
	s_lshl_b32 s5, s6, 8
	s_or_b32 s4, s5, s4
	v_add_u32_e32 v150, s3, v152
	v_and_or_b32 v148, v3, 24, s4
	v_ashrrev_i32_e32 v151, 31, v150
	v_ashrrev_i32_e32 v149, 31, v148
	s_waitcnt lgkmcnt(0)
	v_lshlrev_b64 v[132:133], 10, v[150:151]
	v_readlane_b32 s16, v244, 7
	s_waitcnt vmcnt(0) lgkmcnt(0)
	s_barrier
	v_lshl_add_u64 v[136:137], v[148:149], 2, s[52:53]
	v_lshl_add_u64 v[164:165], v[132:133], 0, v[148:149]
	v_readlane_b32 s17, v244, 8
	global_load_dwordx4 v[140:143], v[136:137], off offset:16
	global_load_dwordx4 v[144:147], v[136:137], off
	v_lshl_add_u64 v[166:167], v[164:165], 2, s[16:17]
	global_load_dwordx4 v[156:159], v[166:167], off nt
	global_load_dwordx4 v[160:163], v[166:167], off offset:16 nt
	v_lshl_add_u32 v3, v152, 2, 0
	ds_read_b32 v168, v3 offset:4096
	v_lshl_add_u64 v[164:165], v[164:165], 1, s[62:63]
	global_load_dwordx4 v[132:135], v[136:137], off offset:528
	s_nop 0
	global_load_dwordx4 v[136:139], v[136:137], off offset:512
	s_lshl_b32 s4, s6, 2
	s_ashr_i32 s5, s4, 31
	s_mov_b32 s11, 0
	v_readlane_b32 s18, v244, 9
	v_readlane_b32 s19, v244, 10
	v_readlane_b32 s20, v244, 11
	v_readlane_b32 s21, v244, 12
	v_readlane_b32 s22, v244, 13
	v_readlane_b32 s23, v244, 14
	v_readlane_b32 s24, v244, 15
	v_readlane_b32 s25, v244, 16
	v_readlane_b32 s26, v244, 17
	v_readlane_b32 s27, v244, 18
	v_readlane_b32 s28, v244, 19
	v_readlane_b32 s29, v244, 20
	v_readlane_b32 s30, v244, 21
	v_readlane_b32 s31, v244, 22
	s_waitcnt vmcnt(0)
	v_pk_mul_f32 v[126:127], v[126:127], v[142:143]
	v_pk_mul_f32 v[130:131], v[130:131], v[146:147]
	v_pk_mul_f32 v[128:129], v[128:129], v[144:145]
	v_pk_mul_f32 v[124:125], v[124:125], v[140:141]
	s_waitcnt lgkmcnt(0)
	v_pk_fma_f32 v[158:159], v[130:131], v[168:169], v[158:159] op_sel_hi:[1,0,1]
	v_pk_fma_f32 v[156:157], v[128:129], v[168:169], v[156:157] op_sel_hi:[1,0,1]
	v_pk_fma_f32 v[162:163], v[126:127], v[168:169], v[162:163] op_sel_hi:[1,0,1]
	v_pk_fma_f32 v[160:161], v[124:125], v[168:169], v[160:161] op_sel_hi:[1,0,1]
	v_cvt_pk_bf16_f32 v124, v156, v157
	v_cvt_pk_bf16_f32 v125, v158, v159
	v_pk_mul_f32 v[122:123], v[122:123], v[138:139]
	v_cvt_pk_bf16_f32 v126, v160, v161
	v_cvt_pk_bf16_f32 v127, v162, v163
	global_store_dwordx4 v[164:165], v[124:127], off sc1 nt
	global_load_dwordx4 v[124:127], v[166:167], off offset:512 nt
	s_nop 0
	global_load_dwordx4 v[128:131], v[166:167], off offset:528 nt
	v_pk_mul_f32 v[120:121], v[120:121], v[136:137]
	v_pk_mul_f32 v[118:119], v[118:119], v[134:135]
	v_pk_mul_f32 v[116:117], v[116:117], v[132:133]
	v_mul_f32_e32 v155, v157, v157
	v_mul_f32_e32 v157, v159, v159
	v_mul_f32_e32 v159, v161, v161
	v_mul_f32_e32 v161, v163, v163
	v_fmac_f32_e32 v155, v156, v156
	v_fmac_f32_e32 v157, v158, v158
	v_fmac_f32_e32 v159, v160, v160
	v_fmac_f32_e32 v161, v162, v162
	v_add_f32_e32 v155, v155, v157
	v_add_f32_e32 v156, v159, v161
	v_add_f32_e32 v155, v155, v156
	s_waitcnt vmcnt(1)
	v_pk_fma_f32 v[122:123], v[122:123], v[168:169], v[126:127] op_sel_hi:[1,0,1]
	v_pk_fma_f32 v[120:121], v[120:121], v[168:169], v[124:125] op_sel_hi:[1,0,1]
	s_waitcnt vmcnt(0)
	v_pk_fma_f32 v[124:125], v[118:119], v[168:169], v[130:131] op_sel_hi:[1,0,1]
	v_pk_fma_f32 v[126:127], v[116:117], v[168:169], v[128:129] op_sel_hi:[1,0,1]
	v_mul_f32_e32 v116, v121, v121
	v_mul_f32_e32 v117, v123, v123
	v_mul_f32_e32 v118, v127, v127
	v_mul_f32_e32 v119, v125, v125
	v_fmac_f32_e32 v116, v120, v120
	v_fmac_f32_e32 v117, v122, v122
	v_fmac_f32_e32 v118, v126, v126
	v_fmac_f32_e32 v119, v124, v124
	v_add_f32_e32 v116, v116, v117
	v_add_f32_e32 v117, v118, v119
	v_add_f32_e32 v116, v116, v117
	v_add_f32_e32 v116, v155, v116
	ds_bpermute_b32 v117, v153, v116
	v_cvt_pk_bf16_f32 v118, v120, v121
	v_cvt_pk_bf16_f32 v119, v122, v123
	v_cvt_pk_bf16_f32 v120, v126, v127
	v_cvt_pk_bf16_f32 v121, v124, v125
	s_waitcnt lgkmcnt(0)
	v_add_f32_e32 v116, v116, v117
	ds_bpermute_b32 v117, v154, v116
	global_store_dwordx4 v[164:165], v[118:121], off offset:256 sc1 nt
	s_and_saveexec_b64 s[6:7], s[0:1]
	s_cbranch_execz .LBB0_715
	s_waitcnt lgkmcnt(0)
	v_add_f32_e32 v118, v116, v117
	v_lshlrev_b64 v[116:117], 6, v[150:151]
	v_lshl_add_u64 v[116:117], s[86:87], 0, v[116:117]
	v_lshl_add_u64 v[116:117], s[4:5], 2, v[116:117]
	v_lshl_add_u64 v[116:117], v[116:117], 0, s[10:11]
	global_store_dword v[116:117], v118, off
.LBB0_715:
	s_or_b64 exec, exec, s[6:7]
	v_add3_u32 v116, s3, v152, 16
	s_waitcnt lgkmcnt(0)
	v_ashrrev_i32_e32 v117, 31, v116
	v_lshlrev_b64 v[118:119], 10, v[116:117]
	v_readlane_b32 s16, v244, 7
	v_lshl_add_u64 v[126:127], v[118:119], 0, v[148:149]
	v_readlane_b32 s17, v244, 8
	v_pk_mul_f32 v[114:115], v[114:115], v[146:147]
	v_pk_mul_f32 v[112:113], v[112:113], v[144:145]
	v_lshl_add_u64 v[128:129], v[126:127], 2, s[16:17]
	global_load_dwordx4 v[118:121], v[128:129], off nt
	global_load_dwordx4 v[122:125], v[128:129], off offset:16 nt
	ds_read_b32 v130, v3 offset:4160
	v_pk_mul_f32 v[110:111], v[110:111], v[142:143]
	v_pk_mul_f32 v[108:109], v[108:109], v[140:141]
	v_lshl_add_u64 v[126:127], v[126:127], 1, s[62:63]
	v_pk_mul_f32 v[106:107], v[106:107], v[138:139]
	v_pk_mul_f32 v[104:105], v[104:105], v[136:137]
	v_pk_mul_f32 v[102:103], v[102:103], v[134:135]
	v_pk_mul_f32 v[100:101], v[100:101], v[132:133]
	v_readlane_b32 s18, v244, 9
	v_readlane_b32 s19, v244, 10
	v_readlane_b32 s20, v244, 11
	v_readlane_b32 s21, v244, 12
	v_readlane_b32 s22, v244, 13
	v_readlane_b32 s23, v244, 14
	v_readlane_b32 s24, v244, 15
	v_readlane_b32 s25, v244, 16
	v_readlane_b32 s26, v244, 17
	v_readlane_b32 s27, v244, 18
	v_readlane_b32 s28, v244, 19
	v_readlane_b32 s29, v244, 20
	v_readlane_b32 s30, v244, 21
	v_readlane_b32 s31, v244, 22
	s_waitcnt vmcnt(1) lgkmcnt(0)
	v_pk_fma_f32 v[120:121], v[114:115], v[130:131], v[120:121] op_sel_hi:[1,0,1]
	v_pk_fma_f32 v[118:119], v[112:113], v[130:131], v[118:119] op_sel_hi:[1,0,1]
	s_waitcnt vmcnt(0)
	v_pk_fma_f32 v[124:125], v[110:111], v[130:131], v[124:125] op_sel_hi:[1,0,1]
	v_pk_fma_f32 v[122:123], v[108:109], v[130:131], v[122:123] op_sel_hi:[1,0,1]
	v_cvt_pk_bf16_f32 v108, v118, v119
	v_cvt_pk_bf16_f32 v109, v120, v121
	v_mul_f32_e32 v119, v119, v119
	v_cvt_pk_bf16_f32 v110, v122, v123
	v_cvt_pk_bf16_f32 v111, v124, v125
	global_store_dwordx4 v[126:127], v[108:111], off sc1 nt
	global_load_dwordx4 v[108:111], v[128:129], off offset:512 nt
	s_nop 0
	global_load_dwordx4 v[112:115], v[128:129], off offset:528 nt
	v_mul_f32_e32 v121, v121, v121
	v_mul_f32_e32 v123, v123, v123
	v_mul_f32_e32 v125, v125, v125
	v_fmac_f32_e32 v119, v118, v118
	v_fmac_f32_e32 v121, v120, v120
	v_fmac_f32_e32 v123, v122, v122
	v_fmac_f32_e32 v125, v124, v124
	v_add_f32_e32 v118, v119, v121
	v_add_f32_e32 v119, v123, v125
	v_add_f32_e32 v118, v118, v119
	s_waitcnt vmcnt(1)
	v_pk_fma_f32 v[106:107], v[106:107], v[130:131], v[110:111] op_sel_hi:[1,0,1]
	v_pk_fma_f32 v[104:105], v[104:105], v[130:131], v[108:109] op_sel_hi:[1,0,1]
	s_waitcnt vmcnt(0)
	v_pk_fma_f32 v[108:109], v[102:103], v[130:131], v[114:115] op_sel_hi:[1,0,1]
	v_pk_fma_f32 v[110:111], v[100:101], v[130:131], v[112:113] op_sel_hi:[1,0,1]
	v_mul_f32_e32 v100, v105, v105
	v_mul_f32_e32 v101, v107, v107
	v_mul_f32_e32 v102, v111, v111
	v_mul_f32_e32 v103, v109, v109
	v_fmac_f32_e32 v100, v104, v104
	v_fmac_f32_e32 v101, v106, v106
	v_fmac_f32_e32 v102, v110, v110
	v_fmac_f32_e32 v103, v108, v108
	v_add_f32_e32 v100, v100, v101
	v_add_f32_e32 v101, v102, v103
	v_add_f32_e32 v100, v100, v101
	v_add_f32_e32 v100, v118, v100
	ds_bpermute_b32 v101, v153, v100
	v_cvt_pk_bf16_f32 v102, v104, v105
	v_cvt_pk_bf16_f32 v103, v106, v107
	v_cvt_pk_bf16_f32 v104, v110, v111
	v_cvt_pk_bf16_f32 v105, v108, v109
	s_waitcnt lgkmcnt(0)
	v_add_f32_e32 v100, v100, v101
	ds_bpermute_b32 v101, v154, v100
	global_store_dwordx4 v[126:127], v[102:105], off offset:256 sc1 nt
	s_and_saveexec_b64 s[6:7], s[0:1]
	s_cbranch_execz .LBB0_717
	s_waitcnt lgkmcnt(0)
	v_add_f32_e32 v102, v100, v101
	v_lshlrev_b64 v[100:101], 6, v[116:117]
	v_lshl_add_u64 v[100:101], s[86:87], 0, v[100:101]
	v_lshl_add_u64 v[100:101], s[4:5], 2, v[100:101]
	v_lshl_add_u64 v[100:101], v[100:101], 0, s[10:11]
	global_store_dword v[100:101], v102, off
.LBB0_717:
	s_or_b64 exec, exec, s[6:7]
	v_add3_u32 v100, s3, v152, 32
	s_waitcnt lgkmcnt(0)
	v_ashrrev_i32_e32 v101, 31, v100
	v_lshlrev_b64 v[102:103], 10, v[100:101]
	v_readlane_b32 s16, v244, 7
	v_lshl_add_u64 v[110:111], v[102:103], 0, v[148:149]
	v_readlane_b32 s17, v244, 8
	v_pk_mul_f32 v[98:99], v[98:99], v[146:147]
	v_pk_mul_f32 v[96:97], v[96:97], v[144:145]
	v_lshl_add_u64 v[112:113], v[110:111], 2, s[16:17]
	global_load_dwordx4 v[102:105], v[112:113], off nt
	global_load_dwordx4 v[106:109], v[112:113], off offset:16 nt
	ds_read_b32 v114, v3 offset:4224
	v_pk_mul_f32 v[94:95], v[94:95], v[142:143]
	v_pk_mul_f32 v[92:93], v[92:93], v[140:141]
	v_lshl_add_u64 v[110:111], v[110:111], 1, s[62:63]
	v_pk_mul_f32 v[90:91], v[90:91], v[138:139]
	v_pk_mul_f32 v[88:89], v[88:89], v[136:137]
	v_pk_mul_f32 v[86:87], v[86:87], v[134:135]
	v_pk_mul_f32 v[84:85], v[84:85], v[132:133]
	v_readlane_b32 s18, v244, 9
	v_readlane_b32 s19, v244, 10
	v_readlane_b32 s20, v244, 11
	v_readlane_b32 s21, v244, 12
	v_readlane_b32 s22, v244, 13
	v_readlane_b32 s23, v244, 14
	v_readlane_b32 s24, v244, 15
	v_readlane_b32 s25, v244, 16
	v_readlane_b32 s26, v244, 17
	v_readlane_b32 s27, v244, 18
	v_readlane_b32 s28, v244, 19
	v_readlane_b32 s29, v244, 20
	v_readlane_b32 s30, v244, 21
	v_readlane_b32 s31, v244, 22
	s_waitcnt vmcnt(1) lgkmcnt(0)
	v_pk_fma_f32 v[104:105], v[98:99], v[114:115], v[104:105] op_sel_hi:[1,0,1]
	v_pk_fma_f32 v[102:103], v[96:97], v[114:115], v[102:103] op_sel_hi:[1,0,1]
	s_waitcnt vmcnt(0)
	v_pk_fma_f32 v[108:109], v[94:95], v[114:115], v[108:109] op_sel_hi:[1,0,1]
	v_pk_fma_f32 v[106:107], v[92:93], v[114:115], v[106:107] op_sel_hi:[1,0,1]
	v_cvt_pk_bf16_f32 v92, v102, v103
	v_cvt_pk_bf16_f32 v93, v104, v105
	v_mul_f32_e32 v103, v103, v103
	v_cvt_pk_bf16_f32 v94, v106, v107
	v_cvt_pk_bf16_f32 v95, v108, v109
	global_store_dwordx4 v[110:111], v[92:95], off sc1 nt
	global_load_dwordx4 v[92:95], v[112:113], off offset:512 nt
	s_nop 0
	global_load_dwordx4 v[96:99], v[112:113], off offset:528 nt
	v_mul_f32_e32 v105, v105, v105
	v_mul_f32_e32 v107, v107, v107
	v_mul_f32_e32 v109, v109, v109
	v_fmac_f32_e32 v103, v102, v102
	v_fmac_f32_e32 v105, v104, v104
	v_fmac_f32_e32 v107, v106, v106
	v_fmac_f32_e32 v109, v108, v108
	v_add_f32_e32 v102, v103, v105
	v_add_f32_e32 v103, v107, v109
	v_add_f32_e32 v102, v102, v103
	s_waitcnt vmcnt(1)
	v_pk_fma_f32 v[90:91], v[90:91], v[114:115], v[94:95] op_sel_hi:[1,0,1]
	v_pk_fma_f32 v[88:89], v[88:89], v[114:115], v[92:93] op_sel_hi:[1,0,1]
	s_waitcnt vmcnt(0)
	v_pk_fma_f32 v[92:93], v[86:87], v[114:115], v[98:99] op_sel_hi:[1,0,1]
	v_pk_fma_f32 v[94:95], v[84:85], v[114:115], v[96:97] op_sel_hi:[1,0,1]
	v_mul_f32_e32 v84, v89, v89
	v_mul_f32_e32 v85, v91, v91
	v_mul_f32_e32 v86, v95, v95
	v_mul_f32_e32 v87, v93, v93
	v_fmac_f32_e32 v84, v88, v88
	v_fmac_f32_e32 v85, v90, v90
	v_fmac_f32_e32 v86, v94, v94
	v_fmac_f32_e32 v87, v92, v92
	v_add_f32_e32 v84, v84, v85
	v_add_f32_e32 v85, v86, v87
	v_add_f32_e32 v84, v84, v85
	v_add_f32_e32 v84, v102, v84
	ds_bpermute_b32 v85, v153, v84
	v_cvt_pk_bf16_f32 v86, v88, v89
	v_cvt_pk_bf16_f32 v87, v90, v91
	v_cvt_pk_bf16_f32 v88, v94, v95
	v_cvt_pk_bf16_f32 v89, v92, v93
	s_waitcnt lgkmcnt(0)
	v_add_f32_e32 v84, v84, v85
	ds_bpermute_b32 v85, v154, v84
	global_store_dwordx4 v[110:111], v[86:89], off offset:256 sc1 nt
	s_and_saveexec_b64 s[6:7], s[0:1]
	s_cbranch_execz .LBB0_719
	s_waitcnt lgkmcnt(0)
	v_add_f32_e32 v86, v84, v85
	v_lshlrev_b64 v[84:85], 6, v[100:101]
	v_lshl_add_u64 v[84:85], s[86:87], 0, v[84:85]
	v_lshl_add_u64 v[84:85], s[4:5], 2, v[84:85]
	v_lshl_add_u64 v[84:85], v[84:85], 0, s[10:11]
	global_store_dword v[84:85], v86, off
.LBB0_719:
	s_or_b64 exec, exec, s[6:7]
	v_add3_u32 v84, s3, v152, 48
	s_waitcnt lgkmcnt(0)
	v_ashrrev_i32_e32 v85, 31, v84
	v_lshlrev_b64 v[86:87], 10, v[84:85]
	v_readlane_b32 s16, v244, 7
	v_lshl_add_u64 v[94:95], v[86:87], 0, v[148:149]
	v_readlane_b32 s17, v244, 8
	v_pk_mul_f32 v[82:83], v[82:83], v[146:147]
	v_pk_mul_f32 v[80:81], v[80:81], v[144:145]
	v_lshl_add_u64 v[96:97], v[94:95], 2, s[16:17]
	global_load_dwordx4 v[86:89], v[96:97], off nt
	global_load_dwordx4 v[90:93], v[96:97], off offset:16 nt
	ds_read_b32 v98, v3 offset:4288
	v_pk_mul_f32 v[78:79], v[78:79], v[142:143]
	v_pk_mul_f32 v[76:77], v[76:77], v[140:141]
	v_lshl_add_u64 v[94:95], v[94:95], 1, s[62:63]
	v_pk_mul_f32 v[74:75], v[74:75], v[138:139]
	v_pk_mul_f32 v[72:73], v[72:73], v[136:137]
	v_pk_mul_f32 v[70:71], v[70:71], v[134:135]
	v_pk_mul_f32 v[68:69], v[68:69], v[132:133]
	v_readlane_b32 s18, v244, 9
	v_readlane_b32 s19, v244, 10
	v_readlane_b32 s20, v244, 11
	v_readlane_b32 s21, v244, 12
	v_readlane_b32 s22, v244, 13
	v_readlane_b32 s23, v244, 14
	v_readlane_b32 s24, v244, 15
	v_readlane_b32 s25, v244, 16
	v_readlane_b32 s26, v244, 17
	v_readlane_b32 s27, v244, 18
	v_readlane_b32 s28, v244, 19
	v_readlane_b32 s29, v244, 20
	v_readlane_b32 s30, v244, 21
	v_readlane_b32 s31, v244, 22
	s_waitcnt vmcnt(1) lgkmcnt(0)
	v_pk_fma_f32 v[88:89], v[82:83], v[98:99], v[88:89] op_sel_hi:[1,0,1]
	v_pk_fma_f32 v[86:87], v[80:81], v[98:99], v[86:87] op_sel_hi:[1,0,1]
	s_waitcnt vmcnt(0)
	v_pk_fma_f32 v[92:93], v[78:79], v[98:99], v[92:93] op_sel_hi:[1,0,1]
	v_pk_fma_f32 v[90:91], v[76:77], v[98:99], v[90:91] op_sel_hi:[1,0,1]
	v_cvt_pk_bf16_f32 v76, v86, v87
	v_cvt_pk_bf16_f32 v77, v88, v89
	v_mul_f32_e32 v87, v87, v87
	v_cvt_pk_bf16_f32 v78, v90, v91
	v_cvt_pk_bf16_f32 v79, v92, v93
	global_store_dwordx4 v[94:95], v[76:79], off sc1 nt
	global_load_dwordx4 v[76:79], v[96:97], off offset:512 nt
	s_nop 0
	global_load_dwordx4 v[80:83], v[96:97], off offset:528 nt
	v_mul_f32_e32 v89, v89, v89
	v_mul_f32_e32 v91, v91, v91
	v_mul_f32_e32 v93, v93, v93
	v_fmac_f32_e32 v87, v86, v86
	v_fmac_f32_e32 v89, v88, v88
	v_fmac_f32_e32 v91, v90, v90
	v_fmac_f32_e32 v93, v92, v92
	v_add_f32_e32 v86, v87, v89
	v_add_f32_e32 v87, v91, v93
	v_add_f32_e32 v86, v86, v87
	s_waitcnt vmcnt(1)
	v_pk_fma_f32 v[74:75], v[74:75], v[98:99], v[78:79] op_sel_hi:[1,0,1]
	v_pk_fma_f32 v[72:73], v[72:73], v[98:99], v[76:77] op_sel_hi:[1,0,1]
	s_waitcnt vmcnt(0)
	v_pk_fma_f32 v[76:77], v[70:71], v[98:99], v[82:83] op_sel_hi:[1,0,1]
	v_pk_fma_f32 v[78:79], v[68:69], v[98:99], v[80:81] op_sel_hi:[1,0,1]
	v_mul_f32_e32 v68, v73, v73
	v_mul_f32_e32 v69, v75, v75
	v_mul_f32_e32 v70, v79, v79
	v_mul_f32_e32 v71, v77, v77
	v_fmac_f32_e32 v68, v72, v72
	v_fmac_f32_e32 v69, v74, v74
	v_fmac_f32_e32 v70, v78, v78
	v_fmac_f32_e32 v71, v76, v76
	v_add_f32_e32 v68, v68, v69
	v_add_f32_e32 v69, v70, v71
	v_add_f32_e32 v68, v68, v69
	v_add_f32_e32 v68, v86, v68
	ds_bpermute_b32 v69, v153, v68
	v_cvt_pk_bf16_f32 v70, v72, v73
	v_cvt_pk_bf16_f32 v71, v74, v75
	v_cvt_pk_bf16_f32 v72, v78, v79
	v_cvt_pk_bf16_f32 v73, v76, v77
	s_waitcnt lgkmcnt(0)
	v_add_f32_e32 v68, v68, v69
	ds_bpermute_b32 v69, v154, v68
	global_store_dwordx4 v[94:95], v[70:73], off offset:256 sc1 nt
	s_and_saveexec_b64 s[6:7], s[0:1]
	s_cbranch_execz .LBB0_721
	s_waitcnt lgkmcnt(0)
	v_add_f32_e32 v70, v68, v69
	v_lshlrev_b64 v[68:69], 6, v[84:85]
	v_lshl_add_u64 v[68:69], s[86:87], 0, v[68:69]
	v_lshl_add_u64 v[68:69], s[4:5], 2, v[68:69]
	v_lshl_add_u64 v[68:69], v[68:69], 0, s[10:11]
	global_store_dword v[68:69], v70, off
.LBB0_721:
	s_or_b64 exec, exec, s[6:7]
	v_add_u32_e32 v68, 0x80, v150
	s_waitcnt lgkmcnt(0)
	v_ashrrev_i32_e32 v69, 31, v68
	v_lshlrev_b64 v[70:71], 10, v[68:69]
	v_readlane_b32 s16, v244, 7
	v_lshl_add_u64 v[78:79], v[70:71], 0, v[148:149]
	v_readlane_b32 s17, v244, 8
	v_pk_mul_f32 v[66:67], v[66:67], v[146:147]
	v_pk_mul_f32 v[64:65], v[64:65], v[144:145]
	v_lshl_add_u64 v[80:81], v[78:79], 2, s[16:17]
	global_load_dwordx4 v[70:73], v[80:81], off nt
	global_load_dwordx4 v[74:77], v[80:81], off offset:16 nt
	ds_read_b32 v82, v3 offset:4608
	v_pk_mul_f32 v[62:63], v[62:63], v[142:143]
	v_pk_mul_f32 v[60:61], v[60:61], v[140:141]
	v_lshl_add_u64 v[78:79], v[78:79], 1, s[62:63]
	v_pk_mul_f32 v[58:59], v[58:59], v[138:139]
	v_pk_mul_f32 v[56:57], v[56:57], v[136:137]
	v_pk_mul_f32 v[54:55], v[54:55], v[134:135]
	v_pk_mul_f32 v[52:53], v[52:53], v[132:133]
	v_readlane_b32 s18, v244, 9
	v_readlane_b32 s19, v244, 10
	v_readlane_b32 s20, v244, 11
	v_readlane_b32 s21, v244, 12
	v_readlane_b32 s22, v244, 13
	v_readlane_b32 s23, v244, 14
	v_readlane_b32 s24, v244, 15
	v_readlane_b32 s25, v244, 16
	v_readlane_b32 s26, v244, 17
	v_readlane_b32 s27, v244, 18
	v_readlane_b32 s28, v244, 19
	v_readlane_b32 s29, v244, 20
	v_readlane_b32 s30, v244, 21
	v_readlane_b32 s31, v244, 22
	s_waitcnt vmcnt(1) lgkmcnt(0)
	v_pk_fma_f32 v[72:73], v[66:67], v[82:83], v[72:73] op_sel_hi:[1,0,1]
	v_pk_fma_f32 v[70:71], v[64:65], v[82:83], v[70:71] op_sel_hi:[1,0,1]
	s_waitcnt vmcnt(0)
	v_pk_fma_f32 v[76:77], v[62:63], v[82:83], v[76:77] op_sel_hi:[1,0,1]
	v_pk_fma_f32 v[74:75], v[60:61], v[82:83], v[74:75] op_sel_hi:[1,0,1]
	v_cvt_pk_bf16_f32 v60, v70, v71
	v_cvt_pk_bf16_f32 v61, v72, v73
	v_mul_f32_e32 v71, v71, v71
	v_cvt_pk_bf16_f32 v62, v74, v75
	v_cvt_pk_bf16_f32 v63, v76, v77
	global_store_dwordx4 v[78:79], v[60:63], off sc1 nt
	global_load_dwordx4 v[60:63], v[80:81], off offset:512 nt
	s_nop 0
	global_load_dwordx4 v[64:67], v[80:81], off offset:528 nt
	v_mul_f32_e32 v73, v73, v73
	v_mul_f32_e32 v75, v75, v75
	v_mul_f32_e32 v77, v77, v77
	v_fmac_f32_e32 v71, v70, v70
	v_fmac_f32_e32 v73, v72, v72
	v_fmac_f32_e32 v75, v74, v74
	v_fmac_f32_e32 v77, v76, v76
	v_add_f32_e32 v70, v71, v73
	v_add_f32_e32 v71, v75, v77
	v_add_f32_e32 v70, v70, v71
	s_waitcnt vmcnt(1)
	v_pk_fma_f32 v[58:59], v[58:59], v[82:83], v[62:63] op_sel_hi:[1,0,1]
	v_pk_fma_f32 v[56:57], v[56:57], v[82:83], v[60:61] op_sel_hi:[1,0,1]
	s_waitcnt vmcnt(0)
	v_pk_fma_f32 v[60:61], v[54:55], v[82:83], v[66:67] op_sel_hi:[1,0,1]
	v_pk_fma_f32 v[62:63], v[52:53], v[82:83], v[64:65] op_sel_hi:[1,0,1]
	v_mul_f32_e32 v52, v57, v57
	v_mul_f32_e32 v53, v59, v59
	v_mul_f32_e32 v54, v63, v63
	v_mul_f32_e32 v55, v61, v61
	v_fmac_f32_e32 v52, v56, v56
	v_fmac_f32_e32 v53, v58, v58
	v_fmac_f32_e32 v54, v62, v62
	v_fmac_f32_e32 v55, v60, v60
	v_add_f32_e32 v52, v52, v53
	v_add_f32_e32 v53, v54, v55
	v_add_f32_e32 v52, v52, v53
	v_add_f32_e32 v52, v70, v52
	ds_bpermute_b32 v53, v153, v52
	v_cvt_pk_bf16_f32 v54, v56, v57
	v_cvt_pk_bf16_f32 v55, v58, v59
	v_cvt_pk_bf16_f32 v56, v62, v63
	v_cvt_pk_bf16_f32 v57, v60, v61
	s_waitcnt lgkmcnt(0)
	v_add_f32_e32 v52, v52, v53
	ds_bpermute_b32 v53, v154, v52
	global_store_dwordx4 v[78:79], v[54:57], off offset:256 sc1 nt
	s_and_saveexec_b64 s[6:7], s[0:1]
	s_cbranch_execz .LBB0_723
	s_waitcnt lgkmcnt(0)
	v_add_f32_e32 v54, v52, v53
	v_lshlrev_b64 v[52:53], 6, v[68:69]
	v_lshl_add_u64 v[52:53], s[86:87], 0, v[52:53]
	v_lshl_add_u64 v[52:53], s[4:5], 2, v[52:53]
	v_lshl_add_u64 v[52:53], v[52:53], 0, s[10:11]
	global_store_dword v[52:53], v54, off
.LBB0_723:
	s_or_b64 exec, exec, s[6:7]
	v_add_u32_e32 v52, 0x90, v150
	s_waitcnt lgkmcnt(0)
	v_ashrrev_i32_e32 v53, 31, v52
	v_lshlrev_b64 v[54:55], 10, v[52:53]
	v_readlane_b32 s16, v244, 7
	v_lshl_add_u64 v[62:63], v[54:55], 0, v[148:149]
	v_readlane_b32 s17, v244, 8
	v_pk_mul_f32 v[50:51], v[50:51], v[146:147]
	v_pk_mul_f32 v[48:49], v[48:49], v[144:145]
	v_lshl_add_u64 v[64:65], v[62:63], 2, s[16:17]
	global_load_dwordx4 v[54:57], v[64:65], off nt
	global_load_dwordx4 v[58:61], v[64:65], off offset:16 nt
	ds_read_b32 v66, v3 offset:4672
	v_pk_mul_f32 v[46:47], v[46:47], v[142:143]
	v_pk_mul_f32 v[44:45], v[44:45], v[140:141]
	v_lshl_add_u64 v[62:63], v[62:63], 1, s[62:63]
	v_pk_mul_f32 v[42:43], v[42:43], v[138:139]
	v_pk_mul_f32 v[40:41], v[40:41], v[136:137]
	v_pk_mul_f32 v[38:39], v[38:39], v[134:135]
	v_pk_mul_f32 v[36:37], v[36:37], v[132:133]
	v_readlane_b32 s18, v244, 9
	v_readlane_b32 s19, v244, 10
	v_readlane_b32 s20, v244, 11
	v_readlane_b32 s21, v244, 12
	v_readlane_b32 s22, v244, 13
	v_readlane_b32 s23, v244, 14
	v_readlane_b32 s24, v244, 15
	v_readlane_b32 s25, v244, 16
	v_readlane_b32 s26, v244, 17
	v_readlane_b32 s27, v244, 18
	v_readlane_b32 s28, v244, 19
	v_readlane_b32 s29, v244, 20
	v_readlane_b32 s30, v244, 21
	v_readlane_b32 s31, v244, 22
	s_waitcnt vmcnt(1) lgkmcnt(0)
	v_pk_fma_f32 v[56:57], v[50:51], v[66:67], v[56:57] op_sel_hi:[1,0,1]
	v_pk_fma_f32 v[54:55], v[48:49], v[66:67], v[54:55] op_sel_hi:[1,0,1]
	s_waitcnt vmcnt(0)
	v_pk_fma_f32 v[60:61], v[46:47], v[66:67], v[60:61] op_sel_hi:[1,0,1]
	v_pk_fma_f32 v[58:59], v[44:45], v[66:67], v[58:59] op_sel_hi:[1,0,1]
	v_cvt_pk_bf16_f32 v44, v54, v55
	v_cvt_pk_bf16_f32 v45, v56, v57
	v_mul_f32_e32 v55, v55, v55
	v_cvt_pk_bf16_f32 v46, v58, v59
	v_cvt_pk_bf16_f32 v47, v60, v61
	global_store_dwordx4 v[62:63], v[44:47], off sc1 nt
	global_load_dwordx4 v[44:47], v[64:65], off offset:512 nt
	s_nop 0
	global_load_dwordx4 v[48:51], v[64:65], off offset:528 nt
	v_mul_f32_e32 v57, v57, v57
	v_mul_f32_e32 v59, v59, v59
	v_mul_f32_e32 v61, v61, v61
	v_fmac_f32_e32 v55, v54, v54
	v_fmac_f32_e32 v57, v56, v56
	v_fmac_f32_e32 v59, v58, v58
	v_fmac_f32_e32 v61, v60, v60
	v_add_f32_e32 v54, v55, v57
	v_add_f32_e32 v55, v59, v61
	v_add_f32_e32 v54, v54, v55
	s_waitcnt vmcnt(1)
	v_pk_fma_f32 v[42:43], v[42:43], v[66:67], v[46:47] op_sel_hi:[1,0,1]
	v_pk_fma_f32 v[40:41], v[40:41], v[66:67], v[44:45] op_sel_hi:[1,0,1]
	s_waitcnt vmcnt(0)
	v_pk_fma_f32 v[44:45], v[38:39], v[66:67], v[50:51] op_sel_hi:[1,0,1]
	v_pk_fma_f32 v[46:47], v[36:37], v[66:67], v[48:49] op_sel_hi:[1,0,1]
	v_mul_f32_e32 v36, v41, v41
	v_mul_f32_e32 v37, v43, v43
	v_mul_f32_e32 v38, v47, v47
	v_mul_f32_e32 v39, v45, v45
	v_fmac_f32_e32 v36, v40, v40
	v_fmac_f32_e32 v37, v42, v42
	v_fmac_f32_e32 v38, v46, v46
	v_fmac_f32_e32 v39, v44, v44
	v_add_f32_e32 v36, v36, v37
	v_add_f32_e32 v37, v38, v39
	v_add_f32_e32 v36, v36, v37
	v_add_f32_e32 v36, v54, v36
	ds_bpermute_b32 v37, v153, v36
	v_cvt_pk_bf16_f32 v38, v40, v41
	v_cvt_pk_bf16_f32 v39, v42, v43
	v_cvt_pk_bf16_f32 v40, v46, v47
	v_cvt_pk_bf16_f32 v41, v44, v45
	s_waitcnt lgkmcnt(0)
	v_add_f32_e32 v36, v36, v37
	ds_bpermute_b32 v37, v154, v36
	global_store_dwordx4 v[62:63], v[38:41], off offset:256 sc1 nt
	s_and_saveexec_b64 s[6:7], s[0:1]
	s_cbranch_execz .LBB0_725
	s_waitcnt lgkmcnt(0)
	v_add_f32_e32 v38, v36, v37
	v_lshlrev_b64 v[36:37], 6, v[52:53]
	v_lshl_add_u64 v[36:37], s[86:87], 0, v[36:37]
	v_lshl_add_u64 v[36:37], s[4:5], 2, v[36:37]
	v_lshl_add_u64 v[36:37], v[36:37], 0, s[10:11]
	global_store_dword v[36:37], v38, off
.LBB0_725:
	s_or_b64 exec, exec, s[6:7]
	v_add_u32_e32 v36, 0xa0, v150
	s_waitcnt lgkmcnt(0)
	v_ashrrev_i32_e32 v37, 31, v36
	v_lshlrev_b64 v[38:39], 10, v[36:37]
	v_readlane_b32 s16, v244, 7
	v_lshl_add_u64 v[46:47], v[38:39], 0, v[148:149]
	v_readlane_b32 s17, v244, 8
	v_pk_mul_f32 v[34:35], v[34:35], v[146:147]
	v_pk_mul_f32 v[32:33], v[32:33], v[144:145]
	v_lshl_add_u64 v[48:49], v[46:47], 2, s[16:17]
	global_load_dwordx4 v[38:41], v[48:49], off nt
	global_load_dwordx4 v[42:45], v[48:49], off offset:16 nt
	ds_read_b32 v50, v3 offset:4736
	v_pk_mul_f32 v[30:31], v[30:31], v[142:143]
	v_pk_mul_f32 v[28:29], v[28:29], v[140:141]
	v_lshl_add_u64 v[46:47], v[46:47], 1, s[62:63]
	v_pk_mul_f32 v[26:27], v[26:27], v[138:139]
	v_pk_mul_f32 v[24:25], v[24:25], v[136:137]
	v_pk_mul_f32 v[22:23], v[22:23], v[134:135]
	v_pk_mul_f32 v[20:21], v[20:21], v[132:133]
	v_readlane_b32 s18, v244, 9
	v_readlane_b32 s19, v244, 10
	v_readlane_b32 s20, v244, 11
	v_readlane_b32 s21, v244, 12
	v_readlane_b32 s22, v244, 13
	v_readlane_b32 s23, v244, 14
	v_readlane_b32 s24, v244, 15
	v_readlane_b32 s25, v244, 16
	v_readlane_b32 s26, v244, 17
	v_readlane_b32 s27, v244, 18
	v_readlane_b32 s28, v244, 19
	v_readlane_b32 s29, v244, 20
	v_readlane_b32 s30, v244, 21
	v_readlane_b32 s31, v244, 22
	s_waitcnt vmcnt(1) lgkmcnt(0)
	v_pk_fma_f32 v[40:41], v[34:35], v[50:51], v[40:41] op_sel_hi:[1,0,1]
	v_pk_fma_f32 v[38:39], v[32:33], v[50:51], v[38:39] op_sel_hi:[1,0,1]
	s_waitcnt vmcnt(0)
	v_pk_fma_f32 v[44:45], v[30:31], v[50:51], v[44:45] op_sel_hi:[1,0,1]
	v_pk_fma_f32 v[42:43], v[28:29], v[50:51], v[42:43] op_sel_hi:[1,0,1]
	v_cvt_pk_bf16_f32 v28, v38, v39
	v_cvt_pk_bf16_f32 v29, v40, v41
	v_mul_f32_e32 v39, v39, v39
	v_cvt_pk_bf16_f32 v30, v42, v43
	v_cvt_pk_bf16_f32 v31, v44, v45
	global_store_dwordx4 v[46:47], v[28:31], off sc1 nt
	global_load_dwordx4 v[28:31], v[48:49], off offset:512 nt
	s_nop 0
	global_load_dwordx4 v[32:35], v[48:49], off offset:528 nt
	v_mul_f32_e32 v41, v41, v41
	v_mul_f32_e32 v43, v43, v43
	v_mul_f32_e32 v45, v45, v45
	v_fmac_f32_e32 v39, v38, v38
	v_fmac_f32_e32 v41, v40, v40
	v_fmac_f32_e32 v43, v42, v42
	v_fmac_f32_e32 v45, v44, v44
	v_add_f32_e32 v38, v39, v41
	v_add_f32_e32 v39, v43, v45
	v_add_f32_e32 v38, v38, v39
	s_waitcnt vmcnt(1)
	v_pk_fma_f32 v[26:27], v[26:27], v[50:51], v[30:31] op_sel_hi:[1,0,1]
	v_pk_fma_f32 v[24:25], v[24:25], v[50:51], v[28:29] op_sel_hi:[1,0,1]
	s_waitcnt vmcnt(0)
	v_pk_fma_f32 v[28:29], v[22:23], v[50:51], v[34:35] op_sel_hi:[1,0,1]
	v_pk_fma_f32 v[30:31], v[20:21], v[50:51], v[32:33] op_sel_hi:[1,0,1]
	v_mul_f32_e32 v20, v25, v25
	v_mul_f32_e32 v21, v27, v27
	v_mul_f32_e32 v22, v31, v31
	v_mul_f32_e32 v23, v29, v29
	v_fmac_f32_e32 v20, v24, v24
	v_fmac_f32_e32 v21, v26, v26
	v_fmac_f32_e32 v22, v30, v30
	v_fmac_f32_e32 v23, v28, v28
	v_add_f32_e32 v20, v20, v21
	v_add_f32_e32 v21, v22, v23
	v_add_f32_e32 v20, v20, v21
	v_add_f32_e32 v20, v38, v20
	ds_bpermute_b32 v21, v153, v20
	v_cvt_pk_bf16_f32 v22, v24, v25
	v_cvt_pk_bf16_f32 v23, v26, v27
	v_cvt_pk_bf16_f32 v24, v30, v31
	v_cvt_pk_bf16_f32 v25, v28, v29
	s_waitcnt lgkmcnt(0)
	v_add_f32_e32 v20, v20, v21
	ds_bpermute_b32 v21, v154, v20
	global_store_dwordx4 v[46:47], v[22:25], off offset:256 sc1 nt
	s_and_saveexec_b64 s[6:7], s[0:1]
	s_cbranch_execz .LBB0_727
	s_waitcnt lgkmcnt(0)
	v_add_f32_e32 v22, v20, v21
	v_lshlrev_b64 v[20:21], 6, v[36:37]
	v_lshl_add_u64 v[20:21], s[86:87], 0, v[20:21]
	v_lshl_add_u64 v[20:21], s[4:5], 2, v[20:21]
	v_lshl_add_u64 v[20:21], v[20:21], 0, s[10:11]
	global_store_dword v[20:21], v22, off
.LBB0_727:
	s_or_b64 exec, exec, s[6:7]
	v_add_u32_e32 v20, 0xb0, v150
	s_waitcnt lgkmcnt(0)
	v_ashrrev_i32_e32 v21, 31, v20
	v_lshlrev_b64 v[22:23], 10, v[20:21]
	v_readlane_b32 s16, v244, 7
	v_lshl_add_u64 v[30:31], v[22:23], 0, v[148:149]
	v_readlane_b32 s17, v244, 8
	v_pk_mul_f32 v[18:19], v[18:19], v[146:147]
	v_pk_mul_f32 v[16:17], v[16:17], v[144:145]
	v_lshl_add_u64 v[32:33], v[30:31], 2, s[16:17]
	global_load_dwordx4 v[22:25], v[32:33], off nt
	global_load_dwordx4 v[26:29], v[32:33], off offset:16 nt
	ds_read_b32 v34, v3 offset:4800
	v_pk_mul_f32 v[14:15], v[14:15], v[142:143]
	v_pk_mul_f32 v[12:13], v[12:13], v[140:141]
	v_lshl_add_u64 v[30:31], v[30:31], 1, s[62:63]
	v_pk_mul_f32 v[10:11], v[10:11], v[138:139]
	v_pk_mul_f32 v[8:9], v[8:9], v[136:137]
	v_pk_mul_f32 v[6:7], v[6:7], v[134:135]
	v_pk_mul_f32 v[4:5], v[4:5], v[132:133]
	v_readlane_b32 s18, v244, 9
	v_readlane_b32 s19, v244, 10
	v_readlane_b32 s20, v244, 11
	v_readlane_b32 s21, v244, 12
	v_readlane_b32 s22, v244, 13
	v_readlane_b32 s23, v244, 14
	v_readlane_b32 s24, v244, 15
	v_readlane_b32 s25, v244, 16
	v_readlane_b32 s26, v244, 17
	v_readlane_b32 s27, v244, 18
	v_readlane_b32 s28, v244, 19
	v_readlane_b32 s29, v244, 20
	v_readlane_b32 s30, v244, 21
	v_readlane_b32 s31, v244, 22
	s_waitcnt vmcnt(1) lgkmcnt(0)
	v_pk_fma_f32 v[24:25], v[18:19], v[34:35], v[24:25] op_sel_hi:[1,0,1]
	v_pk_fma_f32 v[22:23], v[16:17], v[34:35], v[22:23] op_sel_hi:[1,0,1]
	s_waitcnt vmcnt(0)
	v_pk_fma_f32 v[28:29], v[14:15], v[34:35], v[28:29] op_sel_hi:[1,0,1]
	v_pk_fma_f32 v[26:27], v[12:13], v[34:35], v[26:27] op_sel_hi:[1,0,1]
	v_cvt_pk_bf16_f32 v12, v22, v23
	v_cvt_pk_bf16_f32 v13, v24, v25
	v_mul_f32_e32 v3, v23, v23
	v_cvt_pk_bf16_f32 v14, v26, v27
	v_cvt_pk_bf16_f32 v15, v28, v29
	global_store_dwordx4 v[30:31], v[12:15], off sc1 nt
	global_load_dwordx4 v[12:15], v[32:33], off offset:512 nt
	s_nop 0
	global_load_dwordx4 v[16:19], v[32:33], off offset:528 nt
	v_mul_f32_e32 v23, v25, v25
	v_mul_f32_e32 v25, v27, v27
	v_mul_f32_e32 v27, v29, v29
	v_fmac_f32_e32 v3, v22, v22
	v_fmac_f32_e32 v23, v24, v24
	v_fmac_f32_e32 v25, v26, v26
	v_fmac_f32_e32 v27, v28, v28
	v_add_f32_e32 v3, v3, v23
	v_add_f32_e32 v22, v25, v27
	v_add_f32_e32 v3, v3, v22
	s_waitcnt vmcnt(1)
	v_pk_fma_f32 v[10:11], v[10:11], v[34:35], v[14:15] op_sel_hi:[1,0,1]
	v_pk_fma_f32 v[8:9], v[8:9], v[34:35], v[12:13] op_sel_hi:[1,0,1]
	s_waitcnt vmcnt(0)
	v_pk_fma_f32 v[12:13], v[6:7], v[34:35], v[18:19] op_sel_hi:[1,0,1]
	v_pk_fma_f32 v[14:15], v[4:5], v[34:35], v[16:17] op_sel_hi:[1,0,1]
	v_mul_f32_e32 v4, v9, v9
	v_mul_f32_e32 v5, v11, v11
	v_mul_f32_e32 v6, v15, v15
	v_mul_f32_e32 v7, v13, v13
	v_fmac_f32_e32 v4, v8, v8
	v_fmac_f32_e32 v5, v10, v10
	v_fmac_f32_e32 v6, v14, v14
	v_fmac_f32_e32 v7, v12, v12
	v_add_f32_e32 v4, v4, v5
	v_add_f32_e32 v5, v6, v7
	v_add_f32_e32 v4, v4, v5
	v_add_f32_e32 v3, v3, v4
	ds_bpermute_b32 v4, v153, v3
	v_cvt_pk_bf16_f32 v6, v8, v9
	v_cvt_pk_bf16_f32 v7, v10, v11
	v_cvt_pk_bf16_f32 v8, v14, v15
	v_cvt_pk_bf16_f32 v9, v12, v13
	s_waitcnt lgkmcnt(0)
	v_add_f32_e32 v3, v3, v4
	ds_bpermute_b32 v4, v154, v3
	global_store_dwordx4 v[30:31], v[6:9], off offset:256 sc1 nt
	s_and_saveexec_b64 s[6:7], s[0:1]
	s_cbranch_execz .LBB0_729
	s_waitcnt lgkmcnt(0)
	v_add_f32_e32 v3, v3, v4
	v_lshlrev_b64 v[4:5], 6, v[20:21]
	v_lshl_add_u64 v[4:5], s[86:87], 0, v[4:5]
	v_lshl_add_u64 v[4:5], s[4:5], 2, v[4:5]
	v_lshl_add_u64 v[4:5], v[4:5], 0, s[10:11]
	global_store_dword v[4:5], v3, off

.LBB0_823:
	v_lshl_add_u32 v150, s36, 8, v3
	v_ashrrev_i32_e32 v151, 31, v150
	v_lshlrev_b64 v[152:153], 13, v[150:151]
	ds_read_b32 v151, v155
	v_max_f32_e32 v124, v124, v124
	v_max_f32_e32 v124, 0, v124
	v_max_f32_e32 v125, v125, v125
	v_max_f32_e32 v126, v126, v126
	s_waitcnt lgkmcnt(0)
	v_mul_f32_e32 v124, v124, v151
	v_max_f32_e32 v125, 0, v125
	v_max_f32_e32 v126, 0, v126
	v_mul_f32_e32 v161, v124, v124
	v_max_f32_e32 v124, v129, v129
	v_mul_f32_e32 v125, v125, v151
	v_mul_f32_e32 v126, v126, v151
	v_lshl_or_b32 v148, s66, 8, v157
	v_max_f32_e32 v128, v128, v128
	v_max_f32_e32 v124, 0, v124
	v_mul_f32_e32 v129, v125, v125
	v_max_f32_e32 v125, v130, v130
	v_mul_f32_e32 v130, v126, v126
	v_max_f32_e32 v126, v131, v131
	v_max_f32_e32 v127, v127, v127
	v_ashrrev_i32_e32 v149, 31, v148
	v_max_f32_e32 v128, 0, v128
	v_mul_f32_e32 v124, v124, v151
	v_max_f32_e32 v125, 0, v125
	v_max_f32_e32 v126, 0, v126
	v_max_f32_e32 v127, 0, v127
	v_max_f32_e32 v116, v116, v116
	v_max_f32_e32 v117, v117, v117
	v_max_f32_e32 v118, v118, v118
	v_lshl_add_u64 v[162:163], s[10:11], 0, v[152:153]
	v_lshlrev_b64 v[152:153], 1, v[148:149]
	v_mul_f32_e32 v128, v128, v151
	v_mul_f32_e32 v124, v124, v124
	v_mul_f32_e32 v125, v125, v151
	v_mul_f32_e32 v126, v126, v151
	v_mul_f32_e32 v127, v127, v151
	v_max_f32_e32 v116, 0, v116
	v_max_f32_e32 v117, 0, v117
	v_max_f32_e32 v118, 0, v118
	v_lshl_add_u64 v[148:149], v[162:163], 0, v[152:153]
	v_mul_f32_e32 v128, v128, v128
	v_mul_f32_e32 v125, v125, v125
	v_mul_f32_e32 v126, v126, v126
	v_mul_f32_e32 v127, v127, v127
	v_cvt_pk_bf16_f32 v124, v128, v124
	v_mul_f32_e32 v116, v116, v151
	v_mul_f32_e32 v117, v117, v151
	v_mul_f32_e32 v118, v118, v151
	v_cvt_pk_bf16_f32 v125, v125, v126
	v_cvt_pk_bf16_f32 v126, v161, v129
	v_cvt_pk_bf16_f32 v127, v130, v127
	global_store_dwordx4 v[148:149], v[124:127], off sc1 nt
	v_max_f32_e32 v120, v120, v120
	v_max_f32_e32 v119, v119, v119
	v_mul_f32_e32 v124, v116, v116
	v_max_f32_e32 v116, v121, v121
	v_mul_f32_e32 v121, v117, v117
	v_max_f32_e32 v117, v122, v122
	v_mul_f32_e32 v122, v118, v118
	v_max_f32_e32 v118, v123, v123
	v_max_f32_e32 v116, 0, v116
	v_max_f32_e32 v117, 0, v117
	v_max_f32_e32 v118, 0, v118
	v_max_f32_e32 v120, 0, v120
	v_mul_f32_e32 v116, v116, v151
	v_mul_f32_e32 v117, v117, v151
	v_mul_f32_e32 v118, v118, v151
	v_max_f32_e32 v119, 0, v119
	v_mul_f32_e32 v120, v120, v151
	v_mul_f32_e32 v116, v116, v116
	v_mul_f32_e32 v117, v117, v117
	v_mul_f32_e32 v119, v119, v151
	v_mul_f32_e32 v118, v118, v118
	v_mul_f32_e32 v120, v120, v120
	v_mul_f32_e32 v119, v119, v119
	v_cvt_pk_bf16_f32 v116, v120, v116
	v_cvt_pk_bf16_f32 v117, v117, v118
	v_cvt_pk_bf16_f32 v118, v124, v121
	v_cvt_pk_bf16_f32 v119, v122, v119
	global_store_dwordx4 v[148:149], v[116:119], off offset:256 sc1 nt
	ds_read_b32 v118, v155 offset:64
	v_max_f32_e32 v108, v108, v108
	v_max_f32_e32 v108, 0, v108
	v_max_f32_e32 v109, v109, v109
	v_max_f32_e32 v110, v110, v110
	s_waitcnt lgkmcnt(0)
	v_mul_f32_e32 v108, v108, v118
	v_max_f32_e32 v109, 0, v109
	v_max_f32_e32 v110, 0, v110
	v_or_b32_e32 v116, 16, v150
	v_mul_f32_e32 v119, v108, v108
	v_max_f32_e32 v108, v113, v113
	v_mul_f32_e32 v109, v109, v118
	v_mul_f32_e32 v110, v110, v118
	v_ashrrev_i32_e32 v117, 31, v116
	v_max_f32_e32 v112, v112, v112
	v_max_f32_e32 v108, 0, v108
	v_mul_f32_e32 v113, v109, v109
	v_max_f32_e32 v109, v114, v114
	v_mul_f32_e32 v114, v110, v110
	v_max_f32_e32 v110, v115, v115
	v_max_f32_e32 v111, v111, v111
	v_lshlrev_b64 v[116:117], 13, v[116:117]
	v_max_f32_e32 v112, 0, v112
	v_mul_f32_e32 v108, v108, v118
	v_max_f32_e32 v109, 0, v109
	v_max_f32_e32 v110, 0, v110
	v_max_f32_e32 v111, 0, v111
	v_max_f32_e32 v100, v100, v100
	v_max_f32_e32 v101, v101, v101
	v_max_f32_e32 v102, v102, v102
	v_lshl_add_u64 v[116:117], s[10:11], 0, v[116:117]
	v_mul_f32_e32 v112, v112, v118
	v_mul_f32_e32 v108, v108, v108
	v_mul_f32_e32 v109, v109, v118
	v_mul_f32_e32 v110, v110, v118
	v_mul_f32_e32 v111, v111, v118
	v_max_f32_e32 v100, 0, v100
	v_max_f32_e32 v101, 0, v101
	v_max_f32_e32 v102, 0, v102
	v_lshl_add_u64 v[116:117], v[116:117], 0, v[152:153]
	v_mul_f32_e32 v112, v112, v112
	v_mul_f32_e32 v109, v109, v109
	v_mul_f32_e32 v110, v110, v110
	v_mul_f32_e32 v111, v111, v111
	v_cvt_pk_bf16_f32 v108, v112, v108
	v_mul_f32_e32 v100, v100, v118
	v_mul_f32_e32 v101, v101, v118
	v_mul_f32_e32 v102, v102, v118
	v_cvt_pk_bf16_f32 v109, v109, v110
	v_cvt_pk_bf16_f32 v110, v119, v113
	v_cvt_pk_bf16_f32 v111, v114, v111
	global_store_dwordx4 v[116:117], v[108:111], off sc1 nt
	v_max_f32_e32 v104, v104, v104
	v_max_f32_e32 v103, v103, v103
	v_mul_f32_e32 v108, v100, v100
	v_max_f32_e32 v100, v105, v105
	v_mul_f32_e32 v105, v101, v101
	v_max_f32_e32 v101, v106, v106
	v_mul_f32_e32 v106, v102, v102
	v_max_f32_e32 v102, v107, v107
	v_max_f32_e32 v100, 0, v100
	v_max_f32_e32 v101, 0, v101
	v_max_f32_e32 v102, 0, v102
	v_max_f32_e32 v104, 0, v104
	v_mul_f32_e32 v100, v100, v118
	v_mul_f32_e32 v101, v101, v118
	v_mul_f32_e32 v102, v102, v118
	v_max_f32_e32 v103, 0, v103
	v_mul_f32_e32 v104, v104, v118
	v_mul_f32_e32 v100, v100, v100
	v_mul_f32_e32 v101, v101, v101
	v_mul_f32_e32 v103, v103, v118
	v_mul_f32_e32 v102, v102, v102
	v_mul_f32_e32 v104, v104, v104
	v_mul_f32_e32 v103, v103, v103
	v_cvt_pk_bf16_f32 v100, v104, v100
	v_cvt_pk_bf16_f32 v101, v101, v102
	v_cvt_pk_bf16_f32 v102, v108, v105
	v_cvt_pk_bf16_f32 v103, v106, v103
	global_store_dwordx4 v[116:117], v[100:103], off offset:256 sc1 nt
	ds_read_b32 v102, v155 offset:128
	v_max_f32_e32 v92, v92, v92
	v_max_f32_e32 v92, 0, v92
	v_max_f32_e32 v93, v93, v93
	v_max_f32_e32 v94, v94, v94
	s_waitcnt lgkmcnt(0)
	v_mul_f32_e32 v92, v92, v102
	v_max_f32_e32 v93, 0, v93
	v_max_f32_e32 v94, 0, v94
	v_or_b32_e32 v100, 32, v150
	v_mul_f32_e32 v103, v92, v92
	v_max_f32_e32 v92, v97, v97
	v_mul_f32_e32 v93, v93, v102
	v_mul_f32_e32 v94, v94, v102
	v_ashrrev_i32_e32 v101, 31, v100
	v_max_f32_e32 v96, v96, v96
	v_max_f32_e32 v92, 0, v92
	v_mul_f32_e32 v97, v93, v93
	v_max_f32_e32 v93, v98, v98
	v_mul_f32_e32 v98, v94, v94
	v_max_f32_e32 v94, v99, v99
	v_max_f32_e32 v95, v95, v95
	v_lshlrev_b64 v[100:101], 13, v[100:101]
	v_max_f32_e32 v96, 0, v96
	v_mul_f32_e32 v92, v92, v102
	v_max_f32_e32 v93, 0, v93
	v_max_f32_e32 v94, 0, v94
	v_max_f32_e32 v95, 0, v95
	v_max_f32_e32 v84, v84, v84
	v_max_f32_e32 v85, v85, v85
	v_max_f32_e32 v86, v86, v86
	v_lshl_add_u64 v[100:101], s[10:11], 0, v[100:101]
	v_mul_f32_e32 v96, v96, v102
	v_mul_f32_e32 v92, v92, v92
	v_mul_f32_e32 v93, v93, v102
	v_mul_f32_e32 v94, v94, v102
	v_mul_f32_e32 v95, v95, v102
	v_max_f32_e32 v84, 0, v84
	v_max_f32_e32 v85, 0, v85
	v_max_f32_e32 v86, 0, v86
	v_lshl_add_u64 v[100:101], v[100:101], 0, v[152:153]
	v_mul_f32_e32 v96, v96, v96
	v_mul_f32_e32 v93, v93, v93
	v_mul_f32_e32 v94, v94, v94
	v_mul_f32_e32 v95, v95, v95
	v_cvt_pk_bf16_f32 v92, v96, v92
	v_mul_f32_e32 v84, v84, v102
	v_mul_f32_e32 v85, v85, v102
	v_mul_f32_e32 v86, v86, v102
	v_cvt_pk_bf16_f32 v93, v93, v94
	v_cvt_pk_bf16_f32 v94, v103, v97
	v_cvt_pk_bf16_f32 v95, v98, v95
	global_store_dwordx4 v[100:101], v[92:95], off sc1 nt
	v_max_f32_e32 v88, v88, v88
	v_max_f32_e32 v87, v87, v87
	v_mul_f32_e32 v92, v84, v84
	v_max_f32_e32 v84, v89, v89
	v_mul_f32_e32 v89, v85, v85
	v_max_f32_e32 v85, v90, v90
	v_mul_f32_e32 v90, v86, v86
	v_max_f32_e32 v86, v91, v91
	v_max_f32_e32 v84, 0, v84
	v_max_f32_e32 v85, 0, v85
	v_max_f32_e32 v86, 0, v86
	v_max_f32_e32 v88, 0, v88
	v_mul_f32_e32 v84, v84, v102
	v_mul_f32_e32 v85, v85, v102
	v_mul_f32_e32 v86, v86, v102
	v_max_f32_e32 v87, 0, v87
	v_mul_f32_e32 v88, v88, v102
	v_mul_f32_e32 v84, v84, v84
	v_mul_f32_e32 v85, v85, v85
	v_mul_f32_e32 v87, v87, v102
	v_mul_f32_e32 v86, v86, v86
	v_mul_f32_e32 v88, v88, v88
	v_mul_f32_e32 v87, v87, v87
	v_cvt_pk_bf16_f32 v84, v88, v84
	v_cvt_pk_bf16_f32 v85, v85, v86
	v_cvt_pk_bf16_f32 v86, v92, v89
	v_cvt_pk_bf16_f32 v87, v90, v87
	global_store_dwordx4 v[100:101], v[84:87], off offset:256 sc1 nt
	ds_read_b32 v86, v155 offset:192
	v_max_f32_e32 v76, v76, v76
	v_max_f32_e32 v76, 0, v76
	v_max_f32_e32 v77, v77, v77
	v_max_f32_e32 v78, v78, v78
	s_waitcnt lgkmcnt(0)
	v_mul_f32_e32 v76, v76, v86
	v_max_f32_e32 v77, 0, v77
	v_max_f32_e32 v78, 0, v78
	v_or_b32_e32 v84, 48, v150
	v_mul_f32_e32 v87, v76, v76
	v_max_f32_e32 v76, v81, v81
	v_mul_f32_e32 v77, v77, v86
	v_mul_f32_e32 v78, v78, v86
	v_ashrrev_i32_e32 v85, 31, v84
	v_max_f32_e32 v80, v80, v80
	v_max_f32_e32 v76, 0, v76
	v_mul_f32_e32 v81, v77, v77
	v_max_f32_e32 v77, v82, v82
	v_mul_f32_e32 v82, v78, v78
	v_max_f32_e32 v78, v83, v83
	v_max_f32_e32 v79, v79, v79
	v_lshlrev_b64 v[84:85], 13, v[84:85]
	v_max_f32_e32 v80, 0, v80
	v_mul_f32_e32 v76, v76, v86
	v_max_f32_e32 v77, 0, v77
	v_max_f32_e32 v78, 0, v78
	v_max_f32_e32 v79, 0, v79
	v_max_f32_e32 v68, v68, v68
	v_max_f32_e32 v69, v69, v69
	v_max_f32_e32 v70, v70, v70
	v_lshl_add_u64 v[84:85], s[10:11], 0, v[84:85]
	v_mul_f32_e32 v80, v80, v86
	v_mul_f32_e32 v76, v76, v76
	v_mul_f32_e32 v77, v77, v86
	v_mul_f32_e32 v78, v78, v86
	v_mul_f32_e32 v79, v79, v86
	v_max_f32_e32 v68, 0, v68
	v_max_f32_e32 v69, 0, v69
	v_max_f32_e32 v70, 0, v70
	v_lshl_add_u64 v[84:85], v[84:85], 0, v[152:153]
	v_mul_f32_e32 v80, v80, v80
	v_mul_f32_e32 v77, v77, v77
	v_mul_f32_e32 v78, v78, v78
	v_mul_f32_e32 v79, v79, v79
	v_cvt_pk_bf16_f32 v76, v80, v76
	v_mul_f32_e32 v68, v68, v86
	v_mul_f32_e32 v69, v69, v86
	v_mul_f32_e32 v70, v70, v86
	v_cvt_pk_bf16_f32 v77, v77, v78
	v_cvt_pk_bf16_f32 v78, v87, v81
	v_cvt_pk_bf16_f32 v79, v82, v79
	global_store_dwordx4 v[84:85], v[76:79], off sc1 nt
	v_max_f32_e32 v72, v72, v72
	v_max_f32_e32 v71, v71, v71
	v_mul_f32_e32 v76, v68, v68
	v_max_f32_e32 v68, v73, v73
	v_mul_f32_e32 v73, v69, v69
	v_max_f32_e32 v69, v74, v74
	v_mul_f32_e32 v74, v70, v70
	v_max_f32_e32 v70, v75, v75
	v_max_f32_e32 v72, 0, v72
	v_max_f32_e32 v68, 0, v68
	v_max_f32_e32 v69, 0, v69
	v_max_f32_e32 v70, 0, v70
	v_max_f32_e32 v71, 0, v71
	v_mul_f32_e32 v72, v72, v86
	v_mul_f32_e32 v68, v68, v86
	v_mul_f32_e32 v69, v69, v86
	v_mul_f32_e32 v70, v70, v86
	v_mul_f32_e32 v71, v71, v86
	v_mul_f32_e32 v72, v72, v72
	v_mul_f32_e32 v68, v68, v68
	v_mul_f32_e32 v69, v69, v69
	v_mul_f32_e32 v70, v70, v70
	v_mul_f32_e32 v71, v71, v71
	v_cvt_pk_bf16_f32 v68, v72, v68
	v_cvt_pk_bf16_f32 v69, v69, v70
	v_cvt_pk_bf16_f32 v70, v76, v73
	v_cvt_pk_bf16_f32 v71, v74, v71
	ds_read_b32 v72, v156
	v_max_f32_e32 v60, v60, v60
	v_max_f32_e32 v60, 0, v60
	v_max_f32_e32 v61, v61, v61
	v_max_f32_e32 v62, v62, v62
	s_waitcnt lgkmcnt(0)
	v_mul_f32_e32 v60, v60, v72
	v_max_f32_e32 v61, 0, v61
	v_max_f32_e32 v62, 0, v62
	global_store_dwordx4 v[84:85], v[68:71], off offset:256 sc1 nt
	v_max_f32_e32 v64, v64, v64
	v_mul_f32_e32 v61, v61, v72
	v_mul_f32_e32 v70, v60, v60
	v_max_f32_e32 v60, v65, v65
	v_mul_f32_e32 v62, v62, v72
	v_max_f32_e32 v64, 0, v64
	v_max_f32_e32 v60, 0, v60
	v_mul_f32_e32 v65, v61, v61
	v_max_f32_e32 v61, v66, v66
	v_mul_f32_e32 v66, v62, v62
	v_max_f32_e32 v62, v67, v67
	v_mul_f32_e32 v64, v64, v72
	v_mul_f32_e32 v60, v60, v72
	v_max_f32_e32 v61, 0, v61
	v_max_f32_e32 v62, 0, v62
	v_max_f32_e32 v63, v63, v63
	v_mul_f32_e32 v64, v64, v64
	v_mul_f32_e32 v60, v60, v60
	v_mul_f32_e32 v61, v61, v72
	v_mul_f32_e32 v62, v62, v72
	v_max_f32_e32 v63, 0, v63
	v_max_f32_e32 v52, v52, v52
	v_max_f32_e32 v53, v53, v53
	v_max_f32_e32 v54, v54, v54
	v_mul_f32_e32 v61, v61, v61
	v_mul_f32_e32 v63, v63, v72
	v_mul_f32_e32 v62, v62, v62
	v_cvt_pk_bf16_f32 v60, v64, v60
	v_add_co_u32_e32 v64, vcc, s60, v148
	v_max_f32_e32 v52, 0, v52
	v_max_f32_e32 v53, 0, v53
	v_max_f32_e32 v54, 0, v54
	v_mul_f32_e32 v63, v63, v63
	v_cvt_pk_bf16_f32 v61, v61, v62
	v_cvt_pk_bf16_f32 v62, v70, v65
	v_addc_co_u32_e32 v65, vcc, 0, v149, vcc
	v_mul_f32_e32 v52, v52, v72
	v_mul_f32_e32 v53, v53, v72
	v_mul_f32_e32 v54, v54, v72
	v_cvt_pk_bf16_f32 v63, v66, v63
	global_store_dwordx4 v[64:65], v[60:63], off sc1 nt
	v_max_f32_e32 v56, v56, v56
	v_max_f32_e32 v55, v55, v55
	v_mul_f32_e32 v60, v52, v52
	v_max_f32_e32 v52, v57, v57
	v_mul_f32_e32 v57, v53, v53
	v_max_f32_e32 v53, v58, v58
	v_mul_f32_e32 v58, v54, v54
	v_max_f32_e32 v54, v59, v59
	v_max_f32_e32 v56, 0, v56
	v_max_f32_e32 v52, 0, v52
	v_max_f32_e32 v53, 0, v53
	v_max_f32_e32 v54, 0, v54
	v_max_f32_e32 v55, 0, v55
	v_mul_f32_e32 v56, v56, v72
	v_mul_f32_e32 v52, v52, v72
	v_mul_f32_e32 v53, v53, v72
	v_mul_f32_e32 v54, v54, v72
	v_mul_f32_e32 v55, v55, v72
	v_mul_f32_e32 v56, v56, v56
	v_mul_f32_e32 v52, v52, v52
	v_mul_f32_e32 v53, v53, v53
	v_mul_f32_e32 v54, v54, v54
	v_mul_f32_e32 v55, v55, v55
	v_cvt_pk_bf16_f32 v52, v56, v52
	v_cvt_pk_bf16_f32 v53, v53, v54
	v_cvt_pk_bf16_f32 v54, v60, v57
	v_cvt_pk_bf16_f32 v55, v58, v55
	ds_read_b32 v56, v155 offset:576
	v_max_f32_e32 v44, v44, v44
	v_max_f32_e32 v44, 0, v44
	v_max_f32_e32 v45, v45, v45
	v_max_f32_e32 v46, v46, v46
	v_lshl_add_u64 v[68:69], v[148:149], 0, s[18:19]
	s_waitcnt lgkmcnt(0)
	v_mul_f32_e32 v44, v44, v56
	v_max_f32_e32 v45, 0, v45
	v_max_f32_e32 v46, 0, v46
	global_store_dwordx4 v[68:69], v[52:55], off offset:256 sc1 nt
	v_max_f32_e32 v48, v48, v48
	v_mul_f32_e32 v45, v45, v56
	v_mul_f32_e32 v54, v44, v44
	v_max_f32_e32 v44, v49, v49
	v_mul_f32_e32 v46, v46, v56
	v_max_f32_e32 v48, 0, v48
	v_max_f32_e32 v44, 0, v44
	v_mul_f32_e32 v49, v45, v45
	v_max_f32_e32 v45, v50, v50
	v_mul_f32_e32 v50, v46, v46
	v_max_f32_e32 v46, v51, v51
	v_mul_f32_e32 v48, v48, v56
	v_mul_f32_e32 v44, v44, v56
	v_max_f32_e32 v45, 0, v45
	v_max_f32_e32 v46, 0, v46
	v_max_f32_e32 v47, v47, v47
	v_mul_f32_e32 v48, v48, v48
	v_mul_f32_e32 v44, v44, v44
	v_mul_f32_e32 v45, v45, v56
	v_mul_f32_e32 v46, v46, v56
	v_max_f32_e32 v47, 0, v47
	v_max_f32_e32 v36, v36, v36
	v_max_f32_e32 v37, v37, v37
	v_max_f32_e32 v38, v38, v38
	v_mul_f32_e32 v45, v45, v45
	v_mul_f32_e32 v47, v47, v56
	v_mul_f32_e32 v46, v46, v46
	v_cvt_pk_bf16_f32 v44, v48, v44
	v_add_co_u32_e32 v48, vcc, s61, v148
	v_max_f32_e32 v36, 0, v36
	v_max_f32_e32 v37, 0, v37
	v_max_f32_e32 v38, 0, v38
	v_mul_f32_e32 v47, v47, v47
	v_cvt_pk_bf16_f32 v45, v45, v46
	v_cvt_pk_bf16_f32 v46, v54, v49
	v_addc_co_u32_e32 v49, vcc, 0, v149, vcc
	v_mul_f32_e32 v36, v36, v56
	v_mul_f32_e32 v37, v37, v56
	v_mul_f32_e32 v38, v38, v56
	v_cvt_pk_bf16_f32 v47, v50, v47
	global_store_dwordx4 v[48:49], v[44:47], off sc1 nt
	v_max_f32_e32 v40, v40, v40
	v_max_f32_e32 v39, v39, v39
	v_mul_f32_e32 v44, v36, v36
	v_max_f32_e32 v36, v41, v41
	v_mul_f32_e32 v41, v37, v37
	v_max_f32_e32 v37, v42, v42
	v_mul_f32_e32 v42, v38, v38
	v_max_f32_e32 v38, v43, v43
	v_max_f32_e32 v40, 0, v40
	v_max_f32_e32 v36, 0, v36
	v_max_f32_e32 v37, 0, v37
	v_max_f32_e32 v38, 0, v38
	v_max_f32_e32 v39, 0, v39
	v_mul_f32_e32 v40, v40, v56
	v_mul_f32_e32 v36, v36, v56
	v_mul_f32_e32 v37, v37, v56
	v_mul_f32_e32 v38, v38, v56
	v_mul_f32_e32 v39, v39, v56
	v_mul_f32_e32 v40, v40, v40
	v_mul_f32_e32 v36, v36, v36
	v_mul_f32_e32 v37, v37, v37
	v_mul_f32_e32 v38, v38, v38
	v_mul_f32_e32 v39, v39, v39
	v_cvt_pk_bf16_f32 v36, v40, v36
	v_cvt_pk_bf16_f32 v37, v37, v38
	v_cvt_pk_bf16_f32 v38, v44, v41
	v_cvt_pk_bf16_f32 v39, v42, v39
	ds_read_b32 v40, v155 offset:640
	v_max_f32_e32 v28, v28, v28
	v_max_f32_e32 v28, 0, v28
	v_max_f32_e32 v29, v29, v29
	v_max_f32_e32 v30, v30, v30
	v_lshl_add_u64 v[52:53], v[148:149], 0, s[20:21]
	s_waitcnt lgkmcnt(0)
	v_mul_f32_e32 v28, v28, v40
	v_max_f32_e32 v29, 0, v29
	v_max_f32_e32 v30, 0, v30
	global_store_dwordx4 v[52:53], v[36:39], off offset:256 sc1 nt
	v_max_f32_e32 v32, v32, v32
	v_mul_f32_e32 v29, v29, v40
	v_mul_f32_e32 v38, v28, v28
	v_max_f32_e32 v28, v33, v33
	v_mul_f32_e32 v30, v30, v40
	v_max_f32_e32 v32, 0, v32
	v_max_f32_e32 v28, 0, v28
	v_mul_f32_e32 v33, v29, v29
	v_max_f32_e32 v29, v34, v34
	v_mul_f32_e32 v34, v30, v30
	v_max_f32_e32 v30, v35, v35
	v_mul_f32_e32 v32, v32, v40
	v_mul_f32_e32 v28, v28, v40
	v_max_f32_e32 v29, 0, v29
	v_max_f32_e32 v30, 0, v30
	v_max_f32_e32 v31, v31, v31
	v_mul_f32_e32 v32, v32, v32
	v_mul_f32_e32 v28, v28, v28
	v_mul_f32_e32 v29, v29, v40
	v_mul_f32_e32 v30, v30, v40
	v_max_f32_e32 v31, 0, v31
	v_max_f32_e32 v20, v20, v20
	v_max_f32_e32 v21, v21, v21
	v_max_f32_e32 v22, v22, v22
	v_mul_f32_e32 v29, v29, v29
	v_mul_f32_e32 v31, v31, v40
	v_mul_f32_e32 v30, v30, v30
	v_cvt_pk_bf16_f32 v28, v32, v28
	v_add_co_u32_e32 v32, vcc, s64, v148
	v_max_f32_e32 v20, 0, v20
	v_max_f32_e32 v21, 0, v21
	v_max_f32_e32 v22, 0, v22
	v_mul_f32_e32 v31, v31, v31
	v_cvt_pk_bf16_f32 v29, v29, v30
	v_cvt_pk_bf16_f32 v30, v38, v33
	v_addc_co_u32_e32 v33, vcc, 0, v149, vcc
	v_mul_f32_e32 v20, v20, v40
	v_mul_f32_e32 v21, v21, v40
	v_mul_f32_e32 v22, v22, v40
	v_cvt_pk_bf16_f32 v31, v34, v31
	global_store_dwordx4 v[32:33], v[28:31], off sc1 nt
	v_max_f32_e32 v24, v24, v24
	v_max_f32_e32 v23, v23, v23
	v_mul_f32_e32 v28, v20, v20
	v_max_f32_e32 v20, v25, v25
	v_mul_f32_e32 v25, v21, v21
	v_max_f32_e32 v21, v26, v26
	v_mul_f32_e32 v26, v22, v22
	v_max_f32_e32 v22, v27, v27
	v_max_f32_e32 v24, 0, v24
	v_max_f32_e32 v20, 0, v20
	v_max_f32_e32 v21, 0, v21
	v_max_f32_e32 v22, 0, v22
	v_max_f32_e32 v23, 0, v23
	v_mul_f32_e32 v24, v24, v40
	v_mul_f32_e32 v20, v20, v40
	v_mul_f32_e32 v21, v21, v40
	v_mul_f32_e32 v22, v22, v40
	v_mul_f32_e32 v23, v23, v40
	v_mul_f32_e32 v24, v24, v24
	v_mul_f32_e32 v20, v20, v20
	v_mul_f32_e32 v21, v21, v21
	v_mul_f32_e32 v22, v22, v22
	v_mul_f32_e32 v23, v23, v23
	v_cvt_pk_bf16_f32 v20, v24, v20
	v_cvt_pk_bf16_f32 v21, v21, v22
	v_cvt_pk_bf16_f32 v22, v28, v25
	v_cvt_pk_bf16_f32 v23, v26, v23
	ds_read_b32 v24, v155 offset:704
	v_max_f32_e32 v12, v12, v12
	v_max_f32_e32 v12, 0, v12
	v_max_f32_e32 v13, v13, v13
	v_max_f32_e32 v14, v14, v14
	v_lshl_add_u64 v[36:37], v[148:149], 0, s[22:23]
	s_waitcnt lgkmcnt(0)
	v_mul_f32_e32 v12, v12, v24
	v_max_f32_e32 v13, 0, v13
	v_max_f32_e32 v14, 0, v14
	global_store_dwordx4 v[36:37], v[20:23], off offset:256 sc1 nt
	v_max_f32_e32 v16, v16, v16
	v_mul_f32_e32 v13, v13, v24
	v_mul_f32_e32 v22, v12, v12
	v_max_f32_e32 v12, v17, v17
	v_mul_f32_e32 v14, v14, v24
	v_max_f32_e32 v16, 0, v16
	v_max_f32_e32 v12, 0, v12
	v_mul_f32_e32 v17, v13, v13
	v_max_f32_e32 v13, v18, v18
	v_mul_f32_e32 v18, v14, v14
	v_max_f32_e32 v14, v19, v19
	v_mul_f32_e32 v16, v16, v24
	v_mul_f32_e32 v12, v12, v24
	v_max_f32_e32 v13, 0, v13
	v_max_f32_e32 v14, 0, v14
	v_max_f32_e32 v15, v15, v15
	v_mul_f32_e32 v16, v16, v16
	v_mul_f32_e32 v12, v12, v12
	v_mul_f32_e32 v13, v13, v24
	v_mul_f32_e32 v14, v14, v24
	v_max_f32_e32 v15, 0, v15
	v_max_f32_e32 v4, v4, v4
	v_max_f32_e32 v5, v5, v5
	v_max_f32_e32 v6, v6, v6
	v_mul_f32_e32 v13, v13, v13
	v_mul_f32_e32 v15, v15, v24
	v_mul_f32_e32 v14, v14, v14
	v_cvt_pk_bf16_f32 v12, v16, v12
	v_add_co_u32_e32 v16, vcc, s65, v148
	v_max_f32_e32 v4, 0, v4
	v_max_f32_e32 v5, 0, v5
	v_max_f32_e32 v6, 0, v6
	v_mul_f32_e32 v15, v15, v15
	v_cvt_pk_bf16_f32 v13, v13, v14
	v_cvt_pk_bf16_f32 v14, v22, v17
	v_addc_co_u32_e32 v17, vcc, 0, v149, vcc
	v_mul_f32_e32 v4, v4, v24
	v_mul_f32_e32 v5, v5, v24
	v_mul_f32_e32 v6, v6, v24
	v_cvt_pk_bf16_f32 v15, v18, v15
	global_store_dwordx4 v[16:17], v[12:15], off sc1 nt
	v_max_f32_e32 v7, v7, v7
	v_max_f32_e32 v8, v8, v8
	v_mul_f32_e32 v12, v4, v4
	v_max_f32_e32 v4, v9, v9
	v_mul_f32_e32 v9, v5, v5
	v_max_f32_e32 v5, v10, v10
	v_mul_f32_e32 v10, v6, v6
	v_max_f32_e32 v6, v11, v11
	v_max_f32_e32 v4, 0, v4
	v_max_f32_e32 v5, 0, v5
	v_max_f32_e32 v6, 0, v6
	v_max_f32_e32 v7, 0, v7
	v_max_f32_e32 v8, 0, v8
	v_mul_f32_e32 v4, v4, v24
	v_mul_f32_e32 v5, v5, v24
	v_mul_f32_e32 v6, v6, v24
	v_mul_f32_e32 v7, v7, v24
	v_lshl_add_u64 v[20:21], v[148:149], 0, s[24:25]
	v_mul_f32_e32 v8, v8, v24
	v_mul_f32_e32 v4, v4, v4
	v_mul_f32_e32 v5, v5, v5
	v_mul_f32_e32 v6, v6, v6
	v_mul_f32_e32 v7, v7, v7
	s_andn2_b64 vcc, exec, s[0:1]
	s_mov_b64 s[0:1], -1
	v_mul_f32_e32 v8, v8, v8
	v_cvt_pk_bf16_f32 v4, v8, v4
	v_cvt_pk_bf16_f32 v5, v5, v6
	v_cvt_pk_bf16_f32 v6, v12, v9
	v_cvt_pk_bf16_f32 v7, v10, v7
	global_store_dwordx4 v[20:21], v[4:7], off offset:256 sc1 nt
	s_cbranch_vccnz .LBB0_812
	s_andn2_b64 vcc, exec, s[8:9]
	s_cbranch_vccnz .LBB0_811
	s_barrier
	s_branch .LBB0_811

.LBB0_892:
	v_lshlrev_b32_e32 v36, 14, v173
	v_lshlrev_b32_e32 v37, 12, v140
	v_add3_u32 v36, v167, v36, v37
	s_barrier
	s_nop 4
	ds_write2st64_b32 v36, v4, v5 offset1:1
	ds_write2st64_b32 v36, v6, v7 offset0:2 offset1:3
	ds_write2st64_b32 v36, v8, v9 offset0:4 offset1:5
	ds_write2st64_b32 v36, v10, v11 offset0:6 offset1:7
	ds_write2st64_b32 v36, v12, v13 offset0:8 offset1:9
	ds_write2st64_b32 v36, v14, v15 offset0:10 offset1:11
	ds_write2st64_b32 v36, v16, v17 offset0:12 offset1:13
	ds_write2st64_b32 v36, v18, v19 offset0:14 offset1:15
	ds_write2st64_b32 v36, v20, v21 offset0:16 offset1:17
	ds_write2st64_b32 v36, v22, v23 offset0:18 offset1:19
	ds_write2st64_b32 v36, v24, v25 offset0:20 offset1:21
	ds_write2st64_b32 v36, v26, v27 offset0:22 offset1:23
	ds_write2st64_b32 v36, v28, v29 offset0:24 offset1:25
	ds_write2st64_b32 v36, v30, v31 offset0:26 offset1:27
	ds_write2st64_b32 v36, v32, v33 offset0:28 offset1:29
	ds_write2st64_b32 v36, v34, v35 offset0:30 offset1:31
	v_lshrrev_b32_e32 v5, 3, v138
	v_lshlrev_b32_e32 v4, 3, v172
	v_and_b32_e32 v5, 0xfffff0, v5
	v_and_or_b32 v4, v4, 8, v5
	v_lshl_add_u32 v34, v4, 8, v167
	s_waitcnt lgkmcnt(0)
	s_barrier
	ds_read2st64_b32 v[4:5], v34 offset1:1
	ds_read2st64_b32 v[6:7], v34 offset0:2 offset1:3
	ds_read2st64_b32 v[8:9], v34 offset0:4 offset1:5
	ds_read2st64_b32 v[10:11], v34 offset0:6 offset1:7
	ds_read2st64_b32 v[12:13], v34 offset0:64 offset1:65
	ds_read2st64_b32 v[14:15], v34 offset0:66 offset1:67
	ds_read2st64_b32 v[16:17], v34 offset0:68 offset1:69
	ds_read2st64_b32 v[18:19], v34 offset0:70 offset1:71
	ds_read2st64_b32 v[20:21], v34 offset0:128 offset1:129
	ds_read2st64_b32 v[22:23], v34 offset0:130 offset1:131
	ds_read2st64_b32 v[24:25], v34 offset0:132 offset1:133
	ds_read2st64_b32 v[26:27], v34 offset0:134 offset1:135
	ds_read2st64_b32 v[28:29], v34 offset0:192 offset1:193
	ds_read2st64_b32 v[30:31], v34 offset0:194 offset1:195
	ds_read2st64_b32 v[32:33], v34 offset0:196 offset1:197
	ds_read2st64_b32 v[34:35], v34 offset0:198 offset1:199
	s_waitcnt lgkmcnt(0)
	s_barrier
	s_getreg_b32 s6, hwreg(HW_REG_HW_ID, 0, 6)
	s_and_b32 s6, s6, 63
	s_add_i32 s7, 0, 0x23e00
	s_lshl_b32 s6, s6, 2
	s_add_i32 s6, s7, s6
	v_mov_b32_e32 v36, s6
	v_mov_b32_e32 v37, s13
	flat_load_dword v38, v[36:37] sc0 sc1
	s_waitcnt vmcnt(0)
	s_getreg_b32 s6, hwreg(HW_REG_HW_ID, 0, 6)
	s_and_b32 s6, s6, 63
	s_lshl_b32 s6, s6, 2
	s_add_i32 s7, s7, s6
	v_mov_b32_e32 v36, s7
	flat_load_dword v36, v[36:37] sc0 sc1
	s_waitcnt vmcnt(0)
	v_pk_add_f32 v[4:5], v[4:5], 0 op_sel_hi:[1,0]
	v_pk_add_f32 v[6:7], v[6:7], 0 op_sel_hi:[1,0]
	v_pk_add_f32 v[8:9], v[8:9], 0 op_sel_hi:[1,0]
	v_pk_add_f32 v[10:11], v[10:11], 0 op_sel_hi:[1,0]
	v_pk_add_f32 v[4:5], v[4:5], v[12:13]
	v_pk_add_f32 v[6:7], v[6:7], v[14:15]
	v_pk_add_f32 v[8:9], v[8:9], v[16:17]
	v_pk_add_f32 v[10:11], v[10:11], v[18:19]
	v_pk_add_f32 v[4:5], v[4:5], v[20:21]
	v_pk_add_f32 v[6:7], v[6:7], v[22:23]
	v_pk_add_f32 v[12:13], v[8:9], v[24:25]
	v_pk_add_f32 v[14:15], v[10:11], v[26:27]
	v_pk_add_f32 v[8:9], v[4:5], v[28:29]
	v_pk_add_f32 v[10:11], v[6:7], v[30:31]
	v_pk_add_f32 v[4:5], v[12:13], v[32:33]
	v_pk_add_f32 v[6:7], v[14:15], v[34:35]
	s_cmp_eq_u32 s98, 0
	s_cbranch_scc1 .Lskda_owner
	s_mul_i32 s100, s30, 0xc000
	s_lshl_b32 s101, s98, 14
	s_add_i32 s100, s100, s101
	s_add_i32 s100, s100, 0x613c000
	v_lshl_add_u32 v12, v138, 4, s100
	v_add_u32_e32 v13, 0x2000, v12
	global_store_dwordx4 v12, v[8:11], s[82:83] sc1 nt
	global_store_dwordx4 v13, v[4:7], s[82:83] sc1 nt
	s_waitcnt vmcnt(0)
	s_barrier
	v_cmp_eq_u32_e32 vcc, 0, v138
	s_and_saveexec_b64 vcc, vcc
	s_cbranch_execz .Lskda_harr
	s_lshl_b32 s100, s30, 8
	s_add_i32 s100, s100, 0xc0000
	v_mov_b32_e32 v12, s100
	v_mov_b32_e32 v13, 1
	global_atomic_add v12, v13, s[82:83]

.LBB0_970:
	s_or_b64 exec, exec, s[16:17]
	s_waitcnt vmcnt(0) lgkmcnt(0)
	s_barrier
	v_lshl_add_u64 v[164:165], v[218:219], 2, s[56:57]
	global_load_dwordx4 v[180:183], v[164:165], off
	global_load_dwordx4 v[176:179], v[164:165], off offset:16
	global_load_dwordx4 v[168:171], v[164:165], off offset:512
	s_nop 0
	global_load_dwordx4 v[164:167], v[164:165], off offset:528
	v_lshl_add_u32 v227, v215, 2, 0
	ds_read_b32 v236, v227 offset:4096
	s_waitcnt vmcnt(0)
	v_lshlrev_b32_e32 v228, 16, v208
	v_and_b32_e32 v229, 0xffff0000, v208
	v_lshlrev_b32_e32 v208, 16, v209
	v_and_b32_e32 v209, 0xffff0000, v209
	v_lshlrev_b32_e32 v230, 16, v210
	v_and_b32_e32 v231, 0xffff0000, v210
	v_lshlrev_b32_e32 v210, 16, v211
	v_and_b32_e32 v211, 0xffff0000, v211
	v_lshlrev_b32_e32 v232, 16, v204
	v_and_b32_e32 v233, 0xffff0000, v204
	v_lshlrev_b32_e32 v204, 16, v205
	v_and_b32_e32 v205, 0xffff0000, v205
	v_lshlrev_b32_e32 v234, 16, v206
	v_and_b32_e32 v235, 0xffff0000, v206
	v_lshlrev_b32_e32 v206, 16, v207
	v_and_b32_e32 v207, 0xffff0000, v207
	v_add_u32_e32 v220, s20, v215
	v_ashrrev_i32_e32 v221, 31, v220
	v_lshlrev_b64 v[238:239], 11, v[220:221]
	s_lshl_b32 s4, s12, 2
	s_mov_b32 s7, 0
	s_ashr_i32 s5, s4, 31
	v_pk_mul_f32 v[150:151], v[150:151], v[182:183]
	v_pk_mul_f32 v[148:149], v[148:149], v[180:181]
	v_pk_mul_f32 v[146:147], v[146:147], v[178:179]
	v_pk_mul_f32 v[144:145], v[144:145], v[176:177]
	v_pk_mul_f32 v[142:143], v[142:143], v[170:171]
	v_pk_mul_f32 v[140:141], v[140:141], v[168:169]
	v_pk_mul_f32 v[138:139], v[138:139], v[166:167]
	v_pk_mul_f32 v[136:137], v[136:137], v[164:165]
	s_waitcnt lgkmcnt(0)
	v_pk_fma_f32 v[148:149], v[148:149], v[236:237], v[228:229] op_sel_hi:[1,0,1]
	v_pk_fma_f32 v[150:151], v[150:151], v[236:237], v[208:209] op_sel_hi:[1,0,1]
	v_pk_fma_f32 v[144:145], v[144:145], v[236:237], v[230:231] op_sel_hi:[1,0,1]
	v_pk_fma_f32 v[146:147], v[146:147], v[236:237], v[210:211] op_sel_hi:[1,0,1]
	v_pk_fma_f32 v[140:141], v[140:141], v[236:237], v[232:233] op_sel_hi:[1,0,1]
	v_pk_fma_f32 v[142:143], v[142:143], v[236:237], v[204:205] op_sel_hi:[1,0,1]
	v_pk_fma_f32 v[204:205], v[136:137], v[236:237], v[234:235] op_sel_hi:[1,0,1]
	v_pk_fma_f32 v[206:207], v[138:139], v[236:237], v[206:207] op_sel_hi:[1,0,1]
	v_mul_f32_e32 v208, v149, v149
	v_mul_f32_e32 v209, v151, v151
	v_mul_f32_e32 v210, v145, v145
	v_mul_f32_e32 v211, v147, v147
	v_cvt_pk_bf16_f32 v136, v148, v149
	v_cvt_pk_bf16_f32 v137, v150, v151
	v_cvt_pk_bf16_f32 v138, v144, v145
	v_cvt_pk_bf16_f32 v139, v146, v147
	v_mul_f32_e32 v145, v141, v141
	v_mul_f32_e32 v147, v143, v143
	v_mul_f32_e32 v149, v205, v205
	v_mul_f32_e32 v151, v207, v207
	v_fmac_f32_e32 v208, v148, v148
	v_fmac_f32_e32 v209, v150, v150
	v_fmac_f32_e32 v210, v144, v144
	v_fmac_f32_e32 v211, v146, v146
	v_fmac_f32_e32 v145, v140, v140
	v_fmac_f32_e32 v147, v142, v142
	v_fmac_f32_e32 v149, v204, v204
	v_fmac_f32_e32 v151, v206, v206
	v_add_f32_e32 v144, v208, v209
	v_add_f32_e32 v146, v210, v211
	v_add_f32_e32 v145, v145, v147
	v_add_f32_e32 v147, v149, v151
	v_add_f32_e32 v144, v144, v146
	v_add_f32_e32 v145, v145, v147
	v_add_f32_e32 v146, v144, v145
	ds_bpermute_b32 v147, v3, v146
	v_lshl_add_u64 v[144:145], s[62:63], 0, v[238:239]
	v_lshl_add_u64 v[144:145], v[218:219], 1, v[144:145]
	global_store_dwordx4 v[144:145], v[136:139], off sc1 nt
	s_waitcnt lgkmcnt(0)
	s_nop 0
	v_add_f32_e32 v136, v146, v147
	ds_bpermute_b32 v137, v226, v136
	v_cvt_pk_bf16_f32 v138, v140, v141
	v_cvt_pk_bf16_f32 v139, v142, v143
	v_cvt_pk_bf16_f32 v140, v204, v205
	v_cvt_pk_bf16_f32 v141, v206, v207
	global_store_dwordx4 v[144:145], v[138:141], off offset:256 sc1 nt
	s_and_saveexec_b64 s[10:11], s[0:1]
	s_cbranch_execz .LBB0_972
	s_waitcnt lgkmcnt(0)
	v_add_f32_e32 v138, v136, v137
	v_lshlrev_b64 v[136:137], 6, v[220:221]
	v_lshl_add_u64 v[136:137], s[86:87], 0, v[136:137]
	v_lshl_add_u64 v[136:137], s[4:5], 2, v[136:137]
	v_lshl_add_u64 v[136:137], v[136:137], 0, s[6:7]
	global_store_dword v[136:137], v138, off
.LBB0_972:
	s_or_b64 exec, exec, s[10:11]
	ds_read_b32 v138, v227 offset:4160
	v_lshlrev_b32_e32 v142, 16, v200
	v_and_b32_e32 v143, 0xffff0000, v200
	v_lshlrev_b32_e32 v144, 16, v201
	v_and_b32_e32 v145, 0xffff0000, v201
	v_pk_mul_f32 v[130:131], v[130:131], v[182:183]
	v_pk_mul_f32 v[128:129], v[128:129], v[180:181]
	v_lshlrev_b32_e32 v146, 16, v202
	v_and_b32_e32 v147, 0xffff0000, v202
	v_lshlrev_b32_e32 v148, 16, v203
	v_and_b32_e32 v149, 0xffff0000, v203
	s_waitcnt lgkmcnt(0)
	v_pk_fma_f32 v[130:131], v[130:131], v[138:139], v[144:145] op_sel_hi:[1,0,1]
	v_pk_fma_f32 v[128:129], v[128:129], v[138:139], v[142:143] op_sel_hi:[1,0,1]
	v_pk_mul_f32 v[126:127], v[126:127], v[178:179]
	v_pk_mul_f32 v[124:125], v[124:125], v[176:177]
	v_pk_fma_f32 v[142:143], v[126:127], v[138:139], v[148:149] op_sel_hi:[1,0,1]
	v_pk_fma_f32 v[126:127], v[124:125], v[138:139], v[146:147] op_sel_hi:[1,0,1]
	v_mul_f32_e32 v124, v129, v129
	v_mul_f32_e32 v125, v131, v131
	v_fmac_f32_e32 v124, v128, v128
	v_fmac_f32_e32 v125, v130, v130
	v_add_f32_e32 v124, v124, v125
	v_mul_f32_e32 v125, v127, v127
	v_mul_f32_e32 v139, v143, v143
	v_fmac_f32_e32 v125, v126, v126
	v_fmac_f32_e32 v139, v142, v142
	v_add_f32_e32 v125, v125, v139
	v_add_f32_e32 v139, v124, v125
	v_cvt_pk_bf16_f32 v124, v128, v129
	v_cvt_pk_bf16_f32 v125, v130, v131
	v_lshlrev_b32_e32 v128, 16, v196
	v_and_b32_e32 v129, 0xffff0000, v196
	v_lshlrev_b32_e32 v130, 16, v197
	v_and_b32_e32 v131, 0xffff0000, v197
	v_pk_mul_f32 v[118:119], v[118:119], v[170:171]
	v_pk_mul_f32 v[116:117], v[116:117], v[168:169]
	v_cvt_pk_bf16_f32 v126, v126, v127
	v_cvt_pk_bf16_f32 v127, v142, v143
	v_lshlrev_b32_e32 v142, 16, v198
	v_and_b32_e32 v143, 0xffff0000, v198
	v_pk_fma_f32 v[118:119], v[118:119], v[138:139], v[130:131] op_sel_hi:[1,0,1]
	v_pk_fma_f32 v[116:117], v[116:117], v[138:139], v[128:129] op_sel_hi:[1,0,1]
	v_pk_mul_f32 v[108:109], v[108:109], v[164:165]
	v_lshlrev_b32_e32 v144, 16, v199
	v_and_b32_e32 v145, 0xffff0000, v199
	v_pk_mul_f32 v[110:111], v[110:111], v[166:167]
	v_pk_fma_f32 v[128:129], v[108:109], v[138:139], v[142:143] op_sel_hi:[1,0,1]
	v_mul_f32_e32 v108, v117, v117
	v_mul_f32_e32 v109, v119, v119
	v_pk_fma_f32 v[110:111], v[110:111], v[138:139], v[144:145] op_sel_hi:[1,0,1]
	v_fmac_f32_e32 v108, v116, v116
	v_fmac_f32_e32 v109, v118, v118
	v_add_f32_e32 v108, v108, v109
	v_mul_f32_e32 v109, v129, v129
	v_mul_f32_e32 v130, v111, v111
	v_fmac_f32_e32 v109, v128, v128
	v_fmac_f32_e32 v130, v110, v110
	v_add_f32_e32 v109, v109, v130
	v_add_f32_e32 v108, v108, v109
	v_add_f32_e32 v138, v139, v108
	ds_bpermute_b32 v139, v3, v138
	v_add3_u32 v136, s20, v215, 16
	v_ashrrev_i32_e32 v137, 31, v136
	v_lshlrev_b64 v[140:141], 11, v[136:137]
	v_lshl_add_u64 v[108:109], s[62:63], 0, v[140:141]
	v_lshl_add_u64 v[130:131], v[218:219], 1, v[108:109]
	s_waitcnt lgkmcnt(0)
	v_add_f32_e32 v108, v138, v139
	ds_bpermute_b32 v109, v226, v108
	global_store_dwordx4 v[130:131], v[124:127], off sc1 nt
	v_cvt_pk_bf16_f32 v116, v116, v117
	v_cvt_pk_bf16_f32 v117, v118, v119
	v_cvt_pk_bf16_f32 v118, v128, v129
	v_cvt_pk_bf16_f32 v119, v110, v111
	global_store_dwordx4 v[130:131], v[116:119], off offset:256 sc1 nt
	s_and_saveexec_b64 s[10:11], s[0:1]
	s_cbranch_execz .LBB0_974
	s_waitcnt lgkmcnt(0)
	v_add_f32_e32 v110, v108, v109
	v_lshlrev_b64 v[108:109], 6, v[136:137]
	v_lshl_add_u64 v[108:109], s[86:87], 0, v[108:109]
	v_lshl_add_u64 v[108:109], s[4:5], 2, v[108:109]
	v_lshl_add_u64 v[108:109], v[108:109], 0, s[6:7]
	global_store_dword v[108:109], v110, off
.LBB0_974:
	s_or_b64 exec, exec, s[10:11]
	ds_read_b32 v110, v227 offset:4224
	v_lshlrev_b32_e32 v118, 16, v192
	v_and_b32_e32 v119, 0xffff0000, v192
	v_lshlrev_b32_e32 v124, 16, v193
	v_and_b32_e32 v125, 0xffff0000, v193
	v_pk_mul_f32 v[106:107], v[106:107], v[182:183]
	v_pk_mul_f32 v[104:105], v[104:105], v[180:181]
	v_lshlrev_b32_e32 v126, 16, v194
	v_and_b32_e32 v127, 0xffff0000, v194
	v_lshlrev_b32_e32 v128, 16, v195
	v_and_b32_e32 v129, 0xffff0000, v195
	s_waitcnt lgkmcnt(0)
	v_pk_fma_f32 v[106:107], v[106:107], v[110:111], v[124:125] op_sel_hi:[1,0,1]
	v_pk_fma_f32 v[104:105], v[104:105], v[110:111], v[118:119] op_sel_hi:[1,0,1]
	v_pk_mul_f32 v[98:99], v[98:99], v[178:179]
	v_pk_mul_f32 v[96:97], v[96:97], v[176:177]
	v_pk_fma_f32 v[118:119], v[98:99], v[110:111], v[128:129] op_sel_hi:[1,0,1]
	v_pk_fma_f32 v[98:99], v[96:97], v[110:111], v[126:127] op_sel_hi:[1,0,1]
	v_mul_f32_e32 v96, v105, v105
	v_mul_f32_e32 v97, v107, v107
	v_fmac_f32_e32 v96, v104, v104
	v_fmac_f32_e32 v97, v106, v106
	v_add_f32_e32 v96, v96, v97
	v_mul_f32_e32 v97, v99, v99
	v_mul_f32_e32 v111, v119, v119
	v_fmac_f32_e32 v97, v98, v98
	v_fmac_f32_e32 v111, v118, v118
	v_add_f32_e32 v97, v97, v111
	v_add_f32_e32 v111, v96, v97
	v_cvt_pk_bf16_f32 v96, v104, v105
	v_cvt_pk_bf16_f32 v97, v106, v107
	v_lshlrev_b32_e32 v104, 16, v188
	v_and_b32_e32 v105, 0xffff0000, v188
	v_lshlrev_b32_e32 v106, 16, v189
	v_and_b32_e32 v107, 0xffff0000, v189
	v_pk_mul_f32 v[90:91], v[90:91], v[170:171]
	v_pk_mul_f32 v[88:89], v[88:89], v[168:169]
	v_cvt_pk_bf16_f32 v98, v98, v99
	v_cvt_pk_bf16_f32 v99, v118, v119
	v_lshlrev_b32_e32 v118, 16, v190
	v_and_b32_e32 v119, 0xffff0000, v190
	v_pk_fma_f32 v[90:91], v[90:91], v[110:111], v[106:107] op_sel_hi:[1,0,1]
	v_pk_fma_f32 v[88:89], v[88:89], v[110:111], v[104:105] op_sel_hi:[1,0,1]
	v_pk_mul_f32 v[84:85], v[84:85], v[164:165]
	v_lshlrev_b32_e32 v124, 16, v191
	v_and_b32_e32 v125, 0xffff0000, v191
	v_pk_mul_f32 v[86:87], v[86:87], v[166:167]
	v_pk_fma_f32 v[106:107], v[84:85], v[110:111], v[118:119] op_sel_hi:[1,0,1]
	v_mul_f32_e32 v84, v89, v89
	v_mul_f32_e32 v85, v91, v91
	v_pk_fma_f32 v[104:105], v[86:87], v[110:111], v[124:125] op_sel_hi:[1,0,1]
	v_fmac_f32_e32 v84, v88, v88
	v_fmac_f32_e32 v85, v90, v90
	v_add_f32_e32 v84, v84, v85
	v_mul_f32_e32 v85, v107, v107
	v_mul_f32_e32 v86, v105, v105
	v_fmac_f32_e32 v85, v106, v106
	v_fmac_f32_e32 v86, v104, v104
	v_add_f32_e32 v85, v85, v86
	v_add_f32_e32 v84, v84, v85
	v_add_f32_e32 v87, v111, v84
	ds_bpermute_b32 v118, v3, v87
	v_add3_u32 v108, s20, v215, 32
	v_ashrrev_i32_e32 v109, 31, v108
	v_lshlrev_b64 v[116:117], 11, v[108:109]
	v_lshl_add_u64 v[84:85], s[62:63], 0, v[116:117]
	v_lshl_add_u64 v[110:111], v[218:219], 1, v[84:85]
	s_waitcnt lgkmcnt(0)
	v_add_f32_e32 v84, v87, v118
	ds_bpermute_b32 v85, v226, v84
	global_store_dwordx4 v[110:111], v[96:99], off sc1 nt
	v_cvt_pk_bf16_f32 v86, v88, v89
	v_cvt_pk_bf16_f32 v87, v90, v91
	v_cvt_pk_bf16_f32 v88, v106, v107
	v_cvt_pk_bf16_f32 v89, v104, v105
	global_store_dwordx4 v[110:111], v[86:89], off offset:256 sc1 nt
	s_and_saveexec_b64 s[10:11], s[0:1]
	s_cbranch_execz .LBB0_976
	s_waitcnt lgkmcnt(0)
	v_add_f32_e32 v86, v84, v85
	v_lshlrev_b64 v[84:85], 6, v[108:109]
	v_lshl_add_u64 v[84:85], s[86:87], 0, v[84:85]
	v_lshl_add_u64 v[84:85], s[4:5], 2, v[84:85]
	v_lshl_add_u64 v[84:85], v[84:85], 0, s[6:7]
	global_store_dword v[84:85], v86, off
.LBB0_976:
	s_or_b64 exec, exec, s[10:11]
	ds_read_b32 v86, v227 offset:4288
	v_lshlrev_b32_e32 v90, 16, v184
	v_and_b32_e32 v91, 0xffff0000, v184
	v_lshlrev_b32_e32 v96, 16, v185
	v_and_b32_e32 v97, 0xffff0000, v185
	v_pk_mul_f32 v[82:83], v[82:83], v[182:183]
	v_pk_mul_f32 v[80:81], v[80:81], v[180:181]
	v_lshlrev_b32_e32 v98, 16, v186
	v_and_b32_e32 v99, 0xffff0000, v186
	v_lshlrev_b32_e32 v104, 16, v187
	v_and_b32_e32 v105, 0xffff0000, v187
	s_waitcnt lgkmcnt(0)
	v_pk_fma_f32 v[82:83], v[82:83], v[86:87], v[96:97] op_sel_hi:[1,0,1]
	v_pk_fma_f32 v[80:81], v[80:81], v[86:87], v[90:91] op_sel_hi:[1,0,1]
	v_pk_mul_f32 v[78:79], v[78:79], v[178:179]
	v_pk_mul_f32 v[76:77], v[76:77], v[176:177]
	v_pk_fma_f32 v[90:91], v[78:79], v[86:87], v[104:105] op_sel_hi:[1,0,1]
	v_pk_fma_f32 v[78:79], v[76:77], v[86:87], v[98:99] op_sel_hi:[1,0,1]
	v_mul_f32_e32 v76, v81, v81
	v_mul_f32_e32 v77, v83, v83
	v_fmac_f32_e32 v76, v80, v80
	v_fmac_f32_e32 v77, v82, v82
	v_add_f32_e32 v76, v76, v77
	v_mul_f32_e32 v77, v79, v79
	v_mul_f32_e32 v87, v91, v91
	v_fmac_f32_e32 v77, v78, v78
	v_fmac_f32_e32 v87, v90, v90
	v_add_f32_e32 v77, v77, v87
	v_add_f32_e32 v87, v76, v77
	v_cvt_pk_bf16_f32 v76, v80, v81
	v_cvt_pk_bf16_f32 v77, v82, v83
	v_lshlrev_b32_e32 v80, 16, v172
	v_and_b32_e32 v81, 0xffff0000, v172
	v_lshlrev_b32_e32 v82, 16, v173
	v_and_b32_e32 v83, 0xffff0000, v173
	v_pk_mul_f32 v[74:75], v[74:75], v[170:171]
	v_pk_mul_f32 v[72:73], v[72:73], v[168:169]
	v_cvt_pk_bf16_f32 v78, v78, v79
	v_cvt_pk_bf16_f32 v79, v90, v91
	v_lshlrev_b32_e32 v90, 16, v174
	v_and_b32_e32 v91, 0xffff0000, v174
	v_pk_fma_f32 v[74:75], v[74:75], v[86:87], v[82:83] op_sel_hi:[1,0,1]
	v_pk_fma_f32 v[72:73], v[72:73], v[86:87], v[80:81] op_sel_hi:[1,0,1]
	v_pk_mul_f32 v[68:69], v[68:69], v[164:165]
	v_lshlrev_b32_e32 v96, 16, v175
	v_and_b32_e32 v97, 0xffff0000, v175
	v_pk_mul_f32 v[70:71], v[70:71], v[166:167]
	v_pk_fma_f32 v[82:83], v[68:69], v[86:87], v[90:91] op_sel_hi:[1,0,1]
	v_mul_f32_e32 v68, v73, v73
	v_mul_f32_e32 v69, v75, v75
	v_pk_fma_f32 v[80:81], v[70:71], v[86:87], v[96:97] op_sel_hi:[1,0,1]
	v_fmac_f32_e32 v68, v72, v72
	v_fmac_f32_e32 v69, v74, v74
	v_add_f32_e32 v68, v68, v69
	v_mul_f32_e32 v69, v83, v83
	v_mul_f32_e32 v70, v81, v81
	v_fmac_f32_e32 v69, v82, v82
	v_fmac_f32_e32 v70, v80, v80
	v_add_f32_e32 v69, v69, v70
	v_add_f32_e32 v68, v68, v69
	v_add_f32_e32 v71, v87, v68
	ds_bpermute_b32 v90, v3, v71
	v_add3_u32 v84, s20, v215, 48
	v_ashrrev_i32_e32 v85, 31, v84
	v_lshlrev_b64 v[88:89], 11, v[84:85]
	v_lshl_add_u64 v[68:69], s[62:63], 0, v[88:89]
	v_lshl_add_u64 v[86:87], v[218:219], 1, v[68:69]
	s_waitcnt lgkmcnt(0)
	v_add_f32_e32 v68, v71, v90
	ds_bpermute_b32 v69, v226, v68
	global_store_dwordx4 v[86:87], v[76:79], off sc1 nt
	v_cvt_pk_bf16_f32 v70, v72, v73
	v_cvt_pk_bf16_f32 v71, v74, v75
	v_cvt_pk_bf16_f32 v72, v82, v83
	v_cvt_pk_bf16_f32 v73, v80, v81
	global_store_dwordx4 v[86:87], v[70:73], off offset:256 sc1 nt
	s_and_saveexec_b64 s[10:11], s[0:1]
	s_cbranch_execz .LBB0_978
	s_waitcnt lgkmcnt(0)
	v_add_f32_e32 v70, v68, v69
	v_lshlrev_b64 v[68:69], 6, v[84:85]
	v_lshl_add_u64 v[68:69], s[86:87], 0, v[68:69]
	v_lshl_add_u64 v[68:69], s[4:5], 2, v[68:69]
	v_lshl_add_u64 v[68:69], v[68:69], 0, s[6:7]
	global_store_dword v[68:69], v70, off
.LBB0_978:
	s_or_b64 exec, exec, s[10:11]
	ds_read_b32 v70, v227 offset:4608
	v_lshlrev_b32_e32 v74, 16, v160
	v_and_b32_e32 v75, 0xffff0000, v160
	v_lshlrev_b32_e32 v76, 16, v161
	v_and_b32_e32 v77, 0xffff0000, v161
	v_pk_mul_f32 v[66:67], v[66:67], v[182:183]
	v_pk_mul_f32 v[64:65], v[64:65], v[180:181]
	v_lshlrev_b32_e32 v78, 16, v162
	v_and_b32_e32 v79, 0xffff0000, v162
	v_lshlrev_b32_e32 v80, 16, v163
	v_and_b32_e32 v81, 0xffff0000, v163
	s_waitcnt lgkmcnt(0)
	v_pk_fma_f32 v[66:67], v[66:67], v[70:71], v[76:77] op_sel_hi:[1,0,1]
	v_pk_fma_f32 v[64:65], v[64:65], v[70:71], v[74:75] op_sel_hi:[1,0,1]
	v_pk_mul_f32 v[62:63], v[62:63], v[178:179]
	v_pk_mul_f32 v[60:61], v[60:61], v[176:177]
	v_pk_fma_f32 v[74:75], v[62:63], v[70:71], v[80:81] op_sel_hi:[1,0,1]
	v_pk_fma_f32 v[62:63], v[60:61], v[70:71], v[78:79] op_sel_hi:[1,0,1]
	v_mul_f32_e32 v60, v65, v65
	v_mul_f32_e32 v61, v67, v67
	v_fmac_f32_e32 v60, v64, v64
	v_fmac_f32_e32 v61, v66, v66
	v_add_f32_e32 v60, v60, v61
	v_mul_f32_e32 v61, v63, v63
	v_mul_f32_e32 v71, v75, v75
	v_fmac_f32_e32 v61, v62, v62
	v_fmac_f32_e32 v71, v74, v74
	v_add_f32_e32 v61, v61, v71
	v_add_f32_e32 v71, v60, v61
	v_cvt_pk_bf16_f32 v60, v64, v65
	v_cvt_pk_bf16_f32 v61, v66, v67
	v_lshlrev_b32_e32 v64, 16, v156
	v_and_b32_e32 v65, 0xffff0000, v156
	v_lshlrev_b32_e32 v66, 16, v157
	v_and_b32_e32 v67, 0xffff0000, v157
	v_pk_mul_f32 v[58:59], v[58:59], v[170:171]
	v_pk_mul_f32 v[56:57], v[56:57], v[168:169]
	v_cvt_pk_bf16_f32 v62, v62, v63
	v_cvt_pk_bf16_f32 v63, v74, v75
	v_lshlrev_b32_e32 v74, 16, v158
	v_and_b32_e32 v75, 0xffff0000, v158
	v_pk_fma_f32 v[58:59], v[58:59], v[70:71], v[66:67] op_sel_hi:[1,0,1]
	v_pk_fma_f32 v[56:57], v[56:57], v[70:71], v[64:65] op_sel_hi:[1,0,1]
	v_pk_mul_f32 v[52:53], v[52:53], v[164:165]
	v_lshlrev_b32_e32 v76, 16, v159
	v_and_b32_e32 v77, 0xffff0000, v159
	v_pk_mul_f32 v[54:55], v[54:55], v[166:167]
	v_pk_fma_f32 v[66:67], v[52:53], v[70:71], v[74:75] op_sel_hi:[1,0,1]
	v_mul_f32_e32 v52, v57, v57
	v_mul_f32_e32 v53, v59, v59
	v_pk_fma_f32 v[64:65], v[54:55], v[70:71], v[76:77] op_sel_hi:[1,0,1]
	v_fmac_f32_e32 v52, v56, v56
	v_fmac_f32_e32 v53, v58, v58
	v_add_f32_e32 v52, v52, v53
	v_mul_f32_e32 v53, v67, v67
	v_mul_f32_e32 v54, v65, v65
	v_fmac_f32_e32 v53, v66, v66
	v_fmac_f32_e32 v54, v64, v64
	v_add_f32_e32 v53, v53, v54
	v_add_f32_e32 v52, v52, v53
	v_add_f32_e32 v55, v71, v52
	ds_bpermute_b32 v74, v3, v55
	v_add_u32_e32 v68, 0x80, v220
	v_ashrrev_i32_e32 v69, 31, v68
	v_lshlrev_b64 v[72:73], 11, v[68:69]
	v_lshl_add_u64 v[52:53], s[62:63], 0, v[72:73]
	v_lshl_add_u64 v[70:71], v[218:219], 1, v[52:53]
	s_waitcnt lgkmcnt(0)
	v_add_f32_e32 v52, v55, v74
	ds_bpermute_b32 v53, v226, v52
	global_store_dwordx4 v[70:71], v[60:63], off sc1 nt
	v_cvt_pk_bf16_f32 v54, v56, v57
	v_cvt_pk_bf16_f32 v55, v58, v59
	v_cvt_pk_bf16_f32 v56, v66, v67
	v_cvt_pk_bf16_f32 v57, v64, v65
	global_store_dwordx4 v[70:71], v[54:57], off offset:256 sc1 nt
	s_and_saveexec_b64 s[10:11], s[0:1]
	s_cbranch_execz .LBB0_980
	s_waitcnt lgkmcnt(0)
	v_add_f32_e32 v54, v52, v53
	v_lshlrev_b64 v[52:53], 6, v[68:69]
	v_lshl_add_u64 v[52:53], s[86:87], 0, v[52:53]
	v_lshl_add_u64 v[52:53], s[4:5], 2, v[52:53]
	v_lshl_add_u64 v[52:53], v[52:53], 0, s[6:7]
	global_store_dword v[52:53], v54, off
.LBB0_980:
	s_or_b64 exec, exec, s[10:11]
	ds_read_b32 v54, v227 offset:4672
	v_lshlrev_b32_e32 v58, 16, v152
	v_and_b32_e32 v59, 0xffff0000, v152
	v_lshlrev_b32_e32 v60, 16, v153
	v_and_b32_e32 v61, 0xffff0000, v153
	v_pk_mul_f32 v[50:51], v[50:51], v[182:183]
	v_pk_mul_f32 v[48:49], v[48:49], v[180:181]
	v_lshlrev_b32_e32 v62, 16, v154
	v_and_b32_e32 v63, 0xffff0000, v154
	v_lshlrev_b32_e32 v64, 16, v155
	v_and_b32_e32 v65, 0xffff0000, v155
	s_waitcnt lgkmcnt(0)
	v_pk_fma_f32 v[50:51], v[50:51], v[54:55], v[60:61] op_sel_hi:[1,0,1]
	v_pk_fma_f32 v[48:49], v[48:49], v[54:55], v[58:59] op_sel_hi:[1,0,1]
	v_pk_mul_f32 v[46:47], v[46:47], v[178:179]
	v_pk_mul_f32 v[44:45], v[44:45], v[176:177]
	v_pk_fma_f32 v[58:59], v[46:47], v[54:55], v[64:65] op_sel_hi:[1,0,1]
	v_pk_fma_f32 v[46:47], v[44:45], v[54:55], v[62:63] op_sel_hi:[1,0,1]
	v_mul_f32_e32 v44, v49, v49
	v_mul_f32_e32 v45, v51, v51
	v_fmac_f32_e32 v44, v48, v48
	v_fmac_f32_e32 v45, v50, v50
	v_add_f32_e32 v44, v44, v45
	v_mul_f32_e32 v45, v47, v47
	v_mul_f32_e32 v55, v59, v59
	v_fmac_f32_e32 v45, v46, v46
	v_fmac_f32_e32 v55, v58, v58
	v_add_f32_e32 v45, v45, v55
	v_add_f32_e32 v55, v44, v45
	v_cvt_pk_bf16_f32 v44, v48, v49
	v_cvt_pk_bf16_f32 v45, v50, v51
	v_lshlrev_b32_e32 v48, 16, v132
	v_and_b32_e32 v49, 0xffff0000, v132
	v_lshlrev_b32_e32 v50, 16, v133
	v_and_b32_e32 v51, 0xffff0000, v133
	v_pk_mul_f32 v[42:43], v[42:43], v[170:171]
	v_pk_mul_f32 v[40:41], v[40:41], v[168:169]
	v_cvt_pk_bf16_f32 v46, v46, v47
	v_cvt_pk_bf16_f32 v47, v58, v59
	v_lshlrev_b32_e32 v58, 16, v134
	v_and_b32_e32 v59, 0xffff0000, v134
	v_pk_fma_f32 v[42:43], v[42:43], v[54:55], v[50:51] op_sel_hi:[1,0,1]
	v_pk_fma_f32 v[40:41], v[40:41], v[54:55], v[48:49] op_sel_hi:[1,0,1]
	v_pk_mul_f32 v[36:37], v[36:37], v[164:165]
	v_lshlrev_b32_e32 v60, 16, v135
	v_and_b32_e32 v61, 0xffff0000, v135
	v_pk_mul_f32 v[38:39], v[38:39], v[166:167]
	v_pk_fma_f32 v[50:51], v[36:37], v[54:55], v[58:59] op_sel_hi:[1,0,1]
	v_mul_f32_e32 v36, v41, v41
	v_mul_f32_e32 v37, v43, v43
	v_pk_fma_f32 v[48:49], v[38:39], v[54:55], v[60:61] op_sel_hi:[1,0,1]
	v_fmac_f32_e32 v36, v40, v40
	v_fmac_f32_e32 v37, v42, v42
	v_add_f32_e32 v36, v36, v37
	v_mul_f32_e32 v37, v51, v51
	v_mul_f32_e32 v38, v49, v49
	v_fmac_f32_e32 v37, v50, v50
	v_fmac_f32_e32 v38, v48, v48
	v_add_f32_e32 v37, v37, v38
	v_add_f32_e32 v36, v36, v37
	v_add_f32_e32 v39, v55, v36
	ds_bpermute_b32 v58, v3, v39
	v_add_u32_e32 v52, 0x90, v220
	v_ashrrev_i32_e32 v53, 31, v52
	v_lshlrev_b64 v[56:57], 11, v[52:53]
	v_lshl_add_u64 v[36:37], s[62:63], 0, v[56:57]
	v_lshl_add_u64 v[54:55], v[218:219], 1, v[36:37]
	s_waitcnt lgkmcnt(0)
	v_add_f32_e32 v36, v39, v58
	ds_bpermute_b32 v37, v226, v36
	global_store_dwordx4 v[54:55], v[44:47], off sc1 nt
	v_cvt_pk_bf16_f32 v38, v40, v41
	v_cvt_pk_bf16_f32 v39, v42, v43
	v_cvt_pk_bf16_f32 v40, v50, v51
	v_cvt_pk_bf16_f32 v41, v48, v49
	global_store_dwordx4 v[54:55], v[38:41], off offset:256 sc1 nt
	s_and_saveexec_b64 s[10:11], s[0:1]
	s_cbranch_execz .LBB0_982
	s_waitcnt lgkmcnt(0)
	v_add_f32_e32 v38, v36, v37
	v_lshlrev_b64 v[36:37], 6, v[52:53]
	v_lshl_add_u64 v[36:37], s[86:87], 0, v[36:37]
	v_lshl_add_u64 v[36:37], s[4:5], 2, v[36:37]
	v_lshl_add_u64 v[36:37], v[36:37], 0, s[6:7]
	global_store_dword v[36:37], v38, off
.LBB0_982:
	s_or_b64 exec, exec, s[10:11]
	ds_read_b32 v38, v227 offset:4736
	v_lshlrev_b32_e32 v42, 16, v120
	v_and_b32_e32 v43, 0xffff0000, v120
	v_lshlrev_b32_e32 v44, 16, v121
	v_and_b32_e32 v45, 0xffff0000, v121
	v_pk_mul_f32 v[34:35], v[34:35], v[182:183]
	v_pk_mul_f32 v[32:33], v[32:33], v[180:181]
	v_lshlrev_b32_e32 v46, 16, v122
	v_and_b32_e32 v47, 0xffff0000, v122
	v_lshlrev_b32_e32 v48, 16, v123
	v_and_b32_e32 v49, 0xffff0000, v123
	s_waitcnt lgkmcnt(0)
	v_pk_fma_f32 v[34:35], v[34:35], v[38:39], v[44:45] op_sel_hi:[1,0,1]
	v_pk_fma_f32 v[32:33], v[32:33], v[38:39], v[42:43] op_sel_hi:[1,0,1]
	v_pk_mul_f32 v[30:31], v[30:31], v[178:179]
	v_pk_mul_f32 v[28:29], v[28:29], v[176:177]
	v_pk_fma_f32 v[42:43], v[30:31], v[38:39], v[48:49] op_sel_hi:[1,0,1]
	v_pk_fma_f32 v[30:31], v[28:29], v[38:39], v[46:47] op_sel_hi:[1,0,1]
	v_mul_f32_e32 v28, v33, v33
	v_mul_f32_e32 v29, v35, v35
	v_fmac_f32_e32 v28, v32, v32
	v_fmac_f32_e32 v29, v34, v34
	v_add_f32_e32 v28, v28, v29
	v_mul_f32_e32 v29, v31, v31
	v_mul_f32_e32 v39, v43, v43
	v_fmac_f32_e32 v29, v30, v30
	v_fmac_f32_e32 v39, v42, v42
	v_add_f32_e32 v29, v29, v39
	v_add_f32_e32 v39, v28, v29
	v_cvt_pk_bf16_f32 v28, v32, v33
	v_cvt_pk_bf16_f32 v29, v34, v35
	v_lshlrev_b32_e32 v32, 16, v112
	v_and_b32_e32 v33, 0xffff0000, v112
	v_lshlrev_b32_e32 v34, 16, v113
	v_and_b32_e32 v35, 0xffff0000, v113
	v_pk_mul_f32 v[26:27], v[26:27], v[170:171]
	v_pk_mul_f32 v[24:25], v[24:25], v[168:169]
	v_cvt_pk_bf16_f32 v30, v30, v31
	v_cvt_pk_bf16_f32 v31, v42, v43
	v_lshlrev_b32_e32 v42, 16, v114
	v_and_b32_e32 v43, 0xffff0000, v114
	v_pk_fma_f32 v[26:27], v[26:27], v[38:39], v[34:35] op_sel_hi:[1,0,1]
	v_pk_fma_f32 v[24:25], v[24:25], v[38:39], v[32:33] op_sel_hi:[1,0,1]
	v_pk_mul_f32 v[20:21], v[20:21], v[164:165]
	v_lshlrev_b32_e32 v44, 16, v115
	v_and_b32_e32 v45, 0xffff0000, v115
	v_pk_mul_f32 v[22:23], v[22:23], v[166:167]
	v_pk_fma_f32 v[34:35], v[20:21], v[38:39], v[42:43] op_sel_hi:[1,0,1]
	v_mul_f32_e32 v20, v25, v25
	v_mul_f32_e32 v21, v27, v27
	v_pk_fma_f32 v[32:33], v[22:23], v[38:39], v[44:45] op_sel_hi:[1,0,1]
	v_fmac_f32_e32 v20, v24, v24
	v_fmac_f32_e32 v21, v26, v26
	v_add_f32_e32 v20, v20, v21
	v_mul_f32_e32 v21, v35, v35
	v_mul_f32_e32 v22, v33, v33
	v_fmac_f32_e32 v21, v34, v34
	v_fmac_f32_e32 v22, v32, v32
	v_add_f32_e32 v21, v21, v22
	v_add_f32_e32 v20, v20, v21
	v_add_f32_e32 v23, v39, v20
	ds_bpermute_b32 v42, v3, v23
	v_add_u32_e32 v36, 0xa0, v220
	v_ashrrev_i32_e32 v37, 31, v36
	v_lshlrev_b64 v[40:41], 11, v[36:37]
	v_lshl_add_u64 v[20:21], s[62:63], 0, v[40:41]
	v_lshl_add_u64 v[38:39], v[218:219], 1, v[20:21]
	s_waitcnt lgkmcnt(0)
	v_add_f32_e32 v20, v23, v42
	ds_bpermute_b32 v21, v226, v20
	global_store_dwordx4 v[38:39], v[28:31], off sc1 nt
	v_cvt_pk_bf16_f32 v22, v24, v25
	v_cvt_pk_bf16_f32 v23, v26, v27
	v_cvt_pk_bf16_f32 v24, v34, v35
	v_cvt_pk_bf16_f32 v25, v32, v33
	global_store_dwordx4 v[38:39], v[22:25], off offset:256 sc1 nt
	s_and_saveexec_b64 s[10:11], s[0:1]
	s_cbranch_execz .LBB0_984
	s_waitcnt lgkmcnt(0)
	v_add_f32_e32 v22, v20, v21
	v_lshlrev_b64 v[20:21], 6, v[36:37]
	v_lshl_add_u64 v[20:21], s[86:87], 0, v[20:21]
	v_lshl_add_u64 v[20:21], s[4:5], 2, v[20:21]
	v_lshl_add_u64 v[20:21], v[20:21], 0, s[6:7]
	global_store_dword v[20:21], v22, off
.LBB0_984:
	s_or_b64 exec, exec, s[10:11]
	ds_read_b32 v22, v227 offset:4800
	v_lshlrev_b32_e32 v26, 16, v100
	v_and_b32_e32 v27, 0xffff0000, v100
	v_lshlrev_b32_e32 v28, 16, v101
	v_and_b32_e32 v29, 0xffff0000, v101
	v_pk_mul_f32 v[18:19], v[18:19], v[182:183]
	v_pk_mul_f32 v[16:17], v[16:17], v[180:181]
	v_lshlrev_b32_e32 v30, 16, v102
	v_and_b32_e32 v31, 0xffff0000, v102
	v_lshlrev_b32_e32 v32, 16, v103
	v_and_b32_e32 v33, 0xffff0000, v103
	s_waitcnt lgkmcnt(0)
	v_pk_fma_f32 v[18:19], v[18:19], v[22:23], v[28:29] op_sel_hi:[1,0,1]
	v_pk_fma_f32 v[16:17], v[16:17], v[22:23], v[26:27] op_sel_hi:[1,0,1]
	v_pk_mul_f32 v[14:15], v[14:15], v[178:179]
	v_pk_mul_f32 v[12:13], v[12:13], v[176:177]
	v_pk_fma_f32 v[26:27], v[14:15], v[22:23], v[32:33] op_sel_hi:[1,0,1]
	v_pk_fma_f32 v[14:15], v[12:13], v[22:23], v[30:31] op_sel_hi:[1,0,1]
	v_mul_f32_e32 v12, v17, v17
	v_mul_f32_e32 v13, v19, v19
	v_fmac_f32_e32 v12, v16, v16
	v_fmac_f32_e32 v13, v18, v18
	v_add_f32_e32 v12, v12, v13
	v_mul_f32_e32 v13, v15, v15
	v_mul_f32_e32 v23, v27, v27
	v_fmac_f32_e32 v13, v14, v14
	v_fmac_f32_e32 v23, v26, v26
	v_add_f32_e32 v13, v13, v23
	v_add_f32_e32 v23, v12, v13
	v_cvt_pk_bf16_f32 v12, v16, v17
	v_cvt_pk_bf16_f32 v13, v18, v19
	v_lshlrev_b32_e32 v16, 16, v92
	v_and_b32_e32 v17, 0xffff0000, v92
	v_lshlrev_b32_e32 v18, 16, v93
	v_and_b32_e32 v19, 0xffff0000, v93
	v_pk_mul_f32 v[10:11], v[10:11], v[170:171]
	v_pk_mul_f32 v[8:9], v[8:9], v[168:169]
	v_cvt_pk_bf16_f32 v14, v14, v15
	v_cvt_pk_bf16_f32 v15, v26, v27
	v_lshlrev_b32_e32 v26, 16, v94
	v_and_b32_e32 v27, 0xffff0000, v94
	v_pk_fma_f32 v[10:11], v[10:11], v[22:23], v[18:19] op_sel_hi:[1,0,1]
	v_pk_fma_f32 v[8:9], v[8:9], v[22:23], v[16:17] op_sel_hi:[1,0,1]
	v_pk_mul_f32 v[4:5], v[4:5], v[164:165]
	v_lshlrev_b32_e32 v28, 16, v95
	v_and_b32_e32 v29, 0xffff0000, v95
	v_pk_mul_f32 v[6:7], v[6:7], v[166:167]
	v_pk_fma_f32 v[18:19], v[4:5], v[22:23], v[26:27] op_sel_hi:[1,0,1]
	v_mul_f32_e32 v4, v9, v9
	v_mul_f32_e32 v5, v11, v11
	v_pk_fma_f32 v[16:17], v[6:7], v[22:23], v[28:29] op_sel_hi:[1,0,1]
	v_fmac_f32_e32 v4, v8, v8
	v_fmac_f32_e32 v5, v10, v10
	v_add_f32_e32 v4, v4, v5
	v_mul_f32_e32 v5, v19, v19
	v_mul_f32_e32 v6, v17, v17
	v_fmac_f32_e32 v5, v18, v18
	v_fmac_f32_e32 v6, v16, v16
	v_add_f32_e32 v5, v5, v6
	v_add_f32_e32 v4, v4, v5
	v_add_f32_e32 v7, v23, v4
	ds_bpermute_b32 v3, v3, v7
	v_add_u32_e32 v20, 0xb0, v220
	v_ashrrev_i32_e32 v21, 31, v20
	v_lshlrev_b64 v[24:25], 11, v[20:21]
	v_lshl_add_u64 v[4:5], s[62:63], 0, v[24:25]
	s_waitcnt lgkmcnt(0)
	v_add_f32_e32 v3, v7, v3
	v_lshl_add_u64 v[22:23], v[218:219], 1, v[4:5]
	ds_bpermute_b32 v4, v226, v3
	global_store_dwordx4 v[22:23], v[12:15], off sc1 nt
	v_cvt_pk_bf16_f32 v6, v8, v9
	v_cvt_pk_bf16_f32 v7, v10, v11
	v_cvt_pk_bf16_f32 v8, v18, v19
	v_cvt_pk_bf16_f32 v9, v16, v17
	global_store_dwordx4 v[22:23], v[6:9], off offset:256 sc1 nt
	s_and_saveexec_b64 s[10:11], s[0:1]
	s_cbranch_execz .LBB0_986
	s_waitcnt lgkmcnt(0)
	v_add_f32_e32 v3, v3, v4
	v_lshlrev_b64 v[4:5], 6, v[20:21]
	v_lshl_add_u64 v[4:5], s[86:87], 0, v[4:5]
	v_lshl_add_u64 v[4:5], s[4:5], 2, v[4:5]
	v_lshl_add_u64 v[4:5], v[4:5], 0, s[6:7]
	global_store_dword v[4:5], v3, off

.LBB0_1134:
	s_lshl_b32 s39, s46, 8
	s_and_b32 s39, s39, 0x100
	s_cmp_eq_u32 s37, 1
	ds_read_b32 v152, v157
	s_cselect_b64 vcc, -1, 0
	v_lshl_add_u32 v148, s44, 8, v156
	v_cndmask_b32_e32 v149, 1.0, v163, vcc
	v_cndmask_b32_e64 v166, v149, v164, s[4:5]
	v_ashrrev_i32_e32 v149, 31, v148
	v_or_b32_e32 v165, s39, v159
	v_lshlrev_b64 v[150:151], 9, v[148:149]
	s_cmp_lg_u64 s[58:59], 0
	v_or_b32_e32 v150, v150, v165
	s_waitcnt lgkmcnt(0)
	v_mul_f32_e32 v154, v166, v152
	s_cselect_b64 s[44:45], -1, 0
	s_cmp_eq_u64 s[58:59], 0
	v_lshl_add_u64 v[152:153], v[150:151], 1, s[48:49]
	v_lshl_add_u64 v[150:151], v[150:151], 2, s[58:59]
	v_pk_mul_f32 v[130:131], v[130:131], v[154:155] op_sel_hi:[1,0]
	v_pk_mul_f32 v[128:129], v[128:129], v[154:155] op_sel_hi:[1,0]
	v_pk_mul_f32 v[126:127], v[126:127], v[154:155] op_sel_hi:[1,0]
	v_pk_mul_f32 v[124:125], v[124:125], v[154:155] op_sel_hi:[1,0]
	v_cvt_pk_bf16_f32 v168, v128, v129
	v_cvt_pk_bf16_f32 v169, v130, v131
	s_nop 0
	v_cvt_pk_bf16_f32 v170, v124, v125
	v_cvt_pk_bf16_f32 v171, v126, v127
	global_store_dwordx4 v[152:153], v[168:171], off sc1 nt
	s_cbranch_scc1 .LBB0_1136
	global_store_dwordx4 v[150:151], v[128:131], off nt
	global_store_dwordx4 v[150:151], v[124:127], off offset:16 nt
.LBB0_1136:
	v_mov_b32_e32 v155, v154
	s_nop 0
	v_mov_b32_e32 v124, v154
	v_mov_b32_e32 v125, v154
	v_cndmask_b32_e64 v128, 0, 1, s[44:45]
	v_pk_mul_f32 v[122:123], v[122:123], v[124:125]
	v_pk_mul_f32 v[120:121], v[120:121], v[154:155]
	v_pk_mul_f32 v[118:119], v[118:119], v[124:125]
	v_pk_mul_f32 v[116:117], v[116:117], v[154:155]
	v_cmp_ne_u32_e64 s[4:5], 1, v128
	s_andn2_b64 vcc, exec, s[44:45]
	v_cvt_pk_bf16_f32 v124, v120, v121
	v_cvt_pk_bf16_f32 v125, v122, v123
	v_cvt_pk_bf16_f32 v126, v116, v117
	v_cvt_pk_bf16_f32 v127, v118, v119
	global_store_dwordx4 v[152:153], v[124:127], off offset:256 sc1 nt
	s_cbranch_vccnz .LBB0_1138
	global_store_dwordx4 v[150:151], v[120:123], off offset:512 nt
	global_store_dwordx4 v[150:151], v[116:119], off offset:528 nt
.LBB0_1138:
	ds_read_b32 v118, v157 offset:64
	s_nop 0
	v_or_b32_e32 v116, 16, v148
	v_ashrrev_i32_e32 v117, 31, v116
	v_lshlrev_b64 v[116:117], 9, v[116:117]
	v_or_b32_e32 v116, v116, v165
	s_waitcnt lgkmcnt(0)
	v_mul_f32_e32 v120, v166, v118
	v_lshl_add_u64 v[118:119], v[116:117], 1, s[48:49]
	v_lshl_add_u64 v[116:117], v[116:117], 2, s[58:59]
	v_pk_mul_f32 v[114:115], v[114:115], v[120:121] op_sel_hi:[1,0]
	v_pk_mul_f32 v[112:113], v[112:113], v[120:121] op_sel_hi:[1,0]
	v_pk_mul_f32 v[110:111], v[110:111], v[120:121] op_sel_hi:[1,0]
	v_pk_mul_f32 v[108:109], v[108:109], v[120:121] op_sel_hi:[1,0]
	s_and_b64 vcc, exec, s[4:5]
	v_cvt_pk_bf16_f32 v122, v112, v113
	v_cvt_pk_bf16_f32 v123, v114, v115
	v_cvt_pk_bf16_f32 v124, v108, v109
	v_cvt_pk_bf16_f32 v125, v110, v111
	global_store_dwordx4 v[118:119], v[122:125], off sc1 nt
	s_cbranch_vccnz .LBB0_1140
	global_store_dwordx4 v[116:117], v[112:115], off nt
	global_store_dwordx4 v[116:117], v[108:111], off offset:16 nt
.LBB0_1140:
	v_mov_b32_e32 v121, v120
	s_nop 0
	v_mov_b32_e32 v108, v120
	v_mov_b32_e32 v109, v120
	v_pk_mul_f32 v[106:107], v[106:107], v[108:109]
	v_pk_mul_f32 v[104:105], v[104:105], v[120:121]
	v_pk_mul_f32 v[102:103], v[102:103], v[108:109]
	v_pk_mul_f32 v[100:101], v[100:101], v[120:121]
	s_and_b64 vcc, exec, s[4:5]
	v_cvt_pk_bf16_f32 v108, v104, v105
	v_cvt_pk_bf16_f32 v109, v106, v107
	v_cvt_pk_bf16_f32 v110, v100, v101
	v_cvt_pk_bf16_f32 v111, v102, v103
	global_store_dwordx4 v[118:119], v[108:111], off offset:256 sc1 nt
	s_cbranch_vccnz .LBB0_1142
	global_store_dwordx4 v[116:117], v[104:107], off offset:512 nt
	global_store_dwordx4 v[116:117], v[100:103], off offset:528 nt
.LBB0_1142:
	ds_read_b32 v102, v157 offset:128
	s_nop 0
	v_or_b32_e32 v100, 32, v148
	v_ashrrev_i32_e32 v101, 31, v100
	v_lshlrev_b64 v[100:101], 9, v[100:101]
	v_or_b32_e32 v100, v100, v165
	s_waitcnt lgkmcnt(0)
	v_mul_f32_e32 v104, v166, v102
	v_lshl_add_u64 v[102:103], v[100:101], 1, s[48:49]
	v_lshl_add_u64 v[100:101], v[100:101], 2, s[58:59]
	v_pk_mul_f32 v[98:99], v[98:99], v[104:105] op_sel_hi:[1,0]
	v_pk_mul_f32 v[96:97], v[96:97], v[104:105] op_sel_hi:[1,0]
	v_pk_mul_f32 v[94:95], v[94:95], v[104:105] op_sel_hi:[1,0]
	v_pk_mul_f32 v[92:93], v[92:93], v[104:105] op_sel_hi:[1,0]
	s_and_b64 vcc, exec, s[4:5]
	v_cvt_pk_bf16_f32 v106, v96, v97
	v_cvt_pk_bf16_f32 v107, v98, v99
	v_cvt_pk_bf16_f32 v108, v92, v93
	v_cvt_pk_bf16_f32 v109, v94, v95
	global_store_dwordx4 v[102:103], v[106:109], off sc1 nt
	s_cbranch_vccnz .LBB0_1144
	global_store_dwordx4 v[100:101], v[96:99], off nt
	global_store_dwordx4 v[100:101], v[92:95], off offset:16 nt
.LBB0_1144:
	v_mov_b32_e32 v105, v104
	s_nop 0
	v_mov_b32_e32 v92, v104
	v_mov_b32_e32 v93, v104
	v_pk_mul_f32 v[90:91], v[90:91], v[92:93]
	v_pk_mul_f32 v[88:89], v[88:89], v[104:105]
	v_pk_mul_f32 v[86:87], v[86:87], v[92:93]
	v_pk_mul_f32 v[84:85], v[84:85], v[104:105]
	s_and_b64 vcc, exec, s[4:5]
	v_cvt_pk_bf16_f32 v92, v88, v89
	v_cvt_pk_bf16_f32 v93, v90, v91
	v_cvt_pk_bf16_f32 v94, v84, v85
	v_cvt_pk_bf16_f32 v95, v86, v87
	global_store_dwordx4 v[102:103], v[92:95], off offset:256 sc1 nt
	s_cbranch_vccnz .LBB0_1146
	global_store_dwordx4 v[100:101], v[88:91], off offset:512 nt
	global_store_dwordx4 v[100:101], v[84:87], off offset:528 nt
.LBB0_1146:
	ds_read_b32 v86, v157 offset:192
	s_nop 0
	v_or_b32_e32 v84, 48, v148
	v_ashrrev_i32_e32 v85, 31, v84
	v_lshlrev_b64 v[84:85], 9, v[84:85]
	v_or_b32_e32 v84, v84, v165
	s_waitcnt lgkmcnt(0)
	v_mul_f32_e32 v88, v166, v86
	v_lshl_add_u64 v[86:87], v[84:85], 1, s[48:49]
	v_lshl_add_u64 v[84:85], v[84:85], 2, s[58:59]
	v_pk_mul_f32 v[82:83], v[82:83], v[88:89] op_sel_hi:[1,0]
	v_pk_mul_f32 v[80:81], v[80:81], v[88:89] op_sel_hi:[1,0]
	v_pk_mul_f32 v[78:79], v[78:79], v[88:89] op_sel_hi:[1,0]
	v_pk_mul_f32 v[76:77], v[76:77], v[88:89] op_sel_hi:[1,0]
	s_and_b64 vcc, exec, s[4:5]
	v_cvt_pk_bf16_f32 v90, v80, v81
	v_cvt_pk_bf16_f32 v91, v82, v83
	v_cvt_pk_bf16_f32 v92, v76, v77
	v_cvt_pk_bf16_f32 v93, v78, v79
	global_store_dwordx4 v[86:87], v[90:93], off sc1 nt
	s_cbranch_vccnz .LBB0_1148
	global_store_dwordx4 v[84:85], v[80:83], off nt
	global_store_dwordx4 v[84:85], v[76:79], off offset:16 nt
.LBB0_1148:
	v_mov_b32_e32 v89, v88
	s_nop 0
	v_mov_b32_e32 v76, v88
	v_mov_b32_e32 v77, v88
	v_pk_mul_f32 v[74:75], v[74:75], v[76:77]
	v_pk_mul_f32 v[72:73], v[72:73], v[88:89]
	v_pk_mul_f32 v[70:71], v[70:71], v[76:77]
	v_pk_mul_f32 v[68:69], v[68:69], v[88:89]
	s_and_b64 vcc, exec, s[4:5]
	v_cvt_pk_bf16_f32 v76, v72, v73
	v_cvt_pk_bf16_f32 v77, v74, v75
	v_cvt_pk_bf16_f32 v78, v68, v69
	v_cvt_pk_bf16_f32 v79, v70, v71
	global_store_dwordx4 v[86:87], v[76:79], off offset:256 sc1 nt
	s_cbranch_vccnz .LBB0_1150
	global_store_dwordx4 v[84:85], v[72:75], off offset:512 nt
	global_store_dwordx4 v[84:85], v[68:71], off offset:528 nt
.LBB0_1150:
	ds_read_b32 v72, v158
	s_nop 0
	v_lshlrev_b64 v[68:69], 9, v[148:149]
	v_or_b32_e32 v68, v68, v165
	v_lshl_add_u64 v[68:69], v[68:69], 0, s[26:27]
	v_lshl_add_u64 v[70:71], v[68:69], 1, s[48:49]
	s_waitcnt lgkmcnt(0)
	v_mul_f32_e32 v72, v166, v72
	v_lshl_add_u64 v[68:69], v[68:69], 2, s[58:59]
	v_pk_mul_f32 v[66:67], v[66:67], v[72:73] op_sel_hi:[1,0]
	v_pk_mul_f32 v[64:65], v[64:65], v[72:73] op_sel_hi:[1,0]
	v_pk_mul_f32 v[62:63], v[62:63], v[72:73] op_sel_hi:[1,0]
	v_pk_mul_f32 v[60:61], v[60:61], v[72:73] op_sel_hi:[1,0]
	s_and_b64 vcc, exec, s[4:5]
	v_cvt_pk_bf16_f32 v74, v64, v65
	v_cvt_pk_bf16_f32 v75, v66, v67
	v_cvt_pk_bf16_f32 v76, v60, v61
	v_cvt_pk_bf16_f32 v77, v62, v63
	global_store_dwordx4 v[70:71], v[74:77], off sc1 nt
	s_cbranch_vccnz .LBB0_1152
	global_store_dwordx4 v[68:69], v[64:67], off nt
	global_store_dwordx4 v[68:69], v[60:63], off offset:16 nt
.LBB0_1152:
	v_mov_b32_e32 v73, v72
	s_nop 0
	v_mov_b32_e32 v60, v72
	v_mov_b32_e32 v61, v72
	v_pk_mul_f32 v[58:59], v[58:59], v[60:61]
	v_pk_mul_f32 v[56:57], v[56:57], v[72:73]
	v_pk_mul_f32 v[54:55], v[54:55], v[60:61]
	v_pk_mul_f32 v[52:53], v[52:53], v[72:73]
	s_and_b64 vcc, exec, s[4:5]
	v_cvt_pk_bf16_f32 v60, v56, v57
	v_cvt_pk_bf16_f32 v61, v58, v59
	v_cvt_pk_bf16_f32 v62, v52, v53
	v_cvt_pk_bf16_f32 v63, v54, v55
	global_store_dwordx4 v[70:71], v[60:63], off offset:256 sc1 nt
	s_cbranch_vccnz .LBB0_1154
	global_store_dwordx4 v[68:69], v[56:59], off offset:512 nt
	global_store_dwordx4 v[68:69], v[52:55], off offset:528 nt
.LBB0_1154:
	ds_read_b32 v56, v157 offset:576
	s_nop 0
	v_lshlrev_b64 v[52:53], 9, v[148:149]
	v_or_b32_e32 v52, v52, v165
	v_lshl_add_u64 v[52:53], v[52:53], 0, s[28:29]
	v_lshl_add_u64 v[54:55], v[52:53], 1, s[48:49]
	s_waitcnt lgkmcnt(0)
	v_mul_f32_e32 v56, v166, v56
	v_lshl_add_u64 v[52:53], v[52:53], 2, s[58:59]
	v_pk_mul_f32 v[50:51], v[50:51], v[56:57] op_sel_hi:[1,0]
	v_pk_mul_f32 v[48:49], v[48:49], v[56:57] op_sel_hi:[1,0]
	v_pk_mul_f32 v[46:47], v[46:47], v[56:57] op_sel_hi:[1,0]
	v_pk_mul_f32 v[44:45], v[44:45], v[56:57] op_sel_hi:[1,0]
	s_and_b64 vcc, exec, s[4:5]
	v_cvt_pk_bf16_f32 v58, v48, v49
	v_cvt_pk_bf16_f32 v59, v50, v51
	v_cvt_pk_bf16_f32 v60, v44, v45
	v_cvt_pk_bf16_f32 v61, v46, v47
	global_store_dwordx4 v[54:55], v[58:61], off sc1 nt
	s_cbranch_vccnz .LBB0_1156
	global_store_dwordx4 v[52:53], v[48:51], off nt
	global_store_dwordx4 v[52:53], v[44:47], off offset:16 nt
.LBB0_1156:
	v_mov_b32_e32 v57, v56
	s_nop 0
	v_mov_b32_e32 v44, v56
	v_mov_b32_e32 v45, v56
	v_pk_mul_f32 v[42:43], v[42:43], v[44:45]
	v_pk_mul_f32 v[40:41], v[40:41], v[56:57]
	v_pk_mul_f32 v[38:39], v[38:39], v[44:45]
	v_pk_mul_f32 v[36:37], v[36:37], v[56:57]
	s_and_b64 vcc, exec, s[4:5]
	v_cvt_pk_bf16_f32 v44, v40, v41
	v_cvt_pk_bf16_f32 v45, v42, v43
	v_cvt_pk_bf16_f32 v46, v36, v37
	v_cvt_pk_bf16_f32 v47, v38, v39
	global_store_dwordx4 v[54:55], v[44:47], off offset:256 sc1 nt
	s_cbranch_vccnz .LBB0_1158
	global_store_dwordx4 v[52:53], v[40:43], off offset:512 nt
	global_store_dwordx4 v[52:53], v[36:39], off offset:528 nt
.LBB0_1158:
	ds_read_b32 v40, v157 offset:640
	s_nop 0
	v_lshlrev_b64 v[36:37], 9, v[148:149]
	v_or_b32_e32 v36, v36, v165
	v_lshl_add_u64 v[36:37], v[36:37], 0, s[30:31]
	v_lshl_add_u64 v[38:39], v[36:37], 1, s[48:49]
	s_waitcnt lgkmcnt(0)
	v_mul_f32_e32 v40, v166, v40
	v_lshl_add_u64 v[36:37], v[36:37], 2, s[58:59]
	v_pk_mul_f32 v[34:35], v[34:35], v[40:41] op_sel_hi:[1,0]
	v_pk_mul_f32 v[32:33], v[32:33], v[40:41] op_sel_hi:[1,0]
	v_pk_mul_f32 v[30:31], v[30:31], v[40:41] op_sel_hi:[1,0]
	v_pk_mul_f32 v[28:29], v[28:29], v[40:41] op_sel_hi:[1,0]
	s_and_b64 vcc, exec, s[4:5]
	v_cvt_pk_bf16_f32 v42, v32, v33
	v_cvt_pk_bf16_f32 v43, v34, v35
	v_cvt_pk_bf16_f32 v44, v28, v29
	v_cvt_pk_bf16_f32 v45, v30, v31
	global_store_dwordx4 v[38:39], v[42:45], off sc1 nt
	s_cbranch_vccnz .LBB0_1160
	global_store_dwordx4 v[36:37], v[32:35], off nt
	global_store_dwordx4 v[36:37], v[28:31], off offset:16 nt
.LBB0_1160:
	v_mov_b32_e32 v41, v40
	s_nop 0
	v_mov_b32_e32 v28, v40
	v_mov_b32_e32 v29, v40
	v_pk_mul_f32 v[26:27], v[26:27], v[28:29]
	v_pk_mul_f32 v[24:25], v[24:25], v[40:41]
	v_pk_mul_f32 v[22:23], v[22:23], v[28:29]
	v_pk_mul_f32 v[20:21], v[20:21], v[40:41]
	s_and_b64 vcc, exec, s[4:5]
	v_cvt_pk_bf16_f32 v28, v24, v25
	v_cvt_pk_bf16_f32 v29, v26, v27
	v_cvt_pk_bf16_f32 v30, v20, v21
	v_cvt_pk_bf16_f32 v31, v22, v23
	global_store_dwordx4 v[38:39], v[28:31], off offset:256 sc1 nt
	s_cbranch_vccnz .LBB0_1162
	global_store_dwordx4 v[36:37], v[24:27], off offset:512 nt
	global_store_dwordx4 v[36:37], v[20:23], off offset:528 nt
.LBB0_1162:
	ds_read_b32 v24, v157 offset:704
	s_nop 0
	v_lshlrev_b64 v[20:21], 9, v[148:149]
	v_or_b32_e32 v20, v20, v165
	v_lshl_add_u64 v[20:21], v[20:21], 0, s[34:35]
	v_lshl_add_u64 v[22:23], v[20:21], 1, s[48:49]
	s_waitcnt lgkmcnt(0)
	v_mul_f32_e32 v24, v166, v24
	v_lshl_add_u64 v[20:21], v[20:21], 2, s[58:59]
	v_pk_mul_f32 v[18:19], v[18:19], v[24:25] op_sel_hi:[1,0]
	v_pk_mul_f32 v[16:17], v[16:17], v[24:25] op_sel_hi:[1,0]
	v_pk_mul_f32 v[14:15], v[14:15], v[24:25] op_sel_hi:[1,0]
	v_pk_mul_f32 v[12:13], v[12:13], v[24:25] op_sel_hi:[1,0]
	s_and_b64 vcc, exec, s[4:5]
	v_cvt_pk_bf16_f32 v26, v16, v17
	v_cvt_pk_bf16_f32 v27, v18, v19
	v_cvt_pk_bf16_f32 v28, v12, v13
	v_cvt_pk_bf16_f32 v29, v14, v15
	global_store_dwordx4 v[22:23], v[26:29], off sc1 nt
	s_cbranch_vccnz .LBB0_1164
	global_store_dwordx4 v[20:21], v[16:19], off nt
	global_store_dwordx4 v[20:21], v[12:15], off offset:16 nt
.LBB0_1164:
	v_mov_b32_e32 v25, v24
	s_nop 0
	v_mov_b32_e32 v12, v24
	v_mov_b32_e32 v13, v24
	v_pk_mul_f32 v[10:11], v[10:11], v[12:13]
	v_pk_mul_f32 v[8:9], v[8:9], v[24:25]
	v_pk_mul_f32 v[6:7], v[6:7], v[12:13]
	v_pk_mul_f32 v[4:5], v[4:5], v[24:25]
	s_and_b64 vcc, exec, s[4:5]
	v_cvt_pk_bf16_f32 v12, v8, v9
	v_cvt_pk_bf16_f32 v13, v10, v11
	v_cvt_pk_bf16_f32 v14, v4, v5
	v_cvt_pk_bf16_f32 v15, v6, v7
	global_store_dwordx4 v[22:23], v[12:15], off offset:256 sc1 nt
	s_cbranch_vccnz .LBB0_1166
	global_store_dwordx4 v[20:21], v[8:11], off offset:512 nt
	global_store_dwordx4 v[20:21], v[4:7], off offset:528 nt

.LBB0_1646:
	s_or_b64 exec, exec, s[12:13]
	v_lshl_add_u64 v[162:163], v[210:211], 2, s[52:53]
	s_mov_b64 s[4:5], 0x1000
	v_lshl_add_u64 v[164:165], v[162:163], 0, s[4:5]
	v_add_co_u32_e32 v162, vcc, 0x1000, v162
	s_waitcnt vmcnt(0) lgkmcnt(0)
	s_barrier
	s_nop 0
	v_addc_co_u32_e32 v163, vcc, 0, v163, vcc
	global_load_dwordx4 v[174:177], v[164:165], off offset:16
	global_load_dwordx4 v[166:169], v[164:165], off offset:512
	global_load_dwordx4 v[178:181], v[162:163], off
	s_nop 0
	global_load_dwordx4 v[162:165], v[164:165], off offset:528
	v_lshl_add_u32 v225, v216, 2, 0
	ds_read_b32 v234, v225 offset:4096
	s_waitcnt vmcnt(0)
	v_lshlrev_b32_e32 v226, 16, v206
	v_and_b32_e32 v227, 0xffff0000, v206
	v_lshlrev_b32_e32 v206, 16, v207
	v_and_b32_e32 v207, 0xffff0000, v207
	v_lshlrev_b32_e32 v228, 16, v208
	v_and_b32_e32 v229, 0xffff0000, v208
	v_lshlrev_b32_e32 v208, 16, v209
	v_and_b32_e32 v209, 0xffff0000, v209
	v_lshlrev_b32_e32 v230, 16, v202
	v_and_b32_e32 v231, 0xffff0000, v202
	v_lshlrev_b32_e32 v202, 16, v203
	v_and_b32_e32 v203, 0xffff0000, v203
	v_lshlrev_b32_e32 v232, 16, v204
	v_and_b32_e32 v233, 0xffff0000, v204
	v_lshlrev_b32_e32 v204, 16, v205
	v_and_b32_e32 v205, 0xffff0000, v205
	v_add_u32_e32 v214, s20, v216
	v_ashrrev_i32_e32 v215, 31, v214
	v_lshlrev_b64 v[236:237], 11, v[214:215]
	s_lshl_b32 s4, s6, 2
	s_mov_b32 s11, 0
	s_ashr_i32 s5, s4, 31
	v_pk_mul_f32 v[128:129], v[128:129], v[176:177]
	v_pk_mul_f32 v[126:127], v[126:127], v[174:175]
	v_pk_mul_f32 v[120:121], v[120:121], v[168:169]
	v_pk_mul_f32 v[118:119], v[118:119], v[166:167]
	v_pk_mul_f32 v[124:125], v[124:125], v[180:181]
	v_pk_mul_f32 v[122:123], v[122:123], v[178:179]
	v_pk_mul_f32 v[116:117], v[116:117], v[164:165]
	v_pk_mul_f32 v[114:115], v[114:115], v[162:163]
	s_waitcnt lgkmcnt(0)
	v_pk_fma_f32 v[126:127], v[126:127], v[234:235], v[228:229] op_sel_hi:[1,0,1]
	v_pk_fma_f32 v[128:129], v[128:129], v[234:235], v[208:209] op_sel_hi:[1,0,1]
	v_pk_fma_f32 v[118:119], v[118:119], v[234:235], v[230:231] op_sel_hi:[1,0,1]
	v_pk_fma_f32 v[120:121], v[120:121], v[234:235], v[202:203] op_sel_hi:[1,0,1]
	v_pk_fma_f32 v[124:125], v[124:125], v[234:235], v[206:207] op_sel_hi:[1,0,1]
	v_pk_fma_f32 v[122:123], v[122:123], v[234:235], v[226:227] op_sel_hi:[1,0,1]
	v_pk_fma_f32 v[202:203], v[114:115], v[234:235], v[232:233] op_sel_hi:[1,0,1]
	v_pk_fma_f32 v[204:205], v[116:117], v[234:235], v[204:205] op_sel_hi:[1,0,1]
	v_mul_f32_e32 v206, v127, v127
	v_mul_f32_e32 v207, v129, v129
	v_mul_f32_e32 v208, v119, v119
	v_mul_f32_e32 v209, v121, v121
	v_mul_f32_e32 v226, v123, v123
	v_mul_f32_e32 v227, v125, v125
	v_cvt_pk_bf16_f32 v114, v122, v123
	v_cvt_pk_bf16_f32 v115, v124, v125
	v_mul_f32_e32 v123, v203, v203
	v_mul_f32_e32 v125, v205, v205
	v_fmac_f32_e32 v206, v126, v126
	v_fmac_f32_e32 v207, v128, v128
	v_fmac_f32_e32 v208, v118, v118
	v_fmac_f32_e32 v209, v120, v120
	v_fmac_f32_e32 v226, v122, v122
	v_fmac_f32_e32 v227, v124, v124
	v_fmac_f32_e32 v123, v202, v202
	v_fmac_f32_e32 v125, v204, v204
	v_cvt_pk_bf16_f32 v116, v126, v127
	v_add_f32_e32 v122, v206, v207
	v_add_f32_e32 v124, v208, v209
	v_add_f32_e32 v126, v226, v227
	v_add_f32_e32 v123, v123, v125
	v_add_f32_e32 v122, v126, v122
	v_add_f32_e32 v123, v124, v123
	v_add_f32_e32 v124, v122, v123
	ds_bpermute_b32 v125, v220, v124
	v_lshl_add_u64 v[122:123], s[62:63], 0, v[236:237]
	v_lshl_add_u64 v[122:123], v[210:211], 1, v[122:123]
	v_cvt_pk_bf16_f32 v117, v128, v129
	global_store_dwordx4 v[122:123], v[114:117], off sc1 nt
	s_waitcnt lgkmcnt(0)
	s_nop 0
	v_add_f32_e32 v114, v124, v125
	ds_bpermute_b32 v115, v221, v114
	v_cvt_pk_bf16_f32 v116, v118, v119
	v_cvt_pk_bf16_f32 v117, v120, v121
	v_cvt_pk_bf16_f32 v118, v202, v203
	v_cvt_pk_bf16_f32 v119, v204, v205
	global_store_dwordx4 v[122:123], v[116:119], off offset:256 sc1 nt
	s_and_saveexec_b64 s[6:7], s[0:1]
	s_cbranch_execz .LBB0_1648
	s_waitcnt lgkmcnt(0)
	v_add_f32_e32 v116, v114, v115
	v_lshlrev_b64 v[114:115], 6, v[214:215]
	v_lshl_add_u64 v[114:115], s[86:87], 0, v[114:115]
	v_lshl_add_u64 v[114:115], s[4:5], 2, v[114:115]
	v_lshl_add_u64 v[114:115], v[114:115], 0, s[10:11]
	global_store_dword v[114:115], v116, off
.LBB0_1648:
	s_or_b64 exec, exec, s[6:7]
	ds_read_b32 v116, v225 offset:4160
	v_lshlrev_b32_e32 v120, 16, v198
	v_and_b32_e32 v121, 0xffff0000, v198
	v_lshlrev_b32_e32 v122, 16, v199
	v_and_b32_e32 v123, 0xffff0000, v199
	v_pk_mul_f32 v[112:113], v[112:113], v[180:181]
	v_pk_mul_f32 v[110:111], v[110:111], v[178:179]
	v_lshlrev_b32_e32 v124, 16, v200
	v_and_b32_e32 v125, 0xffff0000, v200
	v_lshlrev_b32_e32 v126, 16, v201
	v_and_b32_e32 v127, 0xffff0000, v201
	s_waitcnt lgkmcnt(0)
	v_pk_fma_f32 v[112:113], v[112:113], v[116:117], v[122:123] op_sel_hi:[1,0,1]
	v_pk_fma_f32 v[110:111], v[110:111], v[116:117], v[120:121] op_sel_hi:[1,0,1]
	v_pk_mul_f32 v[108:109], v[108:109], v[176:177]
	v_pk_mul_f32 v[106:107], v[106:107], v[174:175]
	v_pk_fma_f32 v[120:121], v[108:109], v[116:117], v[126:127] op_sel_hi:[1,0,1]
	v_pk_fma_f32 v[108:109], v[106:107], v[116:117], v[124:125] op_sel_hi:[1,0,1]
	v_mul_f32_e32 v106, v111, v111
	v_mul_f32_e32 v107, v113, v113
	v_fmac_f32_e32 v106, v110, v110
	v_fmac_f32_e32 v107, v112, v112
	v_add_f32_e32 v106, v106, v107
	v_mul_f32_e32 v107, v109, v109
	v_mul_f32_e32 v117, v121, v121
	v_fmac_f32_e32 v107, v108, v108
	v_fmac_f32_e32 v117, v120, v120
	v_add_f32_e32 v107, v107, v117
	v_add_f32_e32 v117, v106, v107
	v_cvt_pk_bf16_f32 v106, v110, v111
	v_cvt_pk_bf16_f32 v107, v112, v113
	v_lshlrev_b32_e32 v110, 16, v194
	v_and_b32_e32 v111, 0xffff0000, v194
	v_lshlrev_b32_e32 v112, 16, v195
	v_and_b32_e32 v113, 0xffff0000, v195
	v_pk_mul_f32 v[104:105], v[104:105], v[168:169]
	v_pk_mul_f32 v[102:103], v[102:103], v[166:167]
	v_cvt_pk_bf16_f32 v108, v108, v109
	v_cvt_pk_bf16_f32 v109, v120, v121
	v_lshlrev_b32_e32 v120, 16, v196
	v_and_b32_e32 v121, 0xffff0000, v196
	v_pk_fma_f32 v[104:105], v[104:105], v[116:117], v[112:113] op_sel_hi:[1,0,1]
	v_pk_fma_f32 v[102:103], v[102:103], v[116:117], v[110:111] op_sel_hi:[1,0,1]
	v_pk_mul_f32 v[98:99], v[98:99], v[162:163]
	v_lshlrev_b32_e32 v122, 16, v197
	v_and_b32_e32 v123, 0xffff0000, v197
	v_pk_mul_f32 v[100:101], v[100:101], v[164:165]
	v_pk_fma_f32 v[112:113], v[98:99], v[116:117], v[120:121] op_sel_hi:[1,0,1]
	v_mul_f32_e32 v98, v103, v103
	v_mul_f32_e32 v99, v105, v105
	v_pk_fma_f32 v[110:111], v[100:101], v[116:117], v[122:123] op_sel_hi:[1,0,1]
	v_fmac_f32_e32 v98, v102, v102
	v_fmac_f32_e32 v99, v104, v104
	v_add_f32_e32 v98, v98, v99
	v_mul_f32_e32 v99, v113, v113
	v_mul_f32_e32 v100, v111, v111
	v_fmac_f32_e32 v99, v112, v112
	v_fmac_f32_e32 v100, v110, v110
	v_add_f32_e32 v99, v99, v100
	v_add_f32_e32 v98, v98, v99
	v_add_f32_e32 v101, v117, v98
	ds_bpermute_b32 v120, v220, v101
	v_add3_u32 v114, s20, v216, 16
	v_ashrrev_i32_e32 v115, 31, v114
	v_lshlrev_b64 v[118:119], 11, v[114:115]
	v_lshl_add_u64 v[98:99], s[62:63], 0, v[118:119]
	v_lshl_add_u64 v[116:117], v[210:211], 1, v[98:99]
	s_waitcnt lgkmcnt(0)
	v_add_f32_e32 v98, v101, v120
	ds_bpermute_b32 v99, v221, v98
	global_store_dwordx4 v[116:117], v[106:109], off sc1 nt
	v_cvt_pk_bf16_f32 v100, v102, v103
	v_cvt_pk_bf16_f32 v101, v104, v105
	v_cvt_pk_bf16_f32 v102, v112, v113
	v_cvt_pk_bf16_f32 v103, v110, v111
	global_store_dwordx4 v[116:117], v[100:103], off offset:256 sc1 nt
	s_and_saveexec_b64 s[6:7], s[0:1]
	s_cbranch_execz .LBB0_1650
	s_waitcnt lgkmcnt(0)
	v_add_f32_e32 v100, v98, v99
	v_lshlrev_b64 v[98:99], 6, v[114:115]
	v_lshl_add_u64 v[98:99], s[86:87], 0, v[98:99]
	v_lshl_add_u64 v[98:99], s[4:5], 2, v[98:99]
	v_lshl_add_u64 v[98:99], v[98:99], 0, s[10:11]
	global_store_dword v[98:99], v100, off
.LBB0_1650:
	s_or_b64 exec, exec, s[6:7]
	ds_read_b32 v100, v225 offset:4224
	v_lshlrev_b32_e32 v104, 16, v190
	v_and_b32_e32 v105, 0xffff0000, v190
	v_lshlrev_b32_e32 v106, 16, v191
	v_and_b32_e32 v107, 0xffff0000, v191
	v_pk_mul_f32 v[96:97], v[96:97], v[180:181]
	v_pk_mul_f32 v[94:95], v[94:95], v[178:179]
	v_lshlrev_b32_e32 v108, 16, v192
	v_and_b32_e32 v109, 0xffff0000, v192
	v_lshlrev_b32_e32 v110, 16, v193
	v_and_b32_e32 v111, 0xffff0000, v193
	s_waitcnt lgkmcnt(0)
	v_pk_fma_f32 v[96:97], v[96:97], v[100:101], v[106:107] op_sel_hi:[1,0,1]
	v_pk_fma_f32 v[94:95], v[94:95], v[100:101], v[104:105] op_sel_hi:[1,0,1]
	v_pk_mul_f32 v[92:93], v[92:93], v[176:177]
	v_pk_mul_f32 v[90:91], v[90:91], v[174:175]
	v_pk_fma_f32 v[104:105], v[92:93], v[100:101], v[110:111] op_sel_hi:[1,0,1]
	v_pk_fma_f32 v[92:93], v[90:91], v[100:101], v[108:109] op_sel_hi:[1,0,1]
	v_mul_f32_e32 v90, v95, v95
	v_mul_f32_e32 v91, v97, v97
	v_fmac_f32_e32 v90, v94, v94
	v_fmac_f32_e32 v91, v96, v96
	v_add_f32_e32 v90, v90, v91
	v_mul_f32_e32 v91, v93, v93
	v_mul_f32_e32 v101, v105, v105
	v_fmac_f32_e32 v91, v92, v92
	v_fmac_f32_e32 v101, v104, v104
	v_add_f32_e32 v91, v91, v101
	v_add_f32_e32 v101, v90, v91
	v_cvt_pk_bf16_f32 v90, v94, v95
	v_cvt_pk_bf16_f32 v91, v96, v97
	v_lshlrev_b32_e32 v94, 16, v186
	v_and_b32_e32 v95, 0xffff0000, v186
	v_lshlrev_b32_e32 v96, 16, v187
	v_and_b32_e32 v97, 0xffff0000, v187
	v_pk_mul_f32 v[88:89], v[88:89], v[168:169]
	v_pk_mul_f32 v[86:87], v[86:87], v[166:167]
	v_cvt_pk_bf16_f32 v92, v92, v93
	v_cvt_pk_bf16_f32 v93, v104, v105
	v_lshlrev_b32_e32 v104, 16, v188
	v_and_b32_e32 v105, 0xffff0000, v188
	v_pk_fma_f32 v[88:89], v[88:89], v[100:101], v[96:97] op_sel_hi:[1,0,1]
	v_pk_fma_f32 v[86:87], v[86:87], v[100:101], v[94:95] op_sel_hi:[1,0,1]
	v_pk_mul_f32 v[82:83], v[82:83], v[162:163]
	v_lshlrev_b32_e32 v106, 16, v189
	v_and_b32_e32 v107, 0xffff0000, v189
	v_pk_mul_f32 v[84:85], v[84:85], v[164:165]
	v_pk_fma_f32 v[96:97], v[82:83], v[100:101], v[104:105] op_sel_hi:[1,0,1]
	v_mul_f32_e32 v82, v87, v87
	v_mul_f32_e32 v83, v89, v89
	v_pk_fma_f32 v[94:95], v[84:85], v[100:101], v[106:107] op_sel_hi:[1,0,1]
	v_fmac_f32_e32 v82, v86, v86
	v_fmac_f32_e32 v83, v88, v88
	v_add_f32_e32 v82, v82, v83
	v_mul_f32_e32 v83, v97, v97
	v_mul_f32_e32 v84, v95, v95
	v_fmac_f32_e32 v83, v96, v96
	v_fmac_f32_e32 v84, v94, v94
	v_add_f32_e32 v83, v83, v84
	v_add_f32_e32 v82, v82, v83
	v_add_f32_e32 v85, v101, v82
	ds_bpermute_b32 v104, v220, v85
	v_add3_u32 v98, s20, v216, 32
	v_ashrrev_i32_e32 v99, 31, v98
	v_lshlrev_b64 v[102:103], 11, v[98:99]
	v_lshl_add_u64 v[82:83], s[62:63], 0, v[102:103]
	v_lshl_add_u64 v[100:101], v[210:211], 1, v[82:83]
	s_waitcnt lgkmcnt(0)
	v_add_f32_e32 v82, v85, v104
	ds_bpermute_b32 v83, v221, v82
	global_store_dwordx4 v[100:101], v[90:93], off sc1 nt
	v_cvt_pk_bf16_f32 v84, v86, v87
	v_cvt_pk_bf16_f32 v85, v88, v89
	v_cvt_pk_bf16_f32 v86, v96, v97
	v_cvt_pk_bf16_f32 v87, v94, v95
	global_store_dwordx4 v[100:101], v[84:87], off offset:256 sc1 nt
	s_and_saveexec_b64 s[6:7], s[0:1]
	s_cbranch_execz .LBB0_1652
	s_waitcnt lgkmcnt(0)
	v_add_f32_e32 v84, v82, v83
	v_lshlrev_b64 v[82:83], 6, v[98:99]
	v_lshl_add_u64 v[82:83], s[86:87], 0, v[82:83]
	v_lshl_add_u64 v[82:83], s[4:5], 2, v[82:83]
	v_lshl_add_u64 v[82:83], v[82:83], 0, s[10:11]
	global_store_dword v[82:83], v84, off
.LBB0_1652:
	s_or_b64 exec, exec, s[6:7]
	ds_read_b32 v84, v225 offset:4288
	v_lshlrev_b32_e32 v88, 16, v182
	v_and_b32_e32 v89, 0xffff0000, v182
	v_lshlrev_b32_e32 v90, 16, v183
	v_and_b32_e32 v91, 0xffff0000, v183
	v_pk_mul_f32 v[80:81], v[80:81], v[180:181]
	v_pk_mul_f32 v[78:79], v[78:79], v[178:179]
	v_lshlrev_b32_e32 v92, 16, v184
	v_and_b32_e32 v93, 0xffff0000, v184
	v_lshlrev_b32_e32 v94, 16, v185
	v_and_b32_e32 v95, 0xffff0000, v185
	s_waitcnt lgkmcnt(0)
	v_pk_fma_f32 v[80:81], v[80:81], v[84:85], v[90:91] op_sel_hi:[1,0,1]
	v_pk_fma_f32 v[78:79], v[78:79], v[84:85], v[88:89] op_sel_hi:[1,0,1]
	v_pk_mul_f32 v[76:77], v[76:77], v[176:177]
	v_pk_mul_f32 v[74:75], v[74:75], v[174:175]
	v_pk_fma_f32 v[88:89], v[76:77], v[84:85], v[94:95] op_sel_hi:[1,0,1]
	v_pk_fma_f32 v[76:77], v[74:75], v[84:85], v[92:93] op_sel_hi:[1,0,1]
	v_mul_f32_e32 v74, v79, v79
	v_mul_f32_e32 v75, v81, v81
	v_fmac_f32_e32 v74, v78, v78
	v_fmac_f32_e32 v75, v80, v80
	v_add_f32_e32 v74, v74, v75
	v_mul_f32_e32 v75, v77, v77
	v_mul_f32_e32 v85, v89, v89
	v_fmac_f32_e32 v75, v76, v76
	v_fmac_f32_e32 v85, v88, v88
	v_add_f32_e32 v75, v75, v85
	v_add_f32_e32 v85, v74, v75
	v_cvt_pk_bf16_f32 v74, v78, v79
	v_cvt_pk_bf16_f32 v75, v80, v81
	v_lshlrev_b32_e32 v78, 16, v170
	v_and_b32_e32 v79, 0xffff0000, v170
	v_lshlrev_b32_e32 v80, 16, v171
	v_and_b32_e32 v81, 0xffff0000, v171
	v_pk_mul_f32 v[72:73], v[72:73], v[168:169]
	v_pk_mul_f32 v[70:71], v[70:71], v[166:167]
	v_cvt_pk_bf16_f32 v76, v76, v77
	v_cvt_pk_bf16_f32 v77, v88, v89
	v_lshlrev_b32_e32 v88, 16, v172
	v_and_b32_e32 v89, 0xffff0000, v172
	v_pk_fma_f32 v[72:73], v[72:73], v[84:85], v[80:81] op_sel_hi:[1,0,1]
	v_pk_fma_f32 v[70:71], v[70:71], v[84:85], v[78:79] op_sel_hi:[1,0,1]
	v_pk_mul_f32 v[66:67], v[66:67], v[162:163]
	v_lshlrev_b32_e32 v90, 16, v173
	v_and_b32_e32 v91, 0xffff0000, v173
	v_pk_mul_f32 v[68:69], v[68:69], v[164:165]
	v_pk_fma_f32 v[80:81], v[66:67], v[84:85], v[88:89] op_sel_hi:[1,0,1]
	v_mul_f32_e32 v66, v71, v71
	v_mul_f32_e32 v67, v73, v73
	v_pk_fma_f32 v[78:79], v[68:69], v[84:85], v[90:91] op_sel_hi:[1,0,1]
	v_fmac_f32_e32 v66, v70, v70
	v_fmac_f32_e32 v67, v72, v72
	v_add_f32_e32 v66, v66, v67
	v_mul_f32_e32 v67, v81, v81
	v_mul_f32_e32 v68, v79, v79
	v_fmac_f32_e32 v67, v80, v80
	v_fmac_f32_e32 v68, v78, v78
	v_add_f32_e32 v67, v67, v68
	v_add_f32_e32 v66, v66, v67
	v_add_f32_e32 v69, v85, v66
	ds_bpermute_b32 v88, v220, v69
	v_add3_u32 v82, s20, v216, 48
	v_ashrrev_i32_e32 v83, 31, v82
	v_lshlrev_b64 v[86:87], 11, v[82:83]
	v_lshl_add_u64 v[66:67], s[62:63], 0, v[86:87]
	v_lshl_add_u64 v[84:85], v[210:211], 1, v[66:67]
	s_waitcnt lgkmcnt(0)
	v_add_f32_e32 v66, v69, v88
	ds_bpermute_b32 v67, v221, v66
	global_store_dwordx4 v[84:85], v[74:77], off sc1 nt
	v_cvt_pk_bf16_f32 v68, v70, v71
	v_cvt_pk_bf16_f32 v69, v72, v73
	v_cvt_pk_bf16_f32 v70, v80, v81
	v_cvt_pk_bf16_f32 v71, v78, v79
	global_store_dwordx4 v[84:85], v[68:71], off offset:256 sc1 nt
	s_and_saveexec_b64 s[6:7], s[0:1]
	s_cbranch_execz .LBB0_1654
	s_waitcnt lgkmcnt(0)
	v_add_f32_e32 v68, v66, v67
	v_lshlrev_b64 v[66:67], 6, v[82:83]
	v_lshl_add_u64 v[66:67], s[86:87], 0, v[66:67]
	v_lshl_add_u64 v[66:67], s[4:5], 2, v[66:67]
	v_lshl_add_u64 v[66:67], v[66:67], 0, s[10:11]
	global_store_dword v[66:67], v68, off
.LBB0_1654:
	s_or_b64 exec, exec, s[6:7]
	ds_read_b32 v68, v225 offset:4608
	v_lshlrev_b32_e32 v72, 16, v158
	v_and_b32_e32 v73, 0xffff0000, v158
	v_lshlrev_b32_e32 v74, 16, v159
	v_and_b32_e32 v75, 0xffff0000, v159
	v_pk_mul_f32 v[64:65], v[64:65], v[180:181]
	v_pk_mul_f32 v[62:63], v[62:63], v[178:179]
	v_lshlrev_b32_e32 v76, 16, v160
	v_and_b32_e32 v77, 0xffff0000, v160
	v_lshlrev_b32_e32 v78, 16, v161
	v_and_b32_e32 v79, 0xffff0000, v161
	s_waitcnt lgkmcnt(0)
	v_pk_fma_f32 v[64:65], v[64:65], v[68:69], v[74:75] op_sel_hi:[1,0,1]
	v_pk_fma_f32 v[62:63], v[62:63], v[68:69], v[72:73] op_sel_hi:[1,0,1]
	v_pk_mul_f32 v[60:61], v[60:61], v[176:177]
	v_pk_mul_f32 v[58:59], v[58:59], v[174:175]
	v_pk_fma_f32 v[72:73], v[60:61], v[68:69], v[78:79] op_sel_hi:[1,0,1]
	v_pk_fma_f32 v[60:61], v[58:59], v[68:69], v[76:77] op_sel_hi:[1,0,1]
	v_mul_f32_e32 v58, v63, v63
	v_mul_f32_e32 v59, v65, v65
	v_fmac_f32_e32 v58, v62, v62
	v_fmac_f32_e32 v59, v64, v64
	v_add_f32_e32 v58, v58, v59
	v_mul_f32_e32 v59, v61, v61
	v_mul_f32_e32 v69, v73, v73
	v_fmac_f32_e32 v59, v60, v60
	v_fmac_f32_e32 v69, v72, v72
	v_add_f32_e32 v59, v59, v69
	v_add_f32_e32 v69, v58, v59
	v_cvt_pk_bf16_f32 v58, v62, v63
	v_cvt_pk_bf16_f32 v59, v64, v65
	v_lshlrev_b32_e32 v62, 16, v154
	v_and_b32_e32 v63, 0xffff0000, v154
	v_lshlrev_b32_e32 v64, 16, v155
	v_and_b32_e32 v65, 0xffff0000, v155
	v_pk_mul_f32 v[56:57], v[56:57], v[168:169]
	v_pk_mul_f32 v[54:55], v[54:55], v[166:167]
	v_cvt_pk_bf16_f32 v60, v60, v61
	v_cvt_pk_bf16_f32 v61, v72, v73
	v_lshlrev_b32_e32 v72, 16, v156
	v_and_b32_e32 v73, 0xffff0000, v156
	v_pk_fma_f32 v[56:57], v[56:57], v[68:69], v[64:65] op_sel_hi:[1,0,1]
	v_pk_fma_f32 v[54:55], v[54:55], v[68:69], v[62:63] op_sel_hi:[1,0,1]
	v_pk_mul_f32 v[50:51], v[50:51], v[162:163]
	v_lshlrev_b32_e32 v74, 16, v157
	v_and_b32_e32 v75, 0xffff0000, v157
	v_pk_mul_f32 v[52:53], v[52:53], v[164:165]
	v_pk_fma_f32 v[64:65], v[50:51], v[68:69], v[72:73] op_sel_hi:[1,0,1]
	v_mul_f32_e32 v50, v55, v55
	v_mul_f32_e32 v51, v57, v57
	v_pk_fma_f32 v[62:63], v[52:53], v[68:69], v[74:75] op_sel_hi:[1,0,1]
	v_fmac_f32_e32 v50, v54, v54
	v_fmac_f32_e32 v51, v56, v56
	v_add_f32_e32 v50, v50, v51
	v_mul_f32_e32 v51, v65, v65
	v_mul_f32_e32 v52, v63, v63
	v_fmac_f32_e32 v51, v64, v64
	v_fmac_f32_e32 v52, v62, v62
	v_add_f32_e32 v51, v51, v52
	v_add_f32_e32 v50, v50, v51
	v_add_f32_e32 v53, v69, v50
	ds_bpermute_b32 v72, v220, v53
	v_add_u32_e32 v66, 0x80, v214
	v_ashrrev_i32_e32 v67, 31, v66
	v_lshlrev_b64 v[70:71], 11, v[66:67]
	v_lshl_add_u64 v[50:51], s[62:63], 0, v[70:71]
	v_lshl_add_u64 v[68:69], v[210:211], 1, v[50:51]
	s_waitcnt lgkmcnt(0)
	v_add_f32_e32 v50, v53, v72
	ds_bpermute_b32 v51, v221, v50
	global_store_dwordx4 v[68:69], v[58:61], off sc1 nt
	v_cvt_pk_bf16_f32 v52, v54, v55
	v_cvt_pk_bf16_f32 v53, v56, v57
	v_cvt_pk_bf16_f32 v54, v64, v65
	v_cvt_pk_bf16_f32 v55, v62, v63
	global_store_dwordx4 v[68:69], v[52:55], off offset:256 sc1 nt
	s_and_saveexec_b64 s[6:7], s[0:1]
	s_cbranch_execz .LBB0_1656
	s_waitcnt lgkmcnt(0)
	v_add_f32_e32 v52, v50, v51
	v_lshlrev_b64 v[50:51], 6, v[66:67]
	v_lshl_add_u64 v[50:51], s[86:87], 0, v[50:51]
	v_lshl_add_u64 v[50:51], s[4:5], 2, v[50:51]
	v_lshl_add_u64 v[50:51], v[50:51], 0, s[10:11]
	global_store_dword v[50:51], v52, off
.LBB0_1656:
	s_or_b64 exec, exec, s[6:7]
	ds_read_b32 v52, v225 offset:4672
	v_lshlrev_b32_e32 v56, 16, v150
	v_and_b32_e32 v57, 0xffff0000, v150
	v_lshlrev_b32_e32 v58, 16, v151
	v_and_b32_e32 v59, 0xffff0000, v151
	v_pk_mul_f32 v[48:49], v[48:49], v[180:181]
	v_pk_mul_f32 v[46:47], v[46:47], v[178:179]
	v_lshlrev_b32_e32 v60, 16, v152
	v_and_b32_e32 v61, 0xffff0000, v152
	v_lshlrev_b32_e32 v62, 16, v153
	v_and_b32_e32 v63, 0xffff0000, v153
	s_waitcnt lgkmcnt(0)
	v_pk_fma_f32 v[48:49], v[48:49], v[52:53], v[58:59] op_sel_hi:[1,0,1]
	v_pk_fma_f32 v[46:47], v[46:47], v[52:53], v[56:57] op_sel_hi:[1,0,1]
	v_pk_mul_f32 v[44:45], v[44:45], v[176:177]
	v_pk_mul_f32 v[42:43], v[42:43], v[174:175]
	v_pk_fma_f32 v[56:57], v[44:45], v[52:53], v[62:63] op_sel_hi:[1,0,1]
	v_pk_fma_f32 v[44:45], v[42:43], v[52:53], v[60:61] op_sel_hi:[1,0,1]
	v_mul_f32_e32 v42, v47, v47
	v_mul_f32_e32 v43, v49, v49
	v_fmac_f32_e32 v42, v46, v46
	v_fmac_f32_e32 v43, v48, v48
	v_add_f32_e32 v42, v42, v43
	v_mul_f32_e32 v43, v45, v45
	v_mul_f32_e32 v53, v57, v57
	v_fmac_f32_e32 v43, v44, v44
	v_fmac_f32_e32 v53, v56, v56
	v_add_f32_e32 v43, v43, v53
	v_add_f32_e32 v53, v42, v43
	v_cvt_pk_bf16_f32 v42, v46, v47
	v_cvt_pk_bf16_f32 v43, v48, v49
	v_lshlrev_b32_e32 v46, 16, v146
	v_and_b32_e32 v47, 0xffff0000, v146
	v_lshlrev_b32_e32 v48, 16, v147
	v_and_b32_e32 v49, 0xffff0000, v147
	v_pk_mul_f32 v[40:41], v[40:41], v[168:169]
	v_pk_mul_f32 v[38:39], v[38:39], v[166:167]
	v_cvt_pk_bf16_f32 v44, v44, v45
	v_cvt_pk_bf16_f32 v45, v56, v57
	v_lshlrev_b32_e32 v56, 16, v148
	v_and_b32_e32 v57, 0xffff0000, v148
	v_pk_fma_f32 v[40:41], v[40:41], v[52:53], v[48:49] op_sel_hi:[1,0,1]
	v_pk_fma_f32 v[38:39], v[38:39], v[52:53], v[46:47] op_sel_hi:[1,0,1]
	v_pk_mul_f32 v[34:35], v[34:35], v[162:163]
	v_lshlrev_b32_e32 v58, 16, v149
	v_and_b32_e32 v59, 0xffff0000, v149
	v_pk_mul_f32 v[36:37], v[36:37], v[164:165]
	v_pk_fma_f32 v[48:49], v[34:35], v[52:53], v[56:57] op_sel_hi:[1,0,1]
	v_mul_f32_e32 v34, v39, v39
	v_mul_f32_e32 v35, v41, v41
	v_pk_fma_f32 v[46:47], v[36:37], v[52:53], v[58:59] op_sel_hi:[1,0,1]
	v_fmac_f32_e32 v34, v38, v38
	v_fmac_f32_e32 v35, v40, v40
	v_add_f32_e32 v34, v34, v35
	v_mul_f32_e32 v35, v49, v49
	v_mul_f32_e32 v36, v47, v47
	v_fmac_f32_e32 v35, v48, v48
	v_fmac_f32_e32 v36, v46, v46
	v_add_f32_e32 v35, v35, v36
	v_add_f32_e32 v34, v34, v35
	v_add_f32_e32 v37, v53, v34
	ds_bpermute_b32 v56, v220, v37
	v_add_u32_e32 v50, 0x90, v214
	v_ashrrev_i32_e32 v51, 31, v50
	v_lshlrev_b64 v[54:55], 11, v[50:51]
	v_lshl_add_u64 v[34:35], s[62:63], 0, v[54:55]
	v_lshl_add_u64 v[52:53], v[210:211], 1, v[34:35]
	s_waitcnt lgkmcnt(0)
	v_add_f32_e32 v34, v37, v56
	ds_bpermute_b32 v35, v221, v34
	global_store_dwordx4 v[52:53], v[42:45], off sc1 nt
	v_cvt_pk_bf16_f32 v36, v38, v39
	v_cvt_pk_bf16_f32 v37, v40, v41
	v_cvt_pk_bf16_f32 v38, v48, v49
	v_cvt_pk_bf16_f32 v39, v46, v47
	global_store_dwordx4 v[52:53], v[36:39], off offset:256 sc1 nt
	s_and_saveexec_b64 s[6:7], s[0:1]
	s_cbranch_execz .LBB0_1658
	s_waitcnt lgkmcnt(0)
	v_add_f32_e32 v36, v34, v35
	v_lshlrev_b64 v[34:35], 6, v[50:51]
	v_lshl_add_u64 v[34:35], s[86:87], 0, v[34:35]
	v_lshl_add_u64 v[34:35], s[4:5], 2, v[34:35]
	v_lshl_add_u64 v[34:35], v[34:35], 0, s[10:11]
	global_store_dword v[34:35], v36, off
.LBB0_1658:
	s_or_b64 exec, exec, s[6:7]
	ds_read_b32 v36, v225 offset:4736
	v_lshlrev_b32_e32 v40, 16, v142
	v_and_b32_e32 v41, 0xffff0000, v142
	v_lshlrev_b32_e32 v42, 16, v143
	v_and_b32_e32 v43, 0xffff0000, v143
	v_pk_mul_f32 v[32:33], v[32:33], v[180:181]
	v_pk_mul_f32 v[30:31], v[30:31], v[178:179]
	v_lshlrev_b32_e32 v44, 16, v144
	v_and_b32_e32 v45, 0xffff0000, v144
	v_lshlrev_b32_e32 v46, 16, v145
	v_and_b32_e32 v47, 0xffff0000, v145
	s_waitcnt lgkmcnt(0)
	v_pk_fma_f32 v[32:33], v[32:33], v[36:37], v[42:43] op_sel_hi:[1,0,1]
	v_pk_fma_f32 v[30:31], v[30:31], v[36:37], v[40:41] op_sel_hi:[1,0,1]
	v_pk_mul_f32 v[28:29], v[28:29], v[176:177]
	v_pk_mul_f32 v[26:27], v[26:27], v[174:175]
	v_pk_fma_f32 v[40:41], v[28:29], v[36:37], v[46:47] op_sel_hi:[1,0,1]
	v_pk_fma_f32 v[28:29], v[26:27], v[36:37], v[44:45] op_sel_hi:[1,0,1]
	v_mul_f32_e32 v26, v31, v31
	v_mul_f32_e32 v27, v33, v33
	v_fmac_f32_e32 v26, v30, v30
	v_fmac_f32_e32 v27, v32, v32
	v_add_f32_e32 v26, v26, v27
	v_mul_f32_e32 v27, v29, v29
	v_mul_f32_e32 v37, v41, v41
	v_fmac_f32_e32 v27, v28, v28
	v_fmac_f32_e32 v37, v40, v40
	v_add_f32_e32 v27, v27, v37
	v_add_f32_e32 v37, v26, v27
	v_cvt_pk_bf16_f32 v26, v30, v31
	v_cvt_pk_bf16_f32 v27, v32, v33
	v_lshlrev_b32_e32 v30, 16, v138
	v_and_b32_e32 v31, 0xffff0000, v138
	v_lshlrev_b32_e32 v32, 16, v139
	v_and_b32_e32 v33, 0xffff0000, v139
	v_pk_mul_f32 v[24:25], v[24:25], v[168:169]
	v_pk_mul_f32 v[22:23], v[22:23], v[166:167]
	v_cvt_pk_bf16_f32 v28, v28, v29
	v_cvt_pk_bf16_f32 v29, v40, v41
	v_lshlrev_b32_e32 v40, 16, v140
	v_and_b32_e32 v41, 0xffff0000, v140
	v_pk_fma_f32 v[24:25], v[24:25], v[36:37], v[32:33] op_sel_hi:[1,0,1]
	v_pk_fma_f32 v[22:23], v[22:23], v[36:37], v[30:31] op_sel_hi:[1,0,1]
	v_pk_mul_f32 v[18:19], v[18:19], v[162:163]
	v_lshlrev_b32_e32 v42, 16, v141
	v_and_b32_e32 v43, 0xffff0000, v141
	v_pk_mul_f32 v[20:21], v[20:21], v[164:165]
	v_pk_fma_f32 v[32:33], v[18:19], v[36:37], v[40:41] op_sel_hi:[1,0,1]
	v_mul_f32_e32 v18, v23, v23
	v_mul_f32_e32 v19, v25, v25
	v_pk_fma_f32 v[30:31], v[20:21], v[36:37], v[42:43] op_sel_hi:[1,0,1]
	v_fmac_f32_e32 v18, v22, v22
	v_fmac_f32_e32 v19, v24, v24
	v_add_f32_e32 v18, v18, v19
	v_mul_f32_e32 v19, v33, v33
	v_mul_f32_e32 v20, v31, v31
	v_fmac_f32_e32 v19, v32, v32
	v_fmac_f32_e32 v20, v30, v30
	v_add_f32_e32 v19, v19, v20
	v_add_f32_e32 v18, v18, v19
	v_add_f32_e32 v21, v37, v18
	ds_bpermute_b32 v40, v220, v21
	v_add_u32_e32 v34, 0xa0, v214
	v_ashrrev_i32_e32 v35, 31, v34
	v_lshlrev_b64 v[38:39], 11, v[34:35]
	v_lshl_add_u64 v[18:19], s[62:63], 0, v[38:39]
	v_lshl_add_u64 v[36:37], v[210:211], 1, v[18:19]
	s_waitcnt lgkmcnt(0)
	v_add_f32_e32 v18, v21, v40
	ds_bpermute_b32 v19, v221, v18
	global_store_dwordx4 v[36:37], v[26:29], off sc1 nt
	v_cvt_pk_bf16_f32 v20, v22, v23
	v_cvt_pk_bf16_f32 v21, v24, v25
	v_cvt_pk_bf16_f32 v22, v32, v33
	v_cvt_pk_bf16_f32 v23, v30, v31
	global_store_dwordx4 v[36:37], v[20:23], off offset:256 sc1 nt
	s_and_saveexec_b64 s[6:7], s[0:1]
	s_cbranch_execz .LBB0_1660
	s_waitcnt lgkmcnt(0)
	v_add_f32_e32 v20, v18, v19
	v_lshlrev_b64 v[18:19], 6, v[34:35]
	v_lshl_add_u64 v[18:19], s[86:87], 0, v[18:19]
	v_lshl_add_u64 v[18:19], s[4:5], 2, v[18:19]
	v_lshl_add_u64 v[18:19], v[18:19], 0, s[10:11]
	global_store_dword v[18:19], v20, off
.LBB0_1660:
	s_or_b64 exec, exec, s[6:7]
	ds_read_b32 v20, v225 offset:4800
	v_lshlrev_b32_e32 v24, 16, v134
	v_and_b32_e32 v25, 0xffff0000, v134
	v_lshlrev_b32_e32 v26, 16, v135
	v_and_b32_e32 v27, 0xffff0000, v135
	v_pk_mul_f32 v[16:17], v[16:17], v[180:181]
	v_pk_mul_f32 v[14:15], v[14:15], v[178:179]
	v_lshlrev_b32_e32 v28, 16, v136
	v_and_b32_e32 v29, 0xffff0000, v136
	v_lshlrev_b32_e32 v30, 16, v137
	v_and_b32_e32 v31, 0xffff0000, v137
	s_waitcnt lgkmcnt(0)
	v_pk_fma_f32 v[16:17], v[16:17], v[20:21], v[26:27] op_sel_hi:[1,0,1]
	v_pk_fma_f32 v[14:15], v[14:15], v[20:21], v[24:25] op_sel_hi:[1,0,1]
	v_pk_mul_f32 v[12:13], v[12:13], v[176:177]
	v_pk_mul_f32 v[10:11], v[10:11], v[174:175]
	v_pk_fma_f32 v[24:25], v[12:13], v[20:21], v[30:31] op_sel_hi:[1,0,1]
	v_pk_fma_f32 v[12:13], v[10:11], v[20:21], v[28:29] op_sel_hi:[1,0,1]
	v_mul_f32_e32 v10, v15, v15
	v_mul_f32_e32 v11, v17, v17
	v_fmac_f32_e32 v10, v14, v14
	v_fmac_f32_e32 v11, v16, v16
	v_add_f32_e32 v10, v10, v11
	v_mul_f32_e32 v11, v13, v13
	v_mul_f32_e32 v21, v25, v25
	v_fmac_f32_e32 v11, v12, v12
	v_fmac_f32_e32 v21, v24, v24
	v_add_f32_e32 v11, v11, v21
	v_add_f32_e32 v21, v10, v11
	v_cvt_pk_bf16_f32 v10, v14, v15
	v_cvt_pk_bf16_f32 v11, v16, v17
	v_lshlrev_b32_e32 v14, 16, v130
	v_and_b32_e32 v15, 0xffff0000, v130
	v_lshlrev_b32_e32 v16, 16, v131
	v_and_b32_e32 v17, 0xffff0000, v131
	v_pk_mul_f32 v[8:9], v[8:9], v[168:169]
	v_pk_mul_f32 v[6:7], v[6:7], v[166:167]
	v_cvt_pk_bf16_f32 v12, v12, v13
	v_cvt_pk_bf16_f32 v13, v24, v25
	v_lshlrev_b32_e32 v24, 16, v132
	v_and_b32_e32 v25, 0xffff0000, v132
	v_pk_fma_f32 v[8:9], v[8:9], v[20:21], v[16:17] op_sel_hi:[1,0,1]
	v_pk_fma_f32 v[6:7], v[6:7], v[20:21], v[14:15] op_sel_hi:[1,0,1]
	v_pk_mul_f32 v[2:3], v[2:3], v[162:163]
	v_lshlrev_b32_e32 v26, 16, v133
	v_and_b32_e32 v27, 0xffff0000, v133
	v_pk_mul_f32 v[4:5], v[4:5], v[164:165]
	v_pk_fma_f32 v[16:17], v[2:3], v[20:21], v[24:25] op_sel_hi:[1,0,1]
	v_mul_f32_e32 v2, v7, v7
	v_mul_f32_e32 v3, v9, v9
	v_pk_fma_f32 v[14:15], v[4:5], v[20:21], v[26:27] op_sel_hi:[1,0,1]
	v_fmac_f32_e32 v2, v6, v6
	v_fmac_f32_e32 v3, v8, v8
	v_add_f32_e32 v2, v2, v3
	v_mul_f32_e32 v3, v17, v17
	v_mul_f32_e32 v4, v15, v15
	v_fmac_f32_e32 v3, v16, v16
	v_fmac_f32_e32 v4, v14, v14
	v_add_f32_e32 v3, v3, v4
	v_add_f32_e32 v2, v2, v3
	v_add_f32_e32 v5, v21, v2
	ds_bpermute_b32 v24, v220, v5
	v_add_u32_e32 v18, 0xb0, v214
	v_ashrrev_i32_e32 v19, 31, v18
	v_lshlrev_b64 v[22:23], 11, v[18:19]
	v_lshl_add_u64 v[2:3], s[62:63], 0, v[22:23]
	v_lshl_add_u64 v[20:21], v[210:211], 1, v[2:3]
	s_waitcnt lgkmcnt(0)
	v_add_f32_e32 v2, v5, v24
	ds_bpermute_b32 v3, v221, v2
	global_store_dwordx4 v[20:21], v[10:13], off sc1 nt
	v_cvt_pk_bf16_f32 v4, v6, v7
	v_cvt_pk_bf16_f32 v5, v8, v9
	v_cvt_pk_bf16_f32 v6, v16, v17
	v_cvt_pk_bf16_f32 v7, v14, v15
	global_store_dwordx4 v[20:21], v[4:7], off offset:256 sc1 nt
	s_and_saveexec_b64 s[6:7], s[0:1]
	s_cbranch_execz .LBB0_1662
	s_waitcnt lgkmcnt(0)
	v_add_f32_e32 v4, v2, v3
	v_lshlrev_b64 v[2:3], 6, v[18:19]
	v_lshl_add_u64 v[2:3], s[86:87], 0, v[2:3]
	v_lshl_add_u64 v[2:3], s[4:5], 2, v[2:3]
	v_lshl_add_u64 v[2:3], v[2:3], 0, s[10:11]
	global_store_dword v[2:3], v4, off

.LBB0_1756:
	v_lshl_add_u32 v148, s34, 8, v152
	v_ashrrev_i32_e32 v149, 31, v148
	v_lshlrev_b64 v[150:151], 13, v[148:149]
	ds_read_b32 v149, v154
	v_lshl_or_b32 v146, s58, 8, v156
	v_max_f32_e32 v122, v122, v122
	v_ashrrev_i32_e32 v147, 31, v146
	v_max_f32_e32 v122, 0, v122
	v_max_f32_e32 v123, v123, v123
	v_max_f32_e32 v124, v124, v124
	v_lshl_add_u64 v[160:161], s[10:11], 0, v[150:151]
	v_lshlrev_b64 v[150:151], 1, v[146:147]
	s_waitcnt lgkmcnt(0)
	v_mul_f32_e32 v122, v122, v149
	v_max_f32_e32 v123, 0, v123
	v_max_f32_e32 v124, 0, v124
	v_lshl_add_u64 v[146:147], v[160:161], 0, v[150:151]
	v_mul_f32_e32 v160, v122, v122
	v_max_f32_e32 v122, v127, v127
	v_mul_f32_e32 v123, v123, v149
	v_mul_f32_e32 v124, v124, v149
	v_max_f32_e32 v126, v126, v126
	v_max_f32_e32 v122, 0, v122
	v_mul_f32_e32 v127, v123, v123
	v_max_f32_e32 v123, v128, v128
	v_mul_f32_e32 v128, v124, v124
	v_max_f32_e32 v124, v129, v129
	v_max_f32_e32 v125, v125, v125
	v_max_f32_e32 v126, 0, v126
	v_mul_f32_e32 v122, v122, v149
	v_max_f32_e32 v123, 0, v123
	v_max_f32_e32 v124, 0, v124
	v_max_f32_e32 v125, 0, v125
	v_max_f32_e32 v114, v114, v114
	v_max_f32_e32 v115, v115, v115
	v_max_f32_e32 v116, v116, v116
	v_mul_f32_e32 v126, v126, v149
	v_mul_f32_e32 v122, v122, v122
	v_mul_f32_e32 v123, v123, v149
	v_mul_f32_e32 v124, v124, v149
	v_mul_f32_e32 v125, v125, v149
	v_max_f32_e32 v114, 0, v114
	v_max_f32_e32 v115, 0, v115
	v_max_f32_e32 v116, 0, v116
	v_mul_f32_e32 v126, v126, v126
	v_mul_f32_e32 v123, v123, v123
	v_mul_f32_e32 v124, v124, v124
	v_mul_f32_e32 v125, v125, v125
	v_cvt_pk_bf16_f32 v122, v126, v122
	v_mul_f32_e32 v114, v114, v149
	v_mul_f32_e32 v115, v115, v149
	v_mul_f32_e32 v116, v116, v149
	v_cvt_pk_bf16_f32 v123, v123, v124
	v_cvt_pk_bf16_f32 v124, v160, v127
	v_cvt_pk_bf16_f32 v125, v128, v125
	global_store_dwordx4 v[146:147], v[122:125], off sc1 nt
	v_max_f32_e32 v118, v118, v118
	v_max_f32_e32 v117, v117, v117
	v_mul_f32_e32 v122, v114, v114
	v_max_f32_e32 v114, v119, v119
	v_mul_f32_e32 v119, v115, v115
	v_max_f32_e32 v115, v120, v120
	v_mul_f32_e32 v120, v116, v116
	v_max_f32_e32 v116, v121, v121
	v_max_f32_e32 v114, 0, v114
	v_max_f32_e32 v115, 0, v115
	v_max_f32_e32 v116, 0, v116
	v_max_f32_e32 v118, 0, v118
	v_mul_f32_e32 v114, v114, v149
	v_mul_f32_e32 v115, v115, v149
	v_mul_f32_e32 v116, v116, v149
	v_max_f32_e32 v117, 0, v117
	v_mul_f32_e32 v118, v118, v149
	v_mul_f32_e32 v114, v114, v114
	v_mul_f32_e32 v115, v115, v115
	v_mul_f32_e32 v117, v117, v149
	v_mul_f32_e32 v116, v116, v116
	v_mul_f32_e32 v118, v118, v118
	v_mul_f32_e32 v117, v117, v117
	v_cvt_pk_bf16_f32 v114, v118, v114
	v_cvt_pk_bf16_f32 v115, v115, v116
	v_cvt_pk_bf16_f32 v116, v122, v119
	v_cvt_pk_bf16_f32 v117, v120, v117
	global_store_dwordx4 v[146:147], v[114:117], off offset:256 sc1 nt
	ds_read_b32 v116, v154 offset:64
	v_max_f32_e32 v106, v106, v106
	v_max_f32_e32 v106, 0, v106
	v_max_f32_e32 v107, v107, v107
	v_max_f32_e32 v108, v108, v108
	s_waitcnt lgkmcnt(0)
	v_mul_f32_e32 v106, v106, v116
	v_max_f32_e32 v107, 0, v107
	v_max_f32_e32 v108, 0, v108
	v_or_b32_e32 v114, 16, v148
	v_mul_f32_e32 v117, v106, v106
	v_max_f32_e32 v106, v111, v111
	v_mul_f32_e32 v107, v107, v116
	v_mul_f32_e32 v108, v108, v116
	v_ashrrev_i32_e32 v115, 31, v114
	v_max_f32_e32 v110, v110, v110
	v_max_f32_e32 v106, 0, v106
	v_mul_f32_e32 v111, v107, v107
	v_max_f32_e32 v107, v112, v112
	v_mul_f32_e32 v112, v108, v108
	v_max_f32_e32 v108, v113, v113
	v_max_f32_e32 v109, v109, v109
	v_lshlrev_b64 v[114:115], 13, v[114:115]
	v_max_f32_e32 v110, 0, v110
	v_mul_f32_e32 v106, v106, v116
	v_max_f32_e32 v107, 0, v107
	v_max_f32_e32 v108, 0, v108
	v_max_f32_e32 v109, 0, v109
	v_max_f32_e32 v98, v98, v98
	v_max_f32_e32 v99, v99, v99
	v_max_f32_e32 v100, v100, v100
	v_lshl_add_u64 v[114:115], s[10:11], 0, v[114:115]
	v_mul_f32_e32 v110, v110, v116
	v_mul_f32_e32 v106, v106, v106
	v_mul_f32_e32 v107, v107, v116
	v_mul_f32_e32 v108, v108, v116
	v_mul_f32_e32 v109, v109, v116
	v_max_f32_e32 v98, 0, v98
	v_max_f32_e32 v99, 0, v99
	v_max_f32_e32 v100, 0, v100
	v_lshl_add_u64 v[114:115], v[114:115], 0, v[150:151]
	v_mul_f32_e32 v110, v110, v110
	v_mul_f32_e32 v107, v107, v107
	v_mul_f32_e32 v108, v108, v108
	v_mul_f32_e32 v109, v109, v109
	v_cvt_pk_bf16_f32 v106, v110, v106
	v_mul_f32_e32 v98, v98, v116
	v_mul_f32_e32 v99, v99, v116
	v_mul_f32_e32 v100, v100, v116
	v_cvt_pk_bf16_f32 v107, v107, v108
	v_cvt_pk_bf16_f32 v108, v117, v111
	v_cvt_pk_bf16_f32 v109, v112, v109
	global_store_dwordx4 v[114:115], v[106:109], off sc1 nt
	v_max_f32_e32 v102, v102, v102
	v_max_f32_e32 v101, v101, v101
	v_mul_f32_e32 v106, v98, v98
	v_max_f32_e32 v98, v103, v103
	v_mul_f32_e32 v103, v99, v99
	v_max_f32_e32 v99, v104, v104
	v_mul_f32_e32 v104, v100, v100
	v_max_f32_e32 v100, v105, v105
	v_max_f32_e32 v98, 0, v98
	v_max_f32_e32 v99, 0, v99
	v_max_f32_e32 v100, 0, v100
	v_max_f32_e32 v102, 0, v102
	v_mul_f32_e32 v98, v98, v116
	v_mul_f32_e32 v99, v99, v116
	v_mul_f32_e32 v100, v100, v116
	v_max_f32_e32 v101, 0, v101
	v_mul_f32_e32 v102, v102, v116
	v_mul_f32_e32 v98, v98, v98
	v_mul_f32_e32 v99, v99, v99
	v_mul_f32_e32 v101, v101, v116
	v_mul_f32_e32 v100, v100, v100
	v_mul_f32_e32 v102, v102, v102
	v_mul_f32_e32 v101, v101, v101
	v_cvt_pk_bf16_f32 v98, v102, v98
	v_cvt_pk_bf16_f32 v99, v99, v100
	v_cvt_pk_bf16_f32 v100, v106, v103
	v_cvt_pk_bf16_f32 v101, v104, v101
	global_store_dwordx4 v[114:115], v[98:101], off offset:256 sc1 nt
	ds_read_b32 v100, v154 offset:128
	v_max_f32_e32 v90, v90, v90
	v_max_f32_e32 v90, 0, v90
	v_max_f32_e32 v91, v91, v91
	v_max_f32_e32 v92, v92, v92
	s_waitcnt lgkmcnt(0)
	v_mul_f32_e32 v90, v90, v100
	v_max_f32_e32 v91, 0, v91
	v_max_f32_e32 v92, 0, v92
	v_or_b32_e32 v98, 32, v148
	v_mul_f32_e32 v101, v90, v90
	v_max_f32_e32 v90, v95, v95
	v_mul_f32_e32 v91, v91, v100
	v_mul_f32_e32 v92, v92, v100
	v_ashrrev_i32_e32 v99, 31, v98
	v_max_f32_e32 v94, v94, v94
	v_max_f32_e32 v90, 0, v90
	v_mul_f32_e32 v95, v91, v91
	v_max_f32_e32 v91, v96, v96
	v_mul_f32_e32 v96, v92, v92
	v_max_f32_e32 v92, v97, v97
	v_max_f32_e32 v93, v93, v93
	v_lshlrev_b64 v[98:99], 13, v[98:99]
	v_max_f32_e32 v94, 0, v94
	v_mul_f32_e32 v90, v90, v100
	v_max_f32_e32 v91, 0, v91
	v_max_f32_e32 v92, 0, v92
	v_max_f32_e32 v93, 0, v93
	v_max_f32_e32 v82, v82, v82
	v_max_f32_e32 v83, v83, v83
	v_max_f32_e32 v84, v84, v84
	v_lshl_add_u64 v[98:99], s[10:11], 0, v[98:99]
	v_mul_f32_e32 v94, v94, v100
	v_mul_f32_e32 v90, v90, v90
	v_mul_f32_e32 v91, v91, v100
	v_mul_f32_e32 v92, v92, v100
	v_mul_f32_e32 v93, v93, v100
	v_max_f32_e32 v82, 0, v82
	v_max_f32_e32 v83, 0, v83
	v_max_f32_e32 v84, 0, v84
	v_lshl_add_u64 v[98:99], v[98:99], 0, v[150:151]
	v_mul_f32_e32 v94, v94, v94
	v_mul_f32_e32 v91, v91, v91
	v_mul_f32_e32 v92, v92, v92
	v_mul_f32_e32 v93, v93, v93
	v_cvt_pk_bf16_f32 v90, v94, v90
	v_mul_f32_e32 v82, v82, v100
	v_mul_f32_e32 v83, v83, v100
	v_mul_f32_e32 v84, v84, v100
	v_cvt_pk_bf16_f32 v91, v91, v92
	v_cvt_pk_bf16_f32 v92, v101, v95
	v_cvt_pk_bf16_f32 v93, v96, v93
	global_store_dwordx4 v[98:99], v[90:93], off sc1 nt
	v_max_f32_e32 v86, v86, v86
	v_max_f32_e32 v85, v85, v85
	v_mul_f32_e32 v90, v82, v82
	v_max_f32_e32 v82, v87, v87
	v_mul_f32_e32 v87, v83, v83
	v_max_f32_e32 v83, v88, v88
	v_mul_f32_e32 v88, v84, v84
	v_max_f32_e32 v84, v89, v89
	v_max_f32_e32 v82, 0, v82
	v_max_f32_e32 v83, 0, v83
	v_max_f32_e32 v84, 0, v84
	v_max_f32_e32 v86, 0, v86
	v_mul_f32_e32 v82, v82, v100
	v_mul_f32_e32 v83, v83, v100
	v_mul_f32_e32 v84, v84, v100
	v_max_f32_e32 v85, 0, v85
	v_mul_f32_e32 v86, v86, v100
	v_mul_f32_e32 v82, v82, v82
	v_mul_f32_e32 v83, v83, v83
	v_mul_f32_e32 v85, v85, v100
	v_mul_f32_e32 v84, v84, v84
	v_mul_f32_e32 v86, v86, v86
	v_mul_f32_e32 v85, v85, v85
	v_cvt_pk_bf16_f32 v82, v86, v82
	v_cvt_pk_bf16_f32 v83, v83, v84
	v_cvt_pk_bf16_f32 v84, v90, v87
	v_cvt_pk_bf16_f32 v85, v88, v85
	global_store_dwordx4 v[98:99], v[82:85], off offset:256 sc1 nt
	ds_read_b32 v84, v154 offset:192
	v_max_f32_e32 v74, v74, v74
	v_max_f32_e32 v74, 0, v74
	v_max_f32_e32 v75, v75, v75
	v_max_f32_e32 v76, v76, v76
	s_waitcnt lgkmcnt(0)
	v_mul_f32_e32 v74, v74, v84
	v_max_f32_e32 v75, 0, v75
	v_max_f32_e32 v76, 0, v76
	v_or_b32_e32 v82, 48, v148
	v_mul_f32_e32 v85, v74, v74
	v_max_f32_e32 v74, v79, v79
	v_mul_f32_e32 v75, v75, v84
	v_mul_f32_e32 v76, v76, v84
	v_ashrrev_i32_e32 v83, 31, v82
	v_max_f32_e32 v78, v78, v78
	v_max_f32_e32 v74, 0, v74
	v_mul_f32_e32 v79, v75, v75
	v_max_f32_e32 v75, v80, v80
	v_mul_f32_e32 v80, v76, v76
	v_max_f32_e32 v76, v81, v81
	v_max_f32_e32 v77, v77, v77
	v_lshlrev_b64 v[82:83], 13, v[82:83]
	v_max_f32_e32 v78, 0, v78
	v_mul_f32_e32 v74, v74, v84
	v_max_f32_e32 v75, 0, v75
	v_max_f32_e32 v76, 0, v76
	v_max_f32_e32 v77, 0, v77
	v_max_f32_e32 v66, v66, v66
	v_max_f32_e32 v67, v67, v67
	v_max_f32_e32 v68, v68, v68
	v_lshl_add_u64 v[82:83], s[10:11], 0, v[82:83]
	v_mul_f32_e32 v78, v78, v84
	v_mul_f32_e32 v74, v74, v74
	v_mul_f32_e32 v75, v75, v84
	v_mul_f32_e32 v76, v76, v84
	v_mul_f32_e32 v77, v77, v84
	v_max_f32_e32 v66, 0, v66
	v_max_f32_e32 v67, 0, v67
	v_max_f32_e32 v68, 0, v68
	v_lshl_add_u64 v[82:83], v[82:83], 0, v[150:151]
	v_mul_f32_e32 v78, v78, v78
	v_mul_f32_e32 v75, v75, v75
	v_mul_f32_e32 v76, v76, v76
	v_mul_f32_e32 v77, v77, v77
	v_cvt_pk_bf16_f32 v74, v78, v74
	v_mul_f32_e32 v66, v66, v84
	v_mul_f32_e32 v67, v67, v84
	v_mul_f32_e32 v68, v68, v84
	v_cvt_pk_bf16_f32 v75, v75, v76
	v_cvt_pk_bf16_f32 v76, v85, v79
	v_cvt_pk_bf16_f32 v77, v80, v77
	global_store_dwordx4 v[82:83], v[74:77], off sc1 nt
	v_max_f32_e32 v70, v70, v70
	v_max_f32_e32 v69, v69, v69
	v_mul_f32_e32 v74, v66, v66
	v_max_f32_e32 v66, v71, v71
	v_mul_f32_e32 v71, v67, v67
	v_max_f32_e32 v67, v72, v72
	v_mul_f32_e32 v72, v68, v68
	v_max_f32_e32 v68, v73, v73
	v_max_f32_e32 v70, 0, v70
	v_max_f32_e32 v66, 0, v66
	v_max_f32_e32 v67, 0, v67
	v_max_f32_e32 v68, 0, v68
	v_max_f32_e32 v69, 0, v69
	v_mul_f32_e32 v70, v70, v84
	v_mul_f32_e32 v66, v66, v84
	v_mul_f32_e32 v67, v67, v84
	v_mul_f32_e32 v68, v68, v84
	v_mul_f32_e32 v69, v69, v84
	v_mul_f32_e32 v70, v70, v70
	v_mul_f32_e32 v66, v66, v66
	v_mul_f32_e32 v67, v67, v67
	v_mul_f32_e32 v68, v68, v68
	v_mul_f32_e32 v69, v69, v69
	v_cvt_pk_bf16_f32 v66, v70, v66
	v_cvt_pk_bf16_f32 v67, v67, v68
	v_cvt_pk_bf16_f32 v68, v74, v71
	v_cvt_pk_bf16_f32 v69, v72, v69
	ds_read_b32 v70, v155
	v_max_f32_e32 v58, v58, v58
	v_max_f32_e32 v58, 0, v58
	v_max_f32_e32 v59, v59, v59
	v_max_f32_e32 v60, v60, v60
	s_waitcnt lgkmcnt(0)
	v_mul_f32_e32 v58, v58, v70
	v_max_f32_e32 v59, 0, v59
	v_max_f32_e32 v60, 0, v60
	global_store_dwordx4 v[82:83], v[66:69], off offset:256 sc1 nt
	v_max_f32_e32 v62, v62, v62
	v_mul_f32_e32 v59, v59, v70
	v_mul_f32_e32 v68, v58, v58
	v_max_f32_e32 v58, v63, v63
	v_mul_f32_e32 v60, v60, v70
	v_max_f32_e32 v62, 0, v62
	v_max_f32_e32 v58, 0, v58
	v_mul_f32_e32 v63, v59, v59
	v_max_f32_e32 v59, v64, v64
	v_mul_f32_e32 v64, v60, v60
	v_max_f32_e32 v60, v65, v65
	v_mul_f32_e32 v62, v62, v70
	v_mul_f32_e32 v58, v58, v70
	v_max_f32_e32 v59, 0, v59
	v_max_f32_e32 v60, 0, v60
	v_max_f32_e32 v61, v61, v61
	v_mul_f32_e32 v62, v62, v62
	v_mul_f32_e32 v58, v58, v58
	v_mul_f32_e32 v59, v59, v70
	v_mul_f32_e32 v60, v60, v70
	v_max_f32_e32 v61, 0, v61
	v_max_f32_e32 v50, v50, v50
	v_max_f32_e32 v51, v51, v51
	v_max_f32_e32 v52, v52, v52
	v_mul_f32_e32 v59, v59, v59
	v_mul_f32_e32 v61, v61, v70
	v_mul_f32_e32 v60, v60, v60
	v_cvt_pk_bf16_f32 v58, v62, v58
	v_add_co_u32_e32 v62, vcc, s52, v146
	v_max_f32_e32 v50, 0, v50
	v_max_f32_e32 v51, 0, v51
	v_max_f32_e32 v52, 0, v52
	v_mul_f32_e32 v61, v61, v61
	v_cvt_pk_bf16_f32 v59, v59, v60
	v_cvt_pk_bf16_f32 v60, v68, v63
	v_addc_co_u32_e32 v63, vcc, 0, v147, vcc
	v_mul_f32_e32 v50, v50, v70
	v_mul_f32_e32 v51, v51, v70
	v_mul_f32_e32 v52, v52, v70
	v_cvt_pk_bf16_f32 v61, v64, v61
	global_store_dwordx4 v[62:63], v[58:61], off sc1 nt
	v_max_f32_e32 v54, v54, v54
	v_max_f32_e32 v53, v53, v53
	v_mul_f32_e32 v58, v50, v50
	v_max_f32_e32 v50, v55, v55
	v_mul_f32_e32 v55, v51, v51
	v_max_f32_e32 v51, v56, v56
	v_mul_f32_e32 v56, v52, v52
	v_max_f32_e32 v52, v57, v57
	v_max_f32_e32 v54, 0, v54
	v_max_f32_e32 v50, 0, v50
	v_max_f32_e32 v51, 0, v51
	v_max_f32_e32 v52, 0, v52
	v_max_f32_e32 v53, 0, v53
	v_mul_f32_e32 v54, v54, v70
	v_mul_f32_e32 v50, v50, v70
	v_mul_f32_e32 v51, v51, v70
	v_mul_f32_e32 v52, v52, v70
	v_mul_f32_e32 v53, v53, v70
	v_mul_f32_e32 v54, v54, v54
	v_mul_f32_e32 v50, v50, v50
	v_mul_f32_e32 v51, v51, v51
	v_mul_f32_e32 v52, v52, v52
	v_mul_f32_e32 v53, v53, v53
	v_cvt_pk_bf16_f32 v50, v54, v50
	v_cvt_pk_bf16_f32 v51, v51, v52
	v_cvt_pk_bf16_f32 v52, v58, v55
	v_cvt_pk_bf16_f32 v53, v56, v53
	ds_read_b32 v54, v154 offset:576
	v_max_f32_e32 v42, v42, v42
	v_max_f32_e32 v42, 0, v42
	v_max_f32_e32 v43, v43, v43
	v_max_f32_e32 v44, v44, v44
	v_lshl_add_u64 v[66:67], v[146:147], 0, s[16:17]
	s_waitcnt lgkmcnt(0)
	v_mul_f32_e32 v42, v42, v54
	v_max_f32_e32 v43, 0, v43
	v_max_f32_e32 v44, 0, v44
	global_store_dwordx4 v[66:67], v[50:53], off offset:256 sc1 nt
	v_max_f32_e32 v46, v46, v46
	v_mul_f32_e32 v43, v43, v54
	v_mul_f32_e32 v52, v42, v42
	v_max_f32_e32 v42, v47, v47
	v_mul_f32_e32 v44, v44, v54
	v_max_f32_e32 v46, 0, v46
	v_max_f32_e32 v42, 0, v42
	v_mul_f32_e32 v47, v43, v43
	v_max_f32_e32 v43, v48, v48
	v_mul_f32_e32 v48, v44, v44
	v_max_f32_e32 v44, v49, v49
	v_mul_f32_e32 v46, v46, v54
	v_mul_f32_e32 v42, v42, v54
	v_max_f32_e32 v43, 0, v43
	v_max_f32_e32 v44, 0, v44
	v_max_f32_e32 v45, v45, v45
	v_mul_f32_e32 v46, v46, v46
	v_mul_f32_e32 v42, v42, v42
	v_mul_f32_e32 v43, v43, v54
	v_mul_f32_e32 v44, v44, v54
	v_max_f32_e32 v45, 0, v45
	v_max_f32_e32 v34, v34, v34
	v_max_f32_e32 v35, v35, v35
	v_max_f32_e32 v36, v36, v36
	v_mul_f32_e32 v43, v43, v43
	v_mul_f32_e32 v45, v45, v54
	v_mul_f32_e32 v44, v44, v44
	v_cvt_pk_bf16_f32 v42, v46, v42
	v_add_co_u32_e32 v46, vcc, s53, v146
	v_max_f32_e32 v34, 0, v34
	v_max_f32_e32 v35, 0, v35
	v_max_f32_e32 v36, 0, v36
	v_mul_f32_e32 v45, v45, v45
	v_cvt_pk_bf16_f32 v43, v43, v44
	v_cvt_pk_bf16_f32 v44, v52, v47
	v_addc_co_u32_e32 v47, vcc, 0, v147, vcc
	v_mul_f32_e32 v34, v34, v54
	v_mul_f32_e32 v35, v35, v54
	v_mul_f32_e32 v36, v36, v54
	v_cvt_pk_bf16_f32 v45, v48, v45
	global_store_dwordx4 v[46:47], v[42:45], off sc1 nt
	v_max_f32_e32 v38, v38, v38
	v_max_f32_e32 v37, v37, v37
	v_mul_f32_e32 v42, v34, v34
	v_max_f32_e32 v34, v39, v39
	v_mul_f32_e32 v39, v35, v35
	v_max_f32_e32 v35, v40, v40
	v_mul_f32_e32 v40, v36, v36
	v_max_f32_e32 v36, v41, v41
	v_max_f32_e32 v38, 0, v38
	v_max_f32_e32 v34, 0, v34
	v_max_f32_e32 v35, 0, v35
	v_max_f32_e32 v36, 0, v36
	v_max_f32_e32 v37, 0, v37
	v_mul_f32_e32 v38, v38, v54
	v_mul_f32_e32 v34, v34, v54
	v_mul_f32_e32 v35, v35, v54
	v_mul_f32_e32 v36, v36, v54
	v_mul_f32_e32 v37, v37, v54
	v_mul_f32_e32 v38, v38, v38
	v_mul_f32_e32 v34, v34, v34
	v_mul_f32_e32 v35, v35, v35
	v_mul_f32_e32 v36, v36, v36
	v_mul_f32_e32 v37, v37, v37
	v_cvt_pk_bf16_f32 v34, v38, v34
	v_cvt_pk_bf16_f32 v35, v35, v36
	v_cvt_pk_bf16_f32 v36, v42, v39
	v_cvt_pk_bf16_f32 v37, v40, v37
	ds_read_b32 v38, v154 offset:640
	v_max_f32_e32 v26, v26, v26
	v_max_f32_e32 v26, 0, v26
	v_max_f32_e32 v27, v27, v27
	v_max_f32_e32 v28, v28, v28
	v_lshl_add_u64 v[50:51], v[146:147], 0, s[18:19]
	s_waitcnt lgkmcnt(0)
	v_mul_f32_e32 v26, v26, v38
	v_max_f32_e32 v27, 0, v27
	v_max_f32_e32 v28, 0, v28
	global_store_dwordx4 v[50:51], v[34:37], off offset:256 sc1 nt
	v_max_f32_e32 v30, v30, v30
	v_mul_f32_e32 v27, v27, v38
	v_mul_f32_e32 v36, v26, v26
	v_max_f32_e32 v26, v31, v31
	v_mul_f32_e32 v28, v28, v38
	v_max_f32_e32 v30, 0, v30
	v_max_f32_e32 v26, 0, v26
	v_mul_f32_e32 v31, v27, v27
	v_max_f32_e32 v27, v32, v32
	v_mul_f32_e32 v32, v28, v28
	v_max_f32_e32 v28, v33, v33
	v_mul_f32_e32 v30, v30, v38
	v_mul_f32_e32 v26, v26, v38
	v_max_f32_e32 v27, 0, v27
	v_max_f32_e32 v28, 0, v28
	v_max_f32_e32 v29, v29, v29
	v_mul_f32_e32 v30, v30, v30
	v_mul_f32_e32 v26, v26, v26
	v_mul_f32_e32 v27, v27, v38
	v_mul_f32_e32 v28, v28, v38
	v_max_f32_e32 v29, 0, v29
	v_max_f32_e32 v18, v18, v18
	v_max_f32_e32 v19, v19, v19
	v_max_f32_e32 v20, v20, v20
	v_mul_f32_e32 v27, v27, v27
	v_mul_f32_e32 v29, v29, v38
	v_mul_f32_e32 v28, v28, v28
	v_cvt_pk_bf16_f32 v26, v30, v26
	v_add_co_u32_e32 v30, vcc, s54, v146
	v_max_f32_e32 v18, 0, v18
	v_max_f32_e32 v19, 0, v19
	v_max_f32_e32 v20, 0, v20
	v_mul_f32_e32 v29, v29, v29
	v_cvt_pk_bf16_f32 v27, v27, v28
	v_cvt_pk_bf16_f32 v28, v36, v31
	v_addc_co_u32_e32 v31, vcc, 0, v147, vcc
	v_mul_f32_e32 v18, v18, v38
	v_mul_f32_e32 v19, v19, v38
	v_mul_f32_e32 v20, v20, v38
	v_cvt_pk_bf16_f32 v29, v32, v29
	global_store_dwordx4 v[30:31], v[26:29], off sc1 nt
	v_max_f32_e32 v22, v22, v22
	v_max_f32_e32 v21, v21, v21
	v_mul_f32_e32 v26, v18, v18
	v_max_f32_e32 v18, v23, v23
	v_mul_f32_e32 v23, v19, v19
	v_max_f32_e32 v19, v24, v24
	v_mul_f32_e32 v24, v20, v20
	v_max_f32_e32 v20, v25, v25
	v_max_f32_e32 v22, 0, v22
	v_max_f32_e32 v18, 0, v18
	v_max_f32_e32 v19, 0, v19
	v_max_f32_e32 v20, 0, v20
	v_max_f32_e32 v21, 0, v21
	v_mul_f32_e32 v22, v22, v38
	v_mul_f32_e32 v18, v18, v38
	v_mul_f32_e32 v19, v19, v38
	v_mul_f32_e32 v20, v20, v38
	v_mul_f32_e32 v21, v21, v38
	v_mul_f32_e32 v22, v22, v22
	v_mul_f32_e32 v18, v18, v18
	v_mul_f32_e32 v19, v19, v19
	v_mul_f32_e32 v20, v20, v20
	v_mul_f32_e32 v21, v21, v21
	v_cvt_pk_bf16_f32 v18, v22, v18
	v_cvt_pk_bf16_f32 v19, v19, v20
	v_cvt_pk_bf16_f32 v20, v26, v23
	v_cvt_pk_bf16_f32 v21, v24, v21
	ds_read_b32 v22, v154 offset:704
	v_max_f32_e32 v10, v10, v10
	v_max_f32_e32 v10, 0, v10
	v_max_f32_e32 v11, v11, v11
	v_max_f32_e32 v12, v12, v12
	v_lshl_add_u64 v[34:35], v[146:147], 0, s[20:21]
	s_waitcnt lgkmcnt(0)
	v_mul_f32_e32 v10, v10, v22
	v_max_f32_e32 v11, 0, v11
	v_max_f32_e32 v12, 0, v12
	global_store_dwordx4 v[34:35], v[18:21], off offset:256 sc1 nt
	v_max_f32_e32 v14, v14, v14
	v_mul_f32_e32 v11, v11, v22
	v_mul_f32_e32 v20, v10, v10
	v_max_f32_e32 v10, v15, v15
	v_mul_f32_e32 v12, v12, v22
	v_max_f32_e32 v14, 0, v14
	v_max_f32_e32 v10, 0, v10
	v_mul_f32_e32 v15, v11, v11
	v_max_f32_e32 v11, v16, v16
	v_mul_f32_e32 v16, v12, v12
	v_max_f32_e32 v12, v17, v17
	v_mul_f32_e32 v14, v14, v22
	v_mul_f32_e32 v10, v10, v22
	v_max_f32_e32 v11, 0, v11
	v_max_f32_e32 v12, 0, v12
	v_max_f32_e32 v13, v13, v13
	v_mul_f32_e32 v14, v14, v14
	v_mul_f32_e32 v10, v10, v10
	v_mul_f32_e32 v11, v11, v22
	v_mul_f32_e32 v12, v12, v22
	v_max_f32_e32 v13, 0, v13
	v_max_f32_e32 v2, v2, v2
	v_max_f32_e32 v3, v3, v3
	v_max_f32_e32 v4, v4, v4
	v_mul_f32_e32 v11, v11, v11
	v_mul_f32_e32 v13, v13, v22
	v_mul_f32_e32 v12, v12, v12
	v_cvt_pk_bf16_f32 v10, v14, v10
	v_add_co_u32_e32 v14, vcc, s55, v146
	v_max_f32_e32 v2, 0, v2
	v_max_f32_e32 v3, 0, v3
	v_max_f32_e32 v4, 0, v4
	v_mul_f32_e32 v13, v13, v13
	v_cvt_pk_bf16_f32 v11, v11, v12
	v_cvt_pk_bf16_f32 v12, v20, v15
	v_addc_co_u32_e32 v15, vcc, 0, v147, vcc
	v_mul_f32_e32 v2, v2, v22
	v_mul_f32_e32 v3, v3, v22
	v_mul_f32_e32 v4, v4, v22
	v_cvt_pk_bf16_f32 v13, v16, v13
	global_store_dwordx4 v[14:15], v[10:13], off sc1 nt
	v_max_f32_e32 v5, v5, v5
	v_max_f32_e32 v6, v6, v6
	v_mul_f32_e32 v10, v2, v2
	v_max_f32_e32 v2, v7, v7
	v_mul_f32_e32 v7, v3, v3
	v_max_f32_e32 v3, v8, v8
	v_mul_f32_e32 v8, v4, v4
	v_max_f32_e32 v4, v9, v9
	v_max_f32_e32 v2, 0, v2
	v_max_f32_e32 v3, 0, v3
	v_max_f32_e32 v4, 0, v4
	v_max_f32_e32 v5, 0, v5
	v_max_f32_e32 v6, 0, v6
	v_mul_f32_e32 v2, v2, v22
	v_mul_f32_e32 v3, v3, v22
	v_mul_f32_e32 v4, v4, v22
	v_mul_f32_e32 v5, v5, v22
	v_lshl_add_u64 v[18:19], v[146:147], 0, s[22:23]
	v_mul_f32_e32 v6, v6, v22
	v_mul_f32_e32 v2, v2, v2
	v_mul_f32_e32 v3, v3, v3
	v_mul_f32_e32 v4, v4, v4
	v_mul_f32_e32 v5, v5, v5
	s_andn2_b64 vcc, exec, s[0:1]
	s_mov_b64 s[0:1], -1
	v_mul_f32_e32 v6, v6, v6
	v_cvt_pk_bf16_f32 v2, v6, v2
	v_cvt_pk_bf16_f32 v3, v3, v4
	v_cvt_pk_bf16_f32 v4, v10, v7
	v_cvt_pk_bf16_f32 v5, v8, v5
	global_store_dwordx4 v[18:19], v[2:5], off offset:256 sc1 nt
	s_cbranch_vccnz .LBB0_1745
	s_andn2_b64 vcc, exec, s[8:9]
	s_cbranch_vccnz .LBB0_1744
	s_barrier
	s_branch .LBB0_1744

.LBB0_1825:
	v_lshlrev_b32_e32 v34, 14, v169
	v_lshlrev_b32_e32 v35, 12, v136
	v_add3_u32 v34, v163, v34, v35
	s_barrier
	s_nop 4
	ds_write2st64_b32 v34, v2, v3 offset1:1
	ds_write2st64_b32 v34, v4, v5 offset0:2 offset1:3
	ds_write2st64_b32 v34, v6, v7 offset0:4 offset1:5
	ds_write2st64_b32 v34, v8, v9 offset0:6 offset1:7
	ds_write2st64_b32 v34, v10, v11 offset0:8 offset1:9
	ds_write2st64_b32 v34, v12, v13 offset0:10 offset1:11
	ds_write2st64_b32 v34, v14, v15 offset0:12 offset1:13
	ds_write2st64_b32 v34, v16, v17 offset0:14 offset1:15
	ds_write2st64_b32 v34, v18, v19 offset0:16 offset1:17
	ds_write2st64_b32 v34, v20, v21 offset0:18 offset1:19
	ds_write2st64_b32 v34, v22, v23 offset0:20 offset1:21
	ds_write2st64_b32 v34, v24, v25 offset0:22 offset1:23
	ds_write2st64_b32 v34, v26, v27 offset0:24 offset1:25
	ds_write2st64_b32 v34, v28, v29 offset0:26 offset1:27
	ds_write2st64_b32 v34, v30, v31 offset0:28 offset1:29
	ds_write2st64_b32 v34, v32, v33 offset0:30 offset1:31
	v_lshrrev_b32_e32 v3, 3, v134
	v_lshlrev_b32_e32 v2, 3, v168
	v_and_b32_e32 v3, 0xfffff0, v3
	v_and_or_b32 v2, v2, 8, v3
	v_lshl_add_u32 v32, v2, 8, v163
	s_waitcnt lgkmcnt(0)
	s_barrier
	ds_read2st64_b32 v[2:3], v32 offset1:1
	ds_read2st64_b32 v[4:5], v32 offset0:2 offset1:3
	ds_read2st64_b32 v[10:11], v32 offset0:4 offset1:5
	ds_read2st64_b32 v[12:13], v32 offset0:6 offset1:7
	ds_read2st64_b32 v[6:7], v32 offset0:64 offset1:65
	ds_read2st64_b32 v[8:9], v32 offset0:66 offset1:67
	ds_read2st64_b32 v[14:15], v32 offset0:68 offset1:69
	ds_read2st64_b32 v[16:17], v32 offset0:70 offset1:71
	ds_read2st64_b32 v[18:19], v32 offset0:128 offset1:129
	ds_read2st64_b32 v[20:21], v32 offset0:130 offset1:131
	ds_read2st64_b32 v[22:23], v32 offset0:132 offset1:133
	ds_read2st64_b32 v[24:25], v32 offset0:134 offset1:135
	ds_read2st64_b32 v[26:27], v32 offset0:192 offset1:193
	ds_read2st64_b32 v[28:29], v32 offset0:194 offset1:195
	ds_read2st64_b32 v[30:31], v32 offset0:196 offset1:197
	ds_read2st64_b32 v[32:33], v32 offset0:198 offset1:199
	s_waitcnt lgkmcnt(0)
	s_barrier
	s_getreg_b32 s6, hwreg(HW_REG_HW_ID, 0, 6)
	s_and_b32 s6, s6, 63
	s_add_i32 s7, 0, 0x23e00
	s_lshl_b32 s6, s6, 2
	s_add_i32 s6, s7, s6
	v_mov_b32_e32 v34, s6
	v_mov_b32_e32 v35, s11
	flat_load_dword v36, v[34:35] sc0 sc1
	s_waitcnt vmcnt(0)
	s_getreg_b32 s6, hwreg(HW_REG_HW_ID, 0, 6)
	s_and_b32 s6, s6, 63
	s_lshl_b32 s6, s6, 2
	s_add_i32 s7, s7, s6
	v_mov_b32_e32 v34, s7
	flat_load_dword v34, v[34:35] sc0 sc1
	s_waitcnt vmcnt(0)
	v_pk_add_f32 v[2:3], v[2:3], 0 op_sel_hi:[1,0]
	s_waitcnt lgkmcnt(0)
	v_readfirstlane_b32 s44, v36
	v_pk_add_f32 v[2:3], v[2:3], v[6:7]
	v_readfirstlane_b32 s6, v34
	v_pk_add_f32 v[2:3], v[2:3], v[18:19]
	s_nop 0
	v_pk_add_f32 v[6:7], v[2:3], v[26:27]
	v_pk_add_f32 v[2:3], v[4:5], 0 op_sel_hi:[1,0]
	v_pk_add_f32 v[4:5], v[12:13], 0 op_sel_hi:[1,0]
	v_pk_add_f32 v[2:3], v[2:3], v[8:9]
	v_pk_add_f32 v[4:5], v[4:5], v[16:17]
	v_pk_add_f32 v[2:3], v[2:3], v[20:21]
	v_pk_add_f32 v[4:5], v[4:5], v[24:25]
	v_pk_add_f32 v[8:9], v[2:3], v[28:29]
	v_pk_add_f32 v[2:3], v[10:11], 0 op_sel_hi:[1,0]
	v_pk_add_f32 v[4:5], v[4:5], v[32:33]
	v_pk_add_f32 v[2:3], v[2:3], v[14:15]
	v_pk_add_f32 v[2:3], v[2:3], v[22:23]
	v_pk_add_f32 v[2:3], v[2:3], v[30:31]
	s_cmp_eq_u32 s98, 0
	s_cbranch_scc1 .Lskdb_owner
	s_mul_i32 s100, s28, 0xc000
	s_lshl_b32 s101, s98, 14
	s_add_i32 s100, s100, s101
	s_add_i32 s100, s100, 0x613c000
	v_lshl_add_u32 v12, v134, 4, s100
	v_add_u32_e32 v13, 0x2000, v12
	global_store_dwordx4 v12, v[6:9], s[82:83] sc1 nt
	global_store_dwordx4 v13, v[2:5], s[82:83] sc1 nt
	s_waitcnt vmcnt(0)
	s_barrier
	v_cmp_eq_u32_e32 vcc, 0, v134
	s_and_saveexec_b64 vcc, vcc
	s_cbranch_execz .Lskdb_harr
	s_lshl_b32 s100, s28, 8
	s_add_i32 s100, s100, 0xc4000
	v_mov_b32_e32 v12, s100
	v_mov_b32_e32 v13, 1
	global_atomic_add v12, v13, s[82:83]
